# all global stores made agent-scope write-through (sc1) to shrink every phase-end L2 writeback (experiment on top of the input-GEMM write-through)
# baseline (speedup 1.0000x reference)
.LBB0_96:
	s_or_b64 exec, exec, s[22:23]
	v_add_u32_e32 v170, s27, v164
	v_add_u32_e32 v164, 0x80, v170
	v_ashrrev_i32_e32 v165, 31, v164
	v_lshlrev_b64 v[164:165], 11, v[164:165]
	s_waitcnt lgkmcnt(0)
	s_barrier
	v_lshl_add_u64 v[164:165], v[162:163], 0, v[164:165]
	global_load_dwordx4 v[206:209], v[164:165], off
	global_load_dwordx4 v[202:205], v[164:165], off offset:256
	v_add_u32_e32 v164, 0x90, v170
	v_ashrrev_i32_e32 v165, 31, v164
	v_lshlrev_b64 v[164:165], 11, v[164:165]
	v_lshl_add_u64 v[164:165], v[162:163], 0, v[164:165]
	global_load_dwordx4 v[198:201], v[164:165], off
	global_load_dwordx4 v[194:197], v[164:165], off offset:256
	v_add_u32_e32 v164, 0xa0, v170
	v_ashrrev_i32_e32 v165, 31, v164
	v_lshlrev_b64 v[164:165], 11, v[164:165]
	v_lshl_add_u64 v[164:165], v[162:163], 0, v[164:165]
	global_load_dwordx4 v[186:189], v[164:165], off
	global_load_dwordx4 v[178:181], v[164:165], off offset:256
	v_add_u32_e32 v164, 0xb0, v170
	v_ashrrev_i32_e32 v165, 31, v164
	v_lshlrev_b64 v[164:165], 11, v[164:165]
	v_lshl_add_u64 v[162:163], v[162:163], 0, v[164:165]
	s_waitcnt lgkmcnt(0)
	v_cmp_eq_u32_e32 vcc, 0, v64
	v_lshl_add_u32 v64, v230, 2, 0
	global_load_dwordx4 v[170:173], v[162:163], off
	s_nop 0
	global_load_dwordx4 v[162:165], v[162:163], off offset:256
	ds_read_b32 v210, v64 offset:8192
	s_waitcnt vmcnt(0)
	v_lshlrev_b32_e32 v212, 16, v190
	v_and_b32_e32 v213, 0xffff0000, v190
	v_lshlrev_b32_e32 v190, 16, v191
	v_and_b32_e32 v191, 0xffff0000, v191
	s_waitcnt lgkmcnt(0)
	v_pk_mul_f32 v[128:129], v[128:129], v[210:211] op_sel_hi:[1,0]
	v_readlane_b32 s0, v250, 3
	v_pk_fma_f32 v[128:129], v[144:145], v[128:129], v[190:191]
	v_lshlrev_b32_e32 v190, 16, v192
	v_and_b32_e32 v191, 0xffff0000, v192
	v_pk_mul_f32 v[122:123], v[122:123], v[210:211] op_sel_hi:[1,0]
	s_sub_i32 s0, s0, 19
	v_pk_fma_f32 v[122:123], v[138:139], v[122:123], v[190:191]
	v_lshlrev_b32_e32 v190, 16, v182
	v_and_b32_e32 v191, 0xffff0000, v182
	v_lshlrev_b32_e32 v182, 16, v183
	v_and_b32_e32 v183, 0xffff0000, v183
	v_pk_mul_f32 v[120:121], v[120:121], v[210:211] op_sel_hi:[1,0]
	s_cmp_lt_u32 s0, 6
	v_readlane_b32 s0, v252, 0
	v_readlane_b32 s4, v250, 15
	v_add_u32_e32 v230, s24, v230
	v_pk_mul_f32 v[126:127], v[126:127], v[210:211] op_sel_hi:[1,0]
	v_lshlrev_b32_e32 v192, 16, v193
	v_and_b32_e32 v193, 0xffff0000, v193
	v_pk_mul_f32 v[124:125], v[124:125], v[210:211] op_sel_hi:[1,0]
	v_pk_mul_f32 v[118:119], v[118:119], v[210:211] op_sel_hi:[1,0]
	v_pk_fma_f32 v[120:121], v[136:137], v[120:121], v[182:183]
	v_lshlrev_b32_e32 v182, 16, v184
	v_and_b32_e32 v183, 0xffff0000, v184
	v_lshlrev_b32_e32 v184, 16, v185
	v_and_b32_e32 v185, 0xffff0000, v185
	v_pk_mul_f32 v[116:117], v[116:117], v[210:211] op_sel_hi:[1,0]
	v_pk_mul_f32 v[114:115], v[114:115], v[210:211] op_sel_hi:[1,0]
	v_readlane_b32 s1, v252, 1
	v_readlane_b32 s16, v250, 27
	v_readlane_b32 s17, v250, 28
	v_ashrrev_i32_e32 v231, 31, v230
	v_pk_fma_f32 v[126:127], v[142:143], v[126:127], v[212:213]
	v_pk_fma_f32 v[124:125], v[140:141], v[124:125], v[192:193]
	v_pk_fma_f32 v[118:119], v[134:135], v[118:119], v[190:191]
	v_pk_fma_f32 v[114:115], v[130:131], v[114:115], v[182:183]
	v_pk_fma_f32 v[116:117], v[132:133], v[116:117], v[184:185]
	s_cselect_b32 s1, s1, s17
	s_cselect_b32 s0, s0, s16
	v_cndmask_b32_e32 v129, v238, v129, vcc
	v_cndmask_b32_e32 v127, v238, v127, vcc
	v_cndmask_b32_e32 v125, v238, v125, vcc
	v_cndmask_b32_e32 v123, v238, v123, vcc
	v_cndmask_b32_e32 v121, v238, v121, vcc
	v_cndmask_b32_e32 v119, v238, v119, vcc
	v_cndmask_b32_e32 v117, v238, v117, vcc
	v_cndmask_b32_e32 v115, v238, v115, vcc
	v_lshlrev_b64 v[182:183], 11, v[230:231]
	v_cndmask_b32_e32 v128, v238, v128, vcc
	v_cndmask_b32_e32 v126, v238, v126, vcc
	v_cvt_pk_bf16_f32 v127, v126, v127
	v_cvt_pk_bf16_f32 v129, v128, v129
	v_cndmask_b32_e32 v124, v238, v124, vcc
	v_cndmask_b32_e32 v122, v238, v122, vcc
	v_cvt_pk_bf16_f32 v123, v122, v123
	v_cvt_pk_bf16_f32 v125, v124, v125
	v_cndmask_b32_e32 v120, v238, v120, vcc
	v_cndmask_b32_e32 v118, v238, v118, vcc
	v_cvt_pk_bf16_f32 v119, v118, v119
	v_cvt_pk_bf16_f32 v121, v120, v121
	v_cndmask_b32_e32 v116, v238, v116, vcc
	v_cndmask_b32_e32 v114, v238, v114, vcc
	v_cvt_pk_bf16_f32 v115, v114, v115
	v_cvt_pk_bf16_f32 v117, v116, v117
	v_lshl_add_u64 v[184:185], s[0:1], 0, v[182:183]
	v_lshlrev_b64 v[182:183], 1, v[228:229]
	v_lshlrev_b32_e32 v126, 16, v127
	v_and_b32_e32 v127, 0xffff0000, v127
	v_lshlrev_b32_e32 v128, 16, v129
	v_and_b32_e32 v129, 0xffff0000, v129
	v_lshlrev_b32_e32 v122, 16, v123
	v_and_b32_e32 v123, 0xffff0000, v123
	v_lshlrev_b32_e32 v124, 16, v125
	v_and_b32_e32 v125, 0xffff0000, v125
	v_lshlrev_b32_e32 v118, 16, v119
	v_and_b32_e32 v119, 0xffff0000, v119
	v_lshlrev_b32_e32 v120, 16, v121
	v_and_b32_e32 v121, 0xffff0000, v121
	v_lshlrev_b32_e32 v114, 16, v115
	v_and_b32_e32 v115, 0xffff0000, v115
	v_lshlrev_b32_e32 v116, 16, v117
	v_and_b32_e32 v117, 0xffff0000, v117
	v_cvt_pk_bf16_f32 v190, v126, v127
	v_cvt_pk_bf16_f32 v191, v128, v129
	v_cvt_pk_bf16_f32 v192, v122, v123
	v_cvt_pk_bf16_f32 v193, v124, v125
	v_lshl_add_u64 v[184:185], v[184:185], 0, v[182:183]
	global_store_dwordx4 v[184:185], v[190:193], off sc1
	v_readlane_b32 s5, v250, 16
	v_readlane_b32 s6, v250, 17
	v_cvt_pk_bf16_f32 v190, v118, v119
	v_cvt_pk_bf16_f32 v191, v120, v121
	v_cvt_pk_bf16_f32 v192, v114, v115
	v_cvt_pk_bf16_f32 v193, v116, v117
	global_store_dwordx4 v[184:185], v[190:193], off offset:256 sc1
	ds_read_b32 v184, v64 offset:8256
	v_mul_f32_e32 v123, v123, v123
	v_lshlrev_b32_e32 v192, 16, v174
	v_and_b32_e32 v193, 0xffff0000, v174
	v_lshlrev_b32_e32 v174, 16, v175
	v_and_b32_e32 v175, 0xffff0000, v175
	s_waitcnt lgkmcnt(0)
	v_pk_mul_f32 v[112:113], v[112:113], v[184:185] op_sel_hi:[1,0]
	v_pk_mul_f32 v[106:107], v[106:107], v[184:185] op_sel_hi:[1,0]
	v_pk_fma_f32 v[112:113], v[144:145], v[112:113], v[174:175]
	v_lshlrev_b32_e32 v174, 16, v176
	v_and_b32_e32 v175, 0xffff0000, v176
	v_add_u32_e32 v190, 16, v230
	v_pk_mul_f32 v[110:111], v[110:111], v[184:185] op_sel_hi:[1,0]
	v_pk_fma_f32 v[106:107], v[138:139], v[106:107], v[174:175]
	v_lshlrev_b32_e32 v174, 16, v166
	v_and_b32_e32 v175, 0xffff0000, v166
	v_lshlrev_b32_e32 v166, 16, v167
	v_and_b32_e32 v167, 0xffff0000, v167
	v_pk_mul_f32 v[104:105], v[104:105], v[184:185] op_sel_hi:[1,0]
	v_ashrrev_i32_e32 v191, 31, v190
	v_pk_fma_f32 v[110:111], v[142:143], v[110:111], v[192:193]
	v_lshlrev_b32_e32 v176, 16, v177
	v_and_b32_e32 v177, 0xffff0000, v177
	v_pk_mul_f32 v[108:109], v[108:109], v[184:185] op_sel_hi:[1,0]
	v_pk_mul_f32 v[102:103], v[102:103], v[184:185] op_sel_hi:[1,0]
	v_pk_fma_f32 v[104:105], v[136:137], v[104:105], v[166:167]
	v_lshlrev_b32_e32 v166, 16, v168
	v_and_b32_e32 v167, 0xffff0000, v168
	v_lshlrev_b32_e32 v168, 16, v169
	v_and_b32_e32 v169, 0xffff0000, v169
	v_pk_mul_f32 v[100:101], v[100:101], v[184:185] op_sel_hi:[1,0]
	v_pk_mul_f32 v[98:99], v[98:99], v[184:185] op_sel_hi:[1,0]
	v_cndmask_b32_e32 v111, v238, v111, vcc
	v_pk_fma_f32 v[108:109], v[140:141], v[108:109], v[176:177]
	v_pk_fma_f32 v[102:103], v[134:135], v[102:103], v[174:175]
	v_pk_fma_f32 v[98:99], v[130:131], v[98:99], v[166:167]
	v_pk_fma_f32 v[100:101], v[132:133], v[100:101], v[168:169]
	v_lshlrev_b64 v[174:175], 11, v[190:191]
	v_cndmask_b32_e32 v113, v238, v113, vcc
	v_cndmask_b32_e32 v110, v238, v110, vcc
	v_cvt_pk_bf16_f32 v111, v110, v111
	v_cndmask_b32_e32 v109, v238, v109, vcc
	v_cndmask_b32_e32 v107, v238, v107, vcc
	v_cndmask_b32_e32 v105, v238, v105, vcc
	v_cndmask_b32_e32 v103, v238, v103, vcc
	v_cndmask_b32_e32 v101, v238, v101, vcc
	v_cndmask_b32_e32 v99, v238, v99, vcc
	v_lshl_add_u64 v[174:175], s[0:1], 0, v[174:175]
	v_cndmask_b32_e32 v112, v238, v112, vcc
	v_cvt_pk_bf16_f32 v113, v112, v113
	v_lshlrev_b32_e32 v110, 16, v111
	v_and_b32_e32 v111, 0xffff0000, v111
	v_cndmask_b32_e32 v108, v238, v108, vcc
	v_cndmask_b32_e32 v106, v238, v106, vcc
	v_cvt_pk_bf16_f32 v107, v106, v107
	v_cvt_pk_bf16_f32 v109, v108, v109
	v_cndmask_b32_e32 v104, v238, v104, vcc
	v_cndmask_b32_e32 v102, v238, v102, vcc
	v_cvt_pk_bf16_f32 v103, v102, v103
	v_cvt_pk_bf16_f32 v105, v104, v105
	v_cndmask_b32_e32 v100, v238, v100, vcc
	v_cndmask_b32_e32 v98, v238, v98, vcc
	v_cvt_pk_bf16_f32 v99, v98, v99
	v_cvt_pk_bf16_f32 v101, v100, v101
	v_cvt_pk_bf16_f32 v166, v110, v111
	v_lshl_add_u64 v[174:175], v[174:175], 0, v[182:183]
	v_lshlrev_b32_e32 v112, 16, v113
	v_and_b32_e32 v113, 0xffff0000, v113
	v_lshlrev_b32_e32 v106, 16, v107
	v_and_b32_e32 v107, 0xffff0000, v107
	v_lshlrev_b32_e32 v108, 16, v109
	v_and_b32_e32 v109, 0xffff0000, v109
	v_lshlrev_b32_e32 v102, 16, v103
	v_and_b32_e32 v103, 0xffff0000, v103
	v_lshlrev_b32_e32 v104, 16, v105
	v_and_b32_e32 v105, 0xffff0000, v105
	v_lshlrev_b32_e32 v98, 16, v99
	v_and_b32_e32 v99, 0xffff0000, v99
	v_lshlrev_b32_e32 v100, 16, v101
	v_and_b32_e32 v101, 0xffff0000, v101
	v_cvt_pk_bf16_f32 v167, v112, v113
	v_cvt_pk_bf16_f32 v168, v106, v107
	v_cvt_pk_bf16_f32 v169, v108, v109
	global_store_dwordx4 v[174:175], v[166:169], off sc1
	v_fmac_f32_e32 v123, v122, v122
	v_mul_f32_e32 v122, v125, v125
	v_cvt_pk_bf16_f32 v166, v102, v103
	v_cvt_pk_bf16_f32 v167, v104, v105
	v_cvt_pk_bf16_f32 v168, v98, v99
	v_cvt_pk_bf16_f32 v169, v100, v101
	global_store_dwordx4 v[174:175], v[166:169], off offset:256 sc1
	ds_read_b32 v166, v64 offset:8320
	v_lshlrev_b32_e32 v174, 16, v158
	v_and_b32_e32 v175, 0xffff0000, v158
	v_lshlrev_b32_e32 v158, 16, v159
	v_and_b32_e32 v159, 0xffff0000, v159
	s_waitcnt lgkmcnt(0)
	v_pk_mul_f32 v[96:97], v[96:97], v[166:167] op_sel_hi:[1,0]
	v_pk_mul_f32 v[90:91], v[90:91], v[166:167] op_sel_hi:[1,0]
	v_pk_fma_f32 v[96:97], v[144:145], v[96:97], v[158:159]
	v_lshlrev_b32_e32 v158, 16, v160
	v_and_b32_e32 v159, 0xffff0000, v160
	v_add_u32_e32 v168, 32, v230
	v_pk_mul_f32 v[94:95], v[94:95], v[166:167] op_sel_hi:[1,0]
	v_pk_fma_f32 v[90:91], v[138:139], v[90:91], v[158:159]
	v_lshlrev_b32_e32 v158, 16, v154
	v_and_b32_e32 v159, 0xffff0000, v154
	v_lshlrev_b32_e32 v154, 16, v155
	v_and_b32_e32 v155, 0xffff0000, v155
	v_pk_mul_f32 v[88:89], v[88:89], v[166:167] op_sel_hi:[1,0]
	v_ashrrev_i32_e32 v169, 31, v168
	v_pk_fma_f32 v[94:95], v[142:143], v[94:95], v[174:175]
	v_lshlrev_b32_e32 v160, 16, v161
	v_and_b32_e32 v161, 0xffff0000, v161
	v_pk_mul_f32 v[92:93], v[92:93], v[166:167] op_sel_hi:[1,0]
	v_pk_mul_f32 v[86:87], v[86:87], v[166:167] op_sel_hi:[1,0]
	v_pk_fma_f32 v[88:89], v[136:137], v[88:89], v[154:155]
	v_lshlrev_b32_e32 v154, 16, v156
	v_and_b32_e32 v155, 0xffff0000, v156
	v_lshlrev_b32_e32 v156, 16, v157
	v_and_b32_e32 v157, 0xffff0000, v157
	v_pk_mul_f32 v[84:85], v[84:85], v[166:167] op_sel_hi:[1,0]
	v_pk_mul_f32 v[82:83], v[82:83], v[166:167] op_sel_hi:[1,0]
	v_cndmask_b32_e32 v95, v238, v95, vcc
	v_pk_fma_f32 v[92:93], v[140:141], v[92:93], v[160:161]
	v_pk_fma_f32 v[86:87], v[134:135], v[86:87], v[158:159]
	v_pk_fma_f32 v[82:83], v[130:131], v[82:83], v[154:155]
	v_pk_fma_f32 v[84:85], v[132:133], v[84:85], v[156:157]
	v_lshlrev_b64 v[158:159], 11, v[168:169]
	v_cndmask_b32_e32 v97, v238, v97, vcc
	v_cndmask_b32_e32 v94, v238, v94, vcc
	v_cvt_pk_bf16_f32 v95, v94, v95
	v_cndmask_b32_e32 v93, v238, v93, vcc
	v_cndmask_b32_e32 v91, v238, v91, vcc
	v_cndmask_b32_e32 v89, v238, v89, vcc
	v_cndmask_b32_e32 v87, v238, v87, vcc
	v_cndmask_b32_e32 v85, v238, v85, vcc
	v_cndmask_b32_e32 v83, v238, v83, vcc
	v_lshl_add_u64 v[158:159], s[0:1], 0, v[158:159]
	v_cndmask_b32_e32 v96, v238, v96, vcc
	v_cvt_pk_bf16_f32 v97, v96, v97
	v_lshlrev_b32_e32 v94, 16, v95
	v_and_b32_e32 v95, 0xffff0000, v95
	v_cndmask_b32_e32 v92, v238, v92, vcc
	v_cndmask_b32_e32 v90, v238, v90, vcc
	v_cvt_pk_bf16_f32 v91, v90, v91
	v_cvt_pk_bf16_f32 v93, v92, v93
	v_cndmask_b32_e32 v88, v238, v88, vcc
	v_cndmask_b32_e32 v86, v238, v86, vcc
	v_cvt_pk_bf16_f32 v87, v86, v87
	v_cvt_pk_bf16_f32 v89, v88, v89
	v_cndmask_b32_e32 v84, v238, v84, vcc
	v_cndmask_b32_e32 v82, v238, v82, vcc
	v_cvt_pk_bf16_f32 v83, v82, v83
	v_cvt_pk_bf16_f32 v85, v84, v85
	v_cvt_pk_bf16_f32 v154, v94, v95
	v_lshl_add_u64 v[158:159], v[158:159], 0, v[182:183]
	v_lshlrev_b32_e32 v96, 16, v97
	v_and_b32_e32 v97, 0xffff0000, v97
	v_lshlrev_b32_e32 v90, 16, v91
	v_and_b32_e32 v91, 0xffff0000, v91
	v_lshlrev_b32_e32 v92, 16, v93
	v_and_b32_e32 v93, 0xffff0000, v93
	v_lshlrev_b32_e32 v86, 16, v87
	v_and_b32_e32 v87, 0xffff0000, v87
	v_lshlrev_b32_e32 v88, 16, v89
	v_and_b32_e32 v89, 0xffff0000, v89
	v_lshlrev_b32_e32 v82, 16, v83
	v_and_b32_e32 v83, 0xffff0000, v83
	v_lshlrev_b32_e32 v84, 16, v85
	v_and_b32_e32 v85, 0xffff0000, v85
	v_cvt_pk_bf16_f32 v155, v96, v97
	v_cvt_pk_bf16_f32 v156, v90, v91
	v_cvt_pk_bf16_f32 v157, v92, v93
	global_store_dwordx4 v[158:159], v[154:157], off sc1
	v_mul_f32_e32 v119, v119, v119
	v_fmac_f32_e32 v122, v124, v124
	v_cvt_pk_bf16_f32 v154, v86, v87
	v_cvt_pk_bf16_f32 v155, v88, v89
	v_cvt_pk_bf16_f32 v156, v82, v83
	v_cvt_pk_bf16_f32 v157, v84, v85
	global_store_dwordx4 v[158:159], v[154:157], off offset:256 sc1
	ds_read_b32 v154, v64 offset:8384
	v_lshlrev_b32_e32 v158, 16, v150
	v_and_b32_e32 v159, 0xffff0000, v150
	v_lshlrev_b32_e32 v150, 16, v151
	v_and_b32_e32 v151, 0xffff0000, v151
	s_waitcnt lgkmcnt(0)
	v_pk_mul_f32 v[80:81], v[80:81], v[154:155] op_sel_hi:[1,0]
	v_pk_mul_f32 v[74:75], v[74:75], v[154:155] op_sel_hi:[1,0]
	v_pk_fma_f32 v[80:81], v[144:145], v[80:81], v[150:151]
	v_lshlrev_b32_e32 v150, 16, v152
	v_and_b32_e32 v151, 0xffff0000, v152
	v_add_u32_e32 v156, 48, v230
	v_pk_mul_f32 v[78:79], v[78:79], v[154:155] op_sel_hi:[1,0]
	v_pk_fma_f32 v[74:75], v[138:139], v[74:75], v[150:151]
	v_lshlrev_b32_e32 v150, 16, v146
	v_and_b32_e32 v151, 0xffff0000, v146
	v_lshlrev_b32_e32 v146, 16, v147
	v_and_b32_e32 v147, 0xffff0000, v147
	v_pk_mul_f32 v[72:73], v[72:73], v[154:155] op_sel_hi:[1,0]
	v_ashrrev_i32_e32 v157, 31, v156
	v_pk_fma_f32 v[78:79], v[142:143], v[78:79], v[158:159]
	v_lshlrev_b32_e32 v152, 16, v153
	v_and_b32_e32 v153, 0xffff0000, v153
	v_pk_mul_f32 v[76:77], v[76:77], v[154:155] op_sel_hi:[1,0]
	v_pk_mul_f32 v[70:71], v[70:71], v[154:155] op_sel_hi:[1,0]
	v_pk_fma_f32 v[72:73], v[136:137], v[72:73], v[146:147]
	v_lshlrev_b32_e32 v146, 16, v148
	v_and_b32_e32 v147, 0xffff0000, v148
	v_lshlrev_b32_e32 v148, 16, v149
	v_and_b32_e32 v149, 0xffff0000, v149
	v_pk_mul_f32 v[68:69], v[68:69], v[154:155] op_sel_hi:[1,0]
	v_pk_mul_f32 v[66:67], v[66:67], v[154:155] op_sel_hi:[1,0]
	v_cndmask_b32_e32 v79, v238, v79, vcc
	v_pk_fma_f32 v[76:77], v[140:141], v[76:77], v[152:153]
	v_pk_fma_f32 v[70:71], v[134:135], v[70:71], v[150:151]
	v_pk_fma_f32 v[66:67], v[130:131], v[66:67], v[146:147]
	v_pk_fma_f32 v[68:69], v[132:133], v[68:69], v[148:149]
	v_lshlrev_b64 v[150:151], 11, v[156:157]
	v_cndmask_b32_e32 v81, v238, v81, vcc
	v_cndmask_b32_e32 v78, v238, v78, vcc
	v_cvt_pk_bf16_f32 v79, v78, v79
	v_cndmask_b32_e32 v77, v238, v77, vcc
	v_cndmask_b32_e32 v75, v238, v75, vcc
	v_cndmask_b32_e32 v73, v238, v73, vcc
	v_cndmask_b32_e32 v71, v238, v71, vcc
	v_cndmask_b32_e32 v69, v238, v69, vcc
	v_cndmask_b32_e32 v67, v238, v67, vcc
	v_lshl_add_u64 v[150:151], s[0:1], 0, v[150:151]
	v_cndmask_b32_e32 v80, v238, v80, vcc
	v_cvt_pk_bf16_f32 v81, v80, v81
	v_lshlrev_b32_e32 v78, 16, v79
	v_and_b32_e32 v79, 0xffff0000, v79
	v_cndmask_b32_e32 v76, v238, v76, vcc
	v_cndmask_b32_e32 v74, v238, v74, vcc
	v_cvt_pk_bf16_f32 v75, v74, v75
	v_cvt_pk_bf16_f32 v77, v76, v77
	v_cndmask_b32_e32 v72, v238, v72, vcc
	v_cndmask_b32_e32 v70, v238, v70, vcc
	v_cvt_pk_bf16_f32 v71, v70, v71
	v_cvt_pk_bf16_f32 v73, v72, v73
	v_cndmask_b32_e32 v68, v238, v68, vcc
	v_cndmask_b32_e32 v66, v238, v66, vcc
	v_cvt_pk_bf16_f32 v67, v66, v67
	v_cvt_pk_bf16_f32 v69, v68, v69
	v_cvt_pk_bf16_f32 v146, v78, v79
	v_lshl_add_u64 v[150:151], v[150:151], 0, v[182:183]
	v_lshlrev_b32_e32 v80, 16, v81
	v_and_b32_e32 v81, 0xffff0000, v81
	v_lshlrev_b32_e32 v74, 16, v75
	v_and_b32_e32 v75, 0xffff0000, v75
	v_lshlrev_b32_e32 v76, 16, v77
	v_and_b32_e32 v77, 0xffff0000, v77
	v_lshlrev_b32_e32 v70, 16, v71
	v_and_b32_e32 v71, 0xffff0000, v71
	v_lshlrev_b32_e32 v72, 16, v73
	v_and_b32_e32 v73, 0xffff0000, v73
	v_lshlrev_b32_e32 v66, 16, v67
	v_and_b32_e32 v67, 0xffff0000, v67
	v_lshlrev_b32_e32 v68, 16, v69
	v_and_b32_e32 v69, 0xffff0000, v69
	v_cvt_pk_bf16_f32 v147, v80, v81
	v_cvt_pk_bf16_f32 v148, v74, v75
	v_cvt_pk_bf16_f32 v149, v76, v77
	global_store_dwordx4 v[150:151], v[146:149], off sc1
	v_lshlrev_b32_e32 v152, 16, v207
	v_and_b32_e32 v153, 0xffff0000, v207
	v_cvt_pk_bf16_f32 v146, v70, v71
	v_cvt_pk_bf16_f32 v147, v72, v73
	v_cvt_pk_bf16_f32 v148, v66, v67
	v_cvt_pk_bf16_f32 v149, v68, v69
	global_store_dwordx4 v[150:151], v[146:149], off offset:256 sc1
	ds_read_b32 v146, v64 offset:8704
	v_add_u32_e32 v150, 0x80, v230
	v_lshlrev_b32_e32 v148, 16, v206
	v_and_b32_e32 v149, 0xffff0000, v206
	v_ashrrev_i32_e32 v151, 31, v150
	s_waitcnt lgkmcnt(0)
	v_pk_mul_f32 v[62:63], v[62:63], v[146:147] op_sel_hi:[1,0]
	v_pk_mul_f32 v[60:61], v[60:61], v[146:147] op_sel_hi:[1,0]
	v_pk_fma_f32 v[62:63], v[144:145], v[62:63], v[152:153]
	v_pk_fma_f32 v[60:61], v[142:143], v[60:61], v[148:149]
	v_lshlrev_b32_e32 v148, 16, v208
	v_and_b32_e32 v149, 0xffff0000, v208
	v_lshlrev_b32_e32 v152, 16, v209
	v_and_b32_e32 v153, 0xffff0000, v209
	v_pk_mul_f32 v[58:59], v[58:59], v[146:147] op_sel_hi:[1,0]
	v_pk_mul_f32 v[56:57], v[56:57], v[146:147] op_sel_hi:[1,0]
	v_pk_fma_f32 v[58:59], v[140:141], v[58:59], v[152:153]
	v_pk_fma_f32 v[56:57], v[138:139], v[56:57], v[148:149]
	v_lshlrev_b32_e32 v148, 16, v202
	v_and_b32_e32 v149, 0xffff0000, v202
	v_lshlrev_b32_e32 v152, 16, v203
	v_and_b32_e32 v153, 0xffff0000, v203
	v_pk_mul_f32 v[54:55], v[54:55], v[146:147] op_sel_hi:[1,0]
	v_pk_mul_f32 v[52:53], v[52:53], v[146:147] op_sel_hi:[1,0]
	v_pk_fma_f32 v[54:55], v[136:137], v[54:55], v[152:153]
	v_pk_fma_f32 v[52:53], v[134:135], v[52:53], v[148:149]
	v_lshlrev_b32_e32 v148, 16, v204
	v_and_b32_e32 v149, 0xffff0000, v204
	v_lshlrev_b32_e32 v152, 16, v205
	v_and_b32_e32 v153, 0xffff0000, v205
	v_pk_mul_f32 v[50:51], v[50:51], v[146:147] op_sel_hi:[1,0]
	v_pk_mul_f32 v[48:49], v[48:49], v[146:147] op_sel_hi:[1,0]
	v_cndmask_b32_e32 v61, v238, v61, vcc
	v_pk_fma_f32 v[48:49], v[130:131], v[48:49], v[148:149]
	v_pk_fma_f32 v[50:51], v[132:133], v[50:51], v[152:153]
	v_lshlrev_b64 v[150:151], 11, v[150:151]
	v_cndmask_b32_e32 v63, v238, v63, vcc
	v_cndmask_b32_e32 v60, v238, v60, vcc
	v_cvt_pk_bf16_f32 v61, v60, v61
	v_cndmask_b32_e32 v59, v238, v59, vcc
	v_cndmask_b32_e32 v57, v238, v57, vcc
	v_cndmask_b32_e32 v55, v238, v55, vcc
	v_cndmask_b32_e32 v53, v238, v53, vcc
	v_cndmask_b32_e32 v51, v238, v51, vcc
	v_cndmask_b32_e32 v49, v238, v49, vcc
	v_lshl_add_u64 v[150:151], s[0:1], 0, v[150:151]
	v_cndmask_b32_e32 v62, v238, v62, vcc
	v_cvt_pk_bf16_f32 v63, v62, v63
	v_lshlrev_b32_e32 v60, 16, v61
	v_and_b32_e32 v61, 0xffff0000, v61
	v_cndmask_b32_e32 v58, v238, v58, vcc
	v_cndmask_b32_e32 v56, v238, v56, vcc
	v_cvt_pk_bf16_f32 v57, v56, v57
	v_cvt_pk_bf16_f32 v59, v58, v59
	v_cndmask_b32_e32 v54, v238, v54, vcc
	v_cndmask_b32_e32 v52, v238, v52, vcc
	v_cvt_pk_bf16_f32 v53, v52, v53
	v_cvt_pk_bf16_f32 v55, v54, v55
	v_cndmask_b32_e32 v50, v238, v50, vcc
	v_cndmask_b32_e32 v48, v238, v48, vcc
	v_cvt_pk_bf16_f32 v49, v48, v49
	v_cvt_pk_bf16_f32 v51, v50, v51
	v_cvt_pk_bf16_f32 v146, v60, v61
	v_lshl_add_u64 v[150:151], v[150:151], 0, v[182:183]
	v_lshlrev_b32_e32 v62, 16, v63
	v_and_b32_e32 v63, 0xffff0000, v63
	v_lshlrev_b32_e32 v56, 16, v57
	v_and_b32_e32 v57, 0xffff0000, v57
	v_lshlrev_b32_e32 v58, 16, v59
	v_and_b32_e32 v59, 0xffff0000, v59
	v_lshlrev_b32_e32 v52, 16, v53
	v_and_b32_e32 v53, 0xffff0000, v53
	v_lshlrev_b32_e32 v54, 16, v55
	v_and_b32_e32 v55, 0xffff0000, v55
	v_lshlrev_b32_e32 v48, 16, v49
	v_and_b32_e32 v49, 0xffff0000, v49
	v_lshlrev_b32_e32 v50, 16, v51
	v_and_b32_e32 v51, 0xffff0000, v51
	v_cvt_pk_bf16_f32 v147, v62, v63
	v_cvt_pk_bf16_f32 v148, v56, v57
	v_cvt_pk_bf16_f32 v149, v58, v59
	global_store_dwordx4 v[150:151], v[146:149], off sc1
	v_lshlrev_b32_e32 v152, 16, v199
	v_and_b32_e32 v153, 0xffff0000, v199
	v_cvt_pk_bf16_f32 v146, v52, v53
	v_cvt_pk_bf16_f32 v147, v54, v55
	v_cvt_pk_bf16_f32 v148, v48, v49
	v_cvt_pk_bf16_f32 v149, v50, v51
	global_store_dwordx4 v[150:151], v[146:149], off offset:256 sc1
	ds_read_b32 v146, v64 offset:8768
	v_add_u32_e32 v150, 0x90, v230
	v_lshlrev_b32_e32 v148, 16, v198
	v_and_b32_e32 v149, 0xffff0000, v198
	v_ashrrev_i32_e32 v151, 31, v150
	s_waitcnt lgkmcnt(0)
	v_pk_mul_f32 v[46:47], v[46:47], v[146:147] op_sel_hi:[1,0]
	v_pk_mul_f32 v[44:45], v[44:45], v[146:147] op_sel_hi:[1,0]
	v_pk_fma_f32 v[46:47], v[144:145], v[46:47], v[152:153]
	v_pk_fma_f32 v[44:45], v[142:143], v[44:45], v[148:149]
	v_lshlrev_b32_e32 v148, 16, v200
	v_and_b32_e32 v149, 0xffff0000, v200
	v_lshlrev_b32_e32 v152, 16, v201
	v_and_b32_e32 v153, 0xffff0000, v201
	v_pk_mul_f32 v[42:43], v[42:43], v[146:147] op_sel_hi:[1,0]
	v_pk_mul_f32 v[40:41], v[40:41], v[146:147] op_sel_hi:[1,0]
	v_pk_fma_f32 v[42:43], v[140:141], v[42:43], v[152:153]
	v_pk_fma_f32 v[40:41], v[138:139], v[40:41], v[148:149]
	v_lshlrev_b32_e32 v148, 16, v194
	v_and_b32_e32 v149, 0xffff0000, v194
	v_lshlrev_b32_e32 v152, 16, v195
	v_and_b32_e32 v153, 0xffff0000, v195
	v_pk_mul_f32 v[38:39], v[38:39], v[146:147] op_sel_hi:[1,0]
	v_pk_mul_f32 v[36:37], v[36:37], v[146:147] op_sel_hi:[1,0]
	v_pk_fma_f32 v[38:39], v[136:137], v[38:39], v[152:153]
	v_pk_fma_f32 v[36:37], v[134:135], v[36:37], v[148:149]
	v_lshlrev_b32_e32 v148, 16, v196
	v_and_b32_e32 v149, 0xffff0000, v196
	v_lshlrev_b32_e32 v152, 16, v197
	v_and_b32_e32 v153, 0xffff0000, v197
	v_pk_mul_f32 v[34:35], v[34:35], v[146:147] op_sel_hi:[1,0]
	v_pk_mul_f32 v[32:33], v[32:33], v[146:147] op_sel_hi:[1,0]
	v_cndmask_b32_e32 v45, v238, v45, vcc
	v_pk_fma_f32 v[32:33], v[130:131], v[32:33], v[148:149]
	v_pk_fma_f32 v[34:35], v[132:133], v[34:35], v[152:153]
	v_lshlrev_b64 v[150:151], 11, v[150:151]
	v_cndmask_b32_e32 v47, v238, v47, vcc
	v_cndmask_b32_e32 v44, v238, v44, vcc
	v_cvt_pk_bf16_f32 v45, v44, v45
	v_cndmask_b32_e32 v43, v238, v43, vcc
	v_cndmask_b32_e32 v41, v238, v41, vcc
	v_cndmask_b32_e32 v39, v238, v39, vcc
	v_cndmask_b32_e32 v37, v238, v37, vcc
	v_cndmask_b32_e32 v35, v238, v35, vcc
	v_cndmask_b32_e32 v33, v238, v33, vcc
	v_lshl_add_u64 v[150:151], s[0:1], 0, v[150:151]
	v_cndmask_b32_e32 v46, v238, v46, vcc
	v_cvt_pk_bf16_f32 v47, v46, v47
	v_lshlrev_b32_e32 v44, 16, v45
	v_and_b32_e32 v45, 0xffff0000, v45
	v_cndmask_b32_e32 v42, v238, v42, vcc
	v_cndmask_b32_e32 v40, v238, v40, vcc
	v_cvt_pk_bf16_f32 v41, v40, v41
	v_cvt_pk_bf16_f32 v43, v42, v43
	v_cndmask_b32_e32 v38, v238, v38, vcc
	v_cndmask_b32_e32 v36, v238, v36, vcc
	v_cvt_pk_bf16_f32 v37, v36, v37
	v_cvt_pk_bf16_f32 v39, v38, v39
	v_cndmask_b32_e32 v34, v238, v34, vcc
	v_cndmask_b32_e32 v32, v238, v32, vcc
	v_cvt_pk_bf16_f32 v33, v32, v33
	v_cvt_pk_bf16_f32 v35, v34, v35
	v_cvt_pk_bf16_f32 v146, v44, v45
	v_lshl_add_u64 v[150:151], v[150:151], 0, v[182:183]
	v_lshlrev_b32_e32 v46, 16, v47
	v_and_b32_e32 v47, 0xffff0000, v47
	v_lshlrev_b32_e32 v40, 16, v41
	v_and_b32_e32 v41, 0xffff0000, v41
	v_lshlrev_b32_e32 v42, 16, v43
	v_and_b32_e32 v43, 0xffff0000, v43
	v_lshlrev_b32_e32 v36, 16, v37
	v_and_b32_e32 v37, 0xffff0000, v37
	v_lshlrev_b32_e32 v38, 16, v39
	v_and_b32_e32 v39, 0xffff0000, v39
	v_lshlrev_b32_e32 v32, 16, v33
	v_and_b32_e32 v33, 0xffff0000, v33
	v_lshlrev_b32_e32 v34, 16, v35
	v_and_b32_e32 v35, 0xffff0000, v35
	v_cvt_pk_bf16_f32 v147, v46, v47
	v_cvt_pk_bf16_f32 v148, v40, v41
	v_cvt_pk_bf16_f32 v149, v42, v43
	global_store_dwordx4 v[150:151], v[146:149], off sc1
	v_lshlrev_b32_e32 v152, 16, v187
	v_and_b32_e32 v153, 0xffff0000, v187
	v_cvt_pk_bf16_f32 v146, v36, v37
	v_cvt_pk_bf16_f32 v147, v38, v39
	v_cvt_pk_bf16_f32 v148, v32, v33
	v_cvt_pk_bf16_f32 v149, v34, v35
	global_store_dwordx4 v[150:151], v[146:149], off offset:256 sc1
	ds_read_b32 v146, v64 offset:8832
	v_add_u32_e32 v150, 0xa0, v230
	v_lshlrev_b32_e32 v148, 16, v186
	v_and_b32_e32 v149, 0xffff0000, v186
	v_ashrrev_i32_e32 v151, 31, v150
	s_waitcnt lgkmcnt(0)
	v_pk_mul_f32 v[30:31], v[30:31], v[146:147] op_sel_hi:[1,0]
	v_pk_mul_f32 v[28:29], v[28:29], v[146:147] op_sel_hi:[1,0]
	v_pk_fma_f32 v[30:31], v[144:145], v[30:31], v[152:153]
	v_pk_fma_f32 v[28:29], v[142:143], v[28:29], v[148:149]
	v_lshlrev_b32_e32 v148, 16, v188
	v_and_b32_e32 v149, 0xffff0000, v188
	v_lshlrev_b32_e32 v152, 16, v189
	v_and_b32_e32 v153, 0xffff0000, v189
	v_pk_mul_f32 v[26:27], v[26:27], v[146:147] op_sel_hi:[1,0]
	v_pk_mul_f32 v[24:25], v[24:25], v[146:147] op_sel_hi:[1,0]
	v_pk_fma_f32 v[26:27], v[140:141], v[26:27], v[152:153]
	v_pk_fma_f32 v[24:25], v[138:139], v[24:25], v[148:149]
	v_lshlrev_b32_e32 v148, 16, v178
	v_and_b32_e32 v149, 0xffff0000, v178
	v_lshlrev_b32_e32 v152, 16, v179
	v_and_b32_e32 v153, 0xffff0000, v179
	v_pk_mul_f32 v[22:23], v[22:23], v[146:147] op_sel_hi:[1,0]
	v_pk_mul_f32 v[20:21], v[20:21], v[146:147] op_sel_hi:[1,0]
	v_pk_fma_f32 v[22:23], v[136:137], v[22:23], v[152:153]
	v_pk_fma_f32 v[20:21], v[134:135], v[20:21], v[148:149]
	v_lshlrev_b32_e32 v148, 16, v180
	v_and_b32_e32 v149, 0xffff0000, v180
	v_lshlrev_b32_e32 v152, 16, v181
	v_and_b32_e32 v153, 0xffff0000, v181
	v_pk_mul_f32 v[18:19], v[18:19], v[146:147] op_sel_hi:[1,0]
	v_pk_mul_f32 v[16:17], v[16:17], v[146:147] op_sel_hi:[1,0]
	v_pk_fma_f32 v[18:19], v[132:133], v[18:19], v[152:153]
	v_pk_fma_f32 v[16:17], v[130:131], v[16:17], v[148:149]
	v_cndmask_b32_e32 v31, v238, v31, vcc
	v_cndmask_b32_e32 v29, v238, v29, vcc
	v_cndmask_b32_e32 v27, v238, v27, vcc
	v_cndmask_b32_e32 v25, v238, v25, vcc
	v_cndmask_b32_e32 v23, v238, v23, vcc
	v_cndmask_b32_e32 v21, v238, v21, vcc
	v_cndmask_b32_e32 v19, v238, v19, vcc
	v_cndmask_b32_e32 v17, v238, v17, vcc
	v_lshlrev_b64 v[150:151], 11, v[150:151]
	v_cndmask_b32_e32 v30, v238, v30, vcc
	v_cndmask_b32_e32 v28, v238, v28, vcc
	v_cvt_pk_bf16_f32 v29, v28, v29
	v_cvt_pk_bf16_f32 v31, v30, v31
	v_cndmask_b32_e32 v26, v238, v26, vcc
	v_cndmask_b32_e32 v24, v238, v24, vcc
	v_cvt_pk_bf16_f32 v25, v24, v25
	v_cvt_pk_bf16_f32 v27, v26, v27
	v_cndmask_b32_e32 v22, v238, v22, vcc
	v_cndmask_b32_e32 v20, v238, v20, vcc
	v_cvt_pk_bf16_f32 v21, v20, v21
	v_cvt_pk_bf16_f32 v23, v22, v23
	v_cndmask_b32_e32 v18, v238, v18, vcc
	v_cndmask_b32_e32 v16, v238, v16, vcc
	v_cvt_pk_bf16_f32 v17, v16, v17
	v_cvt_pk_bf16_f32 v19, v18, v19
	v_lshl_add_u64 v[150:151], s[0:1], 0, v[150:151]
	v_lshlrev_b32_e32 v28, 16, v29
	v_and_b32_e32 v29, 0xffff0000, v29
	v_lshlrev_b32_e32 v30, 16, v31
	v_and_b32_e32 v31, 0xffff0000, v31
	v_lshlrev_b32_e32 v24, 16, v25
	v_and_b32_e32 v25, 0xffff0000, v25
	v_lshlrev_b32_e32 v26, 16, v27
	v_and_b32_e32 v27, 0xffff0000, v27
	v_lshlrev_b32_e32 v20, 16, v21
	v_and_b32_e32 v21, 0xffff0000, v21
	v_lshlrev_b32_e32 v22, 16, v23
	v_and_b32_e32 v23, 0xffff0000, v23
	v_lshlrev_b32_e32 v16, 16, v17
	v_and_b32_e32 v17, 0xffff0000, v17
	v_lshlrev_b32_e32 v18, 16, v19
	v_and_b32_e32 v19, 0xffff0000, v19
	v_cvt_pk_bf16_f32 v146, v28, v29
	v_cvt_pk_bf16_f32 v147, v30, v31
	v_cvt_pk_bf16_f32 v148, v24, v25
	v_cvt_pk_bf16_f32 v149, v26, v27
	v_lshl_add_u64 v[150:151], v[150:151], 0, v[182:183]
	global_store_dwordx4 v[150:151], v[146:149], off sc1
	v_fmac_f32_e32 v119, v118, v118
	v_mul_f32_e32 v118, v121, v121
	v_cvt_pk_bf16_f32 v146, v20, v21
	v_cvt_pk_bf16_f32 v147, v22, v23
	v_cvt_pk_bf16_f32 v148, v16, v17
	v_cvt_pk_bf16_f32 v149, v18, v19
	global_store_dwordx4 v[150:151], v[146:149], off offset:256 sc1
	ds_read_b32 v64, v64 offset:8896
	v_mul_f32_e32 v115, v115, v115
	v_add_f32_e32 v122, v123, v122
	v_fmac_f32_e32 v118, v120, v120
	v_fmac_f32_e32 v115, v114, v114
	s_waitcnt lgkmcnt(0)
	v_pk_mul_f32 v[14:15], v[14:15], v[64:65] op_sel_hi:[1,0]
	v_pk_mul_f32 v[12:13], v[12:13], v[64:65] op_sel_hi:[1,0]
	v_pk_mul_f32 v[10:11], v[10:11], v[64:65] op_sel_hi:[1,0]
	v_pk_mul_f32 v[8:9], v[8:9], v[64:65] op_sel_hi:[1,0]
	v_pk_mul_f32 v[6:7], v[6:7], v[64:65] op_sel_hi:[1,0]
	v_pk_mul_f32 v[4:5], v[4:5], v[64:65] op_sel_hi:[1,0]
	v_pk_mul_f32 v[2:3], v[2:3], v[64:65] op_sel_hi:[1,0]
	v_pk_mul_f32 v[0:1], v[0:1], v[64:65] op_sel_hi:[1,0]
	v_mul_f32_e32 v64, v127, v127
	v_fmac_f32_e32 v64, v126, v126
	v_mul_f32_e32 v126, v129, v129
	v_fmac_f32_e32 v126, v128, v128
	v_add_f32_e32 v64, v64, v126
	v_mul_f32_e32 v114, v117, v117
	v_add_f32_e32 v64, v64, v122
	v_add_f32_e32 v118, v119, v118
	v_fmac_f32_e32 v114, v116, v116
	v_add_f32_e32 v64, v118, v64
	v_add_f32_e32 v114, v115, v114
	v_add_f32_e32 v64, v114, v64
	v_lshlrev_b32_e32 v148, 16, v170
	v_and_b32_e32 v149, 0xffff0000, v170
	v_lshlrev_b32_e32 v150, 16, v171
	v_and_b32_e32 v151, 0xffff0000, v171
	ds_swizzle_b32 v114, v64 offset:swizzle(SWAP,16)
	v_pk_fma_f32 v[12:13], v[142:143], v[12:13], v[148:149]
	v_pk_fma_f32 v[14:15], v[144:145], v[14:15], v[150:151]
	v_lshlrev_b32_e32 v142, 16, v172
	v_and_b32_e32 v143, 0xffff0000, v172
	v_lshlrev_b32_e32 v144, 16, v173
	v_and_b32_e32 v145, 0xffff0000, v173
	v_pk_fma_f32 v[8:9], v[138:139], v[8:9], v[142:143]
	v_pk_fma_f32 v[10:11], v[140:141], v[10:11], v[144:145]
	v_lshlrev_b32_e32 v138, 16, v162
	v_and_b32_e32 v139, 0xffff0000, v162
	v_lshlrev_b32_e32 v140, 16, v163
	v_and_b32_e32 v141, 0xffff0000, v163
	v_add_u32_e32 v146, 0xb0, v230
	v_pk_fma_f32 v[4:5], v[134:135], v[4:5], v[138:139]
	v_pk_fma_f32 v[6:7], v[136:137], v[6:7], v[140:141]
	v_lshlrev_b32_e32 v134, 16, v164
	v_and_b32_e32 v135, 0xffff0000, v164
	v_lshlrev_b32_e32 v136, 16, v165
	v_and_b32_e32 v137, 0xffff0000, v165
	v_ashrrev_i32_e32 v147, 31, v146
	v_pk_fma_f32 v[0:1], v[130:131], v[0:1], v[134:135]
	v_pk_fma_f32 v[2:3], v[132:133], v[2:3], v[136:137]
	v_cndmask_b32_e32 v15, v238, v15, vcc
	v_cndmask_b32_e32 v13, v238, v13, vcc
	v_cndmask_b32_e32 v11, v238, v11, vcc
	v_cndmask_b32_e32 v9, v238, v9, vcc
	v_cndmask_b32_e32 v7, v238, v7, vcc
	v_cndmask_b32_e32 v5, v238, v5, vcc
	v_cndmask_b32_e32 v3, v238, v3, vcc
	v_cndmask_b32_e32 v1, v238, v1, vcc
	v_lshlrev_b64 v[134:135], 11, v[146:147]
	s_waitcnt lgkmcnt(0)
	v_add_f32_e32 v64, v64, v114
	v_cndmask_b32_e32 v14, v238, v14, vcc
	v_cndmask_b32_e32 v12, v238, v12, vcc
	v_cvt_pk_bf16_f32 v13, v12, v13
	v_cvt_pk_bf16_f32 v15, v14, v15
	v_cndmask_b32_e32 v10, v238, v10, vcc
	v_cndmask_b32_e32 v8, v238, v8, vcc
	v_cvt_pk_bf16_f32 v9, v8, v9
	v_cvt_pk_bf16_f32 v11, v10, v11
	v_cndmask_b32_e32 v6, v238, v6, vcc
	v_cndmask_b32_e32 v4, v238, v4, vcc
	v_cvt_pk_bf16_f32 v5, v4, v5
	v_cvt_pk_bf16_f32 v7, v6, v7
	v_cndmask_b32_e32 v2, v238, v2, vcc
	v_cndmask_b32_e32 v0, v238, v0, vcc
	v_cvt_pk_bf16_f32 v1, v0, v1
	v_cvt_pk_bf16_f32 v3, v2, v3
	v_lshl_add_u64 v[134:135], s[0:1], 0, v[134:135]
	v_mov_b32_e32 v114, v64
	v_lshlrev_b32_e32 v12, 16, v13
	v_and_b32_e32 v13, 0xffff0000, v13
	v_lshlrev_b32_e32 v14, 16, v15
	v_and_b32_e32 v15, 0xffff0000, v15
	v_lshlrev_b32_e32 v8, 16, v9
	v_and_b32_e32 v9, 0xffff0000, v9
	v_lshlrev_b32_e32 v10, 16, v11
	v_and_b32_e32 v11, 0xffff0000, v11
	v_lshlrev_b32_e32 v4, 16, v5
	v_and_b32_e32 v5, 0xffff0000, v5
	v_lshlrev_b32_e32 v6, 16, v7
	v_and_b32_e32 v7, 0xffff0000, v7
	v_lshlrev_b32_e32 v0, 16, v1
	v_and_b32_e32 v1, 0xffff0000, v1
	v_lshlrev_b32_e32 v2, 16, v3
	v_and_b32_e32 v3, 0xffff0000, v3
	v_cvt_pk_bf16_f32 v130, v12, v13
	v_cvt_pk_bf16_f32 v131, v14, v15
	v_cvt_pk_bf16_f32 v132, v8, v9
	v_cvt_pk_bf16_f32 v133, v10, v11
	v_lshl_add_u64 v[134:135], v[134:135], 0, v[182:183]
	v_permlane32_swap_b32_e32 v64, v114
	v_readlane_b32 s7, v250, 18
	v_readlane_b32 s8, v250, 19
	v_readlane_b32 s9, v250, 20
	v_readlane_b32 s10, v250, 21
	v_readlane_b32 s11, v250, 22
	v_readlane_b32 s12, v250, 23
	v_readlane_b32 s13, v250, 24
	v_readlane_b32 s14, v250, 25
	v_readlane_b32 s15, v250, 26
	v_readlane_b32 s18, v250, 29
	v_readlane_b32 s19, v250, 30
	global_store_dwordx4 v[134:135], v[130:133], off sc1
	s_nop 1
	v_cvt_pk_bf16_f32 v130, v4, v5
	v_cvt_pk_bf16_f32 v131, v6, v7
	v_cvt_pk_bf16_f32 v132, v0, v1
	v_cvt_pk_bf16_f32 v133, v2, v3
	global_store_dwordx4 v[134:135], v[130:133], off offset:256 sc1
	s_and_saveexec_b64 s[0:1], s[42:43]
	s_lshl_b32 s3, s34, 10
	s_add_i32 s3, s48, s3
	v_add_u32_e32 v115, s3, v232
	v_add_f32_e32 v64, v64, v114
	ds_write_b32 v115, v64
	s_or_b64 exec, exec, s[0:1]
	v_mul_f32_e32 v64, v111, v111
	v_mul_f32_e32 v107, v107, v107
	v_fmac_f32_e32 v64, v110, v110
	v_mul_f32_e32 v110, v113, v113
	v_fmac_f32_e32 v107, v106, v106
	v_mul_f32_e32 v106, v109, v109
	v_mul_f32_e32 v103, v103, v103
	v_fmac_f32_e32 v110, v112, v112
	v_fmac_f32_e32 v106, v108, v108
	v_fmac_f32_e32 v103, v102, v102
	v_mul_f32_e32 v102, v105, v105
	v_mul_f32_e32 v99, v99, v99
	v_add_f32_e32 v64, v64, v110
	v_add_f32_e32 v106, v107, v106
	v_fmac_f32_e32 v102, v104, v104
	v_fmac_f32_e32 v99, v98, v98
	v_mul_f32_e32 v98, v101, v101
	v_add_f32_e32 v64, v64, v106
	v_add_f32_e32 v102, v103, v102
	v_fmac_f32_e32 v98, v100, v100
	v_add_f32_e32 v64, v102, v64
	v_add_f32_e32 v98, v99, v98
	v_add_f32_e32 v64, v98, v64
	ds_swizzle_b32 v98, v64 offset:swizzle(SWAP,16)
	s_waitcnt lgkmcnt(0)
	v_add_f32_e32 v64, v64, v98
	v_mov_b32_e32 v98, v64
	s_nop 1
	v_permlane32_swap_b32_e32 v64, v98
	s_and_saveexec_b64 s[0:1], s[42:43]
	s_lshl_b32 s3, s34, 10
	s_add_i32 s3, s48, s3
	v_add_u32_e32 v99, s3, v232
	v_add_f32_e32 v64, v64, v98
	ds_write_b32 v99, v64 offset:256
	s_or_b64 exec, exec, s[0:1]
	v_mul_f32_e32 v64, v95, v95
	v_mul_f32_e32 v91, v91, v91
	v_fmac_f32_e32 v64, v94, v94
	v_mul_f32_e32 v94, v97, v97
	v_fmac_f32_e32 v91, v90, v90
	v_mul_f32_e32 v90, v93, v93
	v_mul_f32_e32 v87, v87, v87
	v_fmac_f32_e32 v94, v96, v96
	v_fmac_f32_e32 v90, v92, v92
	v_fmac_f32_e32 v87, v86, v86
	v_mul_f32_e32 v86, v89, v89
	v_mul_f32_e32 v83, v83, v83
	v_add_f32_e32 v64, v64, v94
	v_add_f32_e32 v90, v91, v90
	v_fmac_f32_e32 v86, v88, v88
	v_fmac_f32_e32 v83, v82, v82
	v_mul_f32_e32 v82, v85, v85
	v_add_f32_e32 v64, v64, v90
	v_add_f32_e32 v86, v87, v86
	v_fmac_f32_e32 v82, v84, v84
	v_add_f32_e32 v64, v86, v64
	v_add_f32_e32 v82, v83, v82
	v_add_f32_e32 v64, v82, v64
	ds_swizzle_b32 v82, v64 offset:swizzle(SWAP,16)
	s_waitcnt lgkmcnt(0)
	v_add_f32_e32 v64, v64, v82
	v_mov_b32_e32 v82, v64
	s_nop 1
	v_permlane32_swap_b32_e32 v64, v82
	s_and_saveexec_b64 s[0:1], s[42:43]
	s_lshl_b32 s3, s34, 10
	s_add_i32 s3, s48, s3
	v_add_u32_e32 v83, s3, v232
	v_add_f32_e32 v64, v64, v82
	ds_write_b32 v83, v64 offset:512
	s_or_b64 exec, exec, s[0:1]
	v_mul_f32_e32 v64, v79, v79
	v_mul_f32_e32 v75, v75, v75
	v_fmac_f32_e32 v64, v78, v78
	v_mul_f32_e32 v78, v81, v81
	v_fmac_f32_e32 v75, v74, v74
	v_mul_f32_e32 v74, v77, v77
	v_mul_f32_e32 v71, v71, v71
	v_fmac_f32_e32 v78, v80, v80
	v_fmac_f32_e32 v74, v76, v76
	v_fmac_f32_e32 v71, v70, v70
	v_mul_f32_e32 v70, v73, v73
	v_mul_f32_e32 v67, v67, v67
	v_add_f32_e32 v64, v64, v78
	v_add_f32_e32 v74, v75, v74
	v_fmac_f32_e32 v70, v72, v72
	v_fmac_f32_e32 v67, v66, v66
	v_mul_f32_e32 v66, v69, v69
	v_add_f32_e32 v64, v64, v74
	v_add_f32_e32 v70, v71, v70
	v_fmac_f32_e32 v66, v68, v68
	v_add_f32_e32 v64, v70, v64
	v_add_f32_e32 v66, v67, v66
	v_add_f32_e32 v64, v66, v64
	ds_swizzle_b32 v66, v64 offset:swizzle(SWAP,16)
	s_waitcnt lgkmcnt(0)
	v_add_f32_e32 v64, v64, v66
	v_mov_b32_e32 v66, v64
	s_nop 1
	v_permlane32_swap_b32_e32 v64, v66
	s_and_saveexec_b64 s[0:1], s[42:43]
	s_lshl_b32 s3, s34, 10
	s_add_i32 s3, s48, s3
	v_add_u32_e32 v67, s3, v232
	v_add_f32_e32 v64, v64, v66
	ds_write_b32 v67, v64 offset:768
	s_or_b64 exec, exec, s[0:1]
	v_mul_f32_e32 v61, v61, v61
	v_mul_f32_e32 v57, v57, v57
	v_fmac_f32_e32 v61, v60, v60
	v_mul_f32_e32 v60, v63, v63
	v_fmac_f32_e32 v57, v56, v56
	v_mul_f32_e32 v56, v59, v59
	v_mul_f32_e32 v53, v53, v53
	v_fmac_f32_e32 v60, v62, v62
	v_fmac_f32_e32 v56, v58, v58
	v_fmac_f32_e32 v53, v52, v52
	v_mul_f32_e32 v52, v55, v55
	v_mul_f32_e32 v49, v49, v49
	v_add_f32_e32 v60, v61, v60
	v_add_f32_e32 v56, v57, v56
	v_fmac_f32_e32 v52, v54, v54
	v_fmac_f32_e32 v49, v48, v48
	v_mul_f32_e32 v48, v51, v51
	v_add_f32_e32 v56, v60, v56
	v_add_f32_e32 v52, v53, v52
	v_fmac_f32_e32 v48, v50, v50
	v_add_f32_e32 v52, v52, v56
	v_add_f32_e32 v48, v49, v48
	v_add_f32_e32 v48, v48, v52
	ds_swizzle_b32 v49, v48 offset:swizzle(SWAP,16)
	s_waitcnt lgkmcnt(0)
	v_add_f32_e32 v48, v48, v49
	v_mov_b32_e32 v49, v48
	s_nop 1
	v_permlane32_swap_b32_e32 v48, v49
	s_and_saveexec_b64 s[0:1], s[42:43]
	s_lshl_b32 s3, s34, 10
	s_add_i32 s3, s48, s3
	v_add_u32_e32 v50, s3, v232
	v_add_f32_e32 v48, v48, v49
	ds_write_b32 v50, v48 offset:2048
	s_or_b64 exec, exec, s[0:1]
	v_mul_f32_e32 v45, v45, v45
	v_mul_f32_e32 v41, v41, v41
	v_fmac_f32_e32 v45, v44, v44
	v_mul_f32_e32 v44, v47, v47
	v_fmac_f32_e32 v41, v40, v40
	v_mul_f32_e32 v40, v43, v43
	v_mul_f32_e32 v37, v37, v37
	v_fmac_f32_e32 v44, v46, v46
	v_fmac_f32_e32 v40, v42, v42
	v_fmac_f32_e32 v37, v36, v36
	v_mul_f32_e32 v36, v39, v39
	v_mul_f32_e32 v33, v33, v33
	v_add_f32_e32 v44, v45, v44
	v_add_f32_e32 v40, v41, v40
	v_fmac_f32_e32 v36, v38, v38
	v_fmac_f32_e32 v33, v32, v32
	v_mul_f32_e32 v32, v35, v35
	v_add_f32_e32 v40, v44, v40
	v_add_f32_e32 v36, v37, v36
	v_fmac_f32_e32 v32, v34, v34
	v_add_f32_e32 v36, v36, v40
	v_add_f32_e32 v32, v33, v32
	v_add_f32_e32 v32, v32, v36
	ds_swizzle_b32 v33, v32 offset:swizzle(SWAP,16)
	s_waitcnt lgkmcnt(0)
	v_add_f32_e32 v32, v32, v33
	v_mov_b32_e32 v33, v32
	s_nop 1
	v_permlane32_swap_b32_e32 v32, v33
	s_and_saveexec_b64 s[0:1], s[42:43]
	s_lshl_b32 s3, s34, 10
	s_add_i32 s3, s48, s3
	v_add_u32_e32 v34, s3, v232
	v_add_f32_e32 v32, v32, v33
	ds_write_b32 v34, v32 offset:2304
	s_or_b64 exec, exec, s[0:1]
	v_mul_f32_e32 v29, v29, v29
	v_mul_f32_e32 v25, v25, v25
	v_fmac_f32_e32 v29, v28, v28
	v_mul_f32_e32 v28, v31, v31
	v_fmac_f32_e32 v25, v24, v24
	v_mul_f32_e32 v24, v27, v27
	v_mul_f32_e32 v21, v21, v21
	v_fmac_f32_e32 v28, v30, v30
	v_fmac_f32_e32 v24, v26, v26
	v_fmac_f32_e32 v21, v20, v20
	v_mul_f32_e32 v20, v23, v23
	v_mul_f32_e32 v17, v17, v17
	v_add_f32_e32 v28, v29, v28
	v_add_f32_e32 v24, v25, v24
	v_fmac_f32_e32 v20, v22, v22
	v_fmac_f32_e32 v17, v16, v16
	v_mul_f32_e32 v16, v19, v19
	v_add_f32_e32 v24, v28, v24
	v_add_f32_e32 v20, v21, v20
	v_fmac_f32_e32 v16, v18, v18
	v_add_f32_e32 v20, v20, v24
	v_add_f32_e32 v16, v17, v16
	v_add_f32_e32 v16, v16, v20
	ds_swizzle_b32 v17, v16 offset:swizzle(SWAP,16)
	s_waitcnt lgkmcnt(0)
	v_add_f32_e32 v16, v16, v17
	v_mov_b32_e32 v17, v16
	s_nop 1
	v_permlane32_swap_b32_e32 v16, v17
	s_and_saveexec_b64 s[0:1], s[42:43]
	s_lshl_b32 s3, s34, 10
	s_add_i32 s3, s48, s3
	v_add_u32_e32 v18, s3, v232
	v_add_f32_e32 v16, v16, v17
	ds_write_b32 v18, v16 offset:2560
	s_or_b64 exec, exec, s[0:1]
	v_mul_f32_e32 v13, v13, v13
	v_mul_f32_e32 v9, v9, v9
	v_fmac_f32_e32 v13, v12, v12
	v_mul_f32_e32 v12, v15, v15
	v_fmac_f32_e32 v9, v8, v8
	v_mul_f32_e32 v8, v11, v11
	v_mul_f32_e32 v5, v5, v5
	v_fmac_f32_e32 v12, v14, v14
	v_fmac_f32_e32 v8, v10, v10
	v_fmac_f32_e32 v5, v4, v4
	v_mul_f32_e32 v4, v7, v7
	v_mul_f32_e32 v1, v1, v1
	v_add_f32_e32 v12, v13, v12
	v_add_f32_e32 v8, v9, v8
	v_fmac_f32_e32 v4, v6, v6
	v_fmac_f32_e32 v1, v0, v0
	v_mul_f32_e32 v0, v3, v3
	v_add_f32_e32 v8, v12, v8
	v_add_f32_e32 v4, v5, v4
	v_fmac_f32_e32 v0, v2, v2
	v_add_f32_e32 v4, v4, v8
	v_add_f32_e32 v0, v1, v0
	v_add_f32_e32 v0, v0, v4
	ds_swizzle_b32 v1, v0 offset:swizzle(SWAP,16)
	s_waitcnt lgkmcnt(0)
	v_add_f32_e32 v0, v0, v1
	v_mov_b32_e32 v1, v0
	s_nop 1
	v_permlane32_swap_b32_e32 v0, v1
	s_and_saveexec_b64 s[0:1], s[42:43]
	s_lshl_b32 s3, s34, 10
	s_add_i32 s48, s48, s3
	v_add_u32_e32 v2, s48, v232
	v_add_f32_e32 v0, v0, v1
	ds_write_b32 v2, v0 offset:2816
	s_or_b64 exec, exec, s[0:1]
	s_waitcnt lgkmcnt(0)
	s_barrier
	s_and_saveexec_b64 s[0:1], s[44:45]
	s_cbranch_execz .LBB0_114
	ds_read_b128 v[0:3], v233
	s_ashr_i32 s3, s2, 31
	v_lshl_add_u64 v[4:5], v[226:227], 4, s[40:41]
	s_waitcnt lgkmcnt(0)
	v_mov_b32_e32 v6, v1
	v_mov_b32_e32 v7, v2
	v_mov_b32_e32 v1, v3
	v_pk_add_f32 v[0:1], v[6:7], v[0:1]
	s_nop 0
	v_add_f32_e32 v2, v0, v1
	v_lshl_add_u64 v[0:1], s[2:3], 2, v[4:5]
	global_store_dword v[0:1], v2, off sc1

.LBB0_127:
	s_barrier
	s_mov_b64 s[2:3], -1
	s_and_b64 vcc, s[62:63], exec
	s_cbranch_vccz .LBB0_129
	s_add_i32 s3, s42, -2
	s_mul_i32 s2, s3, 0xab
	s_bfe_u32 s2, s2, 0x70009
	s_mul_i32 s2, s2, 3
	s_sub_i32 s2, s3, s2
	s_and_b32 s2, s2, 0xff
	s_mul_i32 s2, s2, 0xa400
	s_add_i32 s4, s2, s90
	v_add_u32_e32 v8, s4, v60
	v_add_u32_e32 v62, s2, v40
	ds_read2st64_b64 v[12:15], v8 offset0:64 offset1:65
	ds_read2st64_b64 v[16:19], v8 offset0:66 offset1:67
	ds_read_b128 v[94:97], v62 offset:16384
	ds_read_b128 v[102:105], v62 offset:18432
	ds_read_b128 v[110:113], v62 offset:20480
	ds_read_b128 v[118:121], v62 offset:22528
	ds_read_b128 v[98:101], v62 offset:17408
	ds_read_b128 v[106:109], v62 offset:19456
	ds_read_b128 v[114:117], v62 offset:21504
	ds_read_b128 v[122:125], v62 offset:23552
	ds_read_b128 v[126:129], v62
	ds_read_b128 v[130:133], v62 offset:1024
	ds_read_b128 v[134:137], v62 offset:2048
	ds_read_b128 v[138:141], v62 offset:3072
	ds_read_b128 v[142:145], v62 offset:4096
	s_add_i32 s2, s2, s37
	s_and_b64 s[4:5], s[0:1], exec
	s_cselect_b32 s3, s3, s43
	v_lshl_add_u32 v9, v61, 2, s2
	v_lshl_add_u32 v11, s3, 6, v61
	s_add_i32 s2, s2, s36
	v_mov_b32_e32 v10, s2
	s_waitcnt lgkmcnt(13)
	v_lshlrev_b32_e32 v20, 16, v12
	v_and_b32_e32 v21, 0xffff0000, v12
	v_lshlrev_b32_e32 v22, 16, v13
	v_and_b32_e32 v23, 0xffff0000, v13
	v_lshlrev_b32_e32 v24, 16, v14
	v_and_b32_e32 v25, 0xffff0000, v14
	v_lshlrev_b32_e32 v26, 16, v15
	v_and_b32_e32 v27, 0xffff0000, v15
	v_lshlrev_b32_e32 v28, 16, v16
	v_and_b32_e32 v29, 0xffff0000, v16
	v_lshlrev_b32_e32 v30, 16, v17
	v_and_b32_e32 v31, 0xffff0000, v17
	v_lshlrev_b32_e32 v32, 16, v18
	v_and_b32_e32 v33, 0xffff0000, v18
	v_lshlrev_b32_e32 v34, 16, v19
	v_and_b32_e32 v35, 0xffff0000, v19
	s_waitcnt lgkmcnt(9)
	v_mfma_f32_16x16x32_bf16 v[20:23], v[94:97], v[0:3], v[20:23]
	v_mfma_f32_16x16x32_bf16 v[24:27], v[102:105], v[0:3], v[24:27]
	v_mfma_f32_16x16x32_bf16 v[28:31], v[110:113], v[0:3], v[28:31]
	v_mfma_f32_16x16x32_bf16 v[32:35], v[118:121], v[0:3], v[32:35]
	ds_read_b128 v[146:149], v62 offset:5120
	ds_read_b128 v[150:153], v62 offset:6144
	ds_read_b128 v[154:157], v62 offset:7168
	ds_read_b32 v206, v10 offset:40960
	s_waitcnt lgkmcnt(9)
	v_mfma_f32_16x16x32_bf16 v[20:23], v[98:101], v[4:7], v[20:23]
	v_mfma_f32_16x16x32_bf16 v[24:27], v[106:109], v[4:7], v[24:27]
	v_mfma_f32_16x16x32_bf16 v[28:31], v[114:117], v[4:7], v[28:31]
	v_mfma_f32_16x16x32_bf16 v[32:35], v[122:125], v[4:7], v[32:35]
	ds_read_b128 v[190:193], v9 offset:41216
	ds_read_b128 v[194:197], v9 offset:41280
	ds_read_b128 v[198:201], v9 offset:41344
	ds_read_b128 v[202:205], v9 offset:41408
	s_waitcnt lgkmcnt(5)
	ds_read_b128 v[158:161], v62 offset:8192
	ds_read_b128 v[166:169], v62 offset:10240
	ds_read_b128 v[174:177], v62 offset:12288
	ds_read_b128 v[182:185], v62 offset:14336
	v_mfma_f32_16x16x32_bf16 v[36:39], v[126:129], v[0:3], 0
	v_mfma_f32_16x16x32_bf16 v[36:39], v[130:133], v[4:7], v[36:39]
	v_mfma_f32_16x16x32_bf16 v[66:69], v[134:137], v[0:3], 0
	v_mfma_f32_16x16x32_bf16 v[66:69], v[138:141], v[4:7], v[66:69]
	ds_read_b128 v[162:165], v62 offset:9216
	ds_read_b128 v[170:173], v62 offset:11264
	ds_read_b128 v[178:181], v62 offset:13312
	ds_read_b128 v[186:189], v62 offset:15360
	v_mfma_f32_16x16x32_bf16 v[70:73], v[142:145], v[0:3], 0
	v_mfma_f32_16x16x32_bf16 v[70:73], v[146:149], v[4:7], v[70:73]
	v_mfma_f32_16x16x32_bf16 v[74:77], v[150:153], v[0:3], 0
	v_mfma_f32_16x16x32_bf16 v[74:77], v[154:157], v[4:7], v[74:77]
	s_waitcnt lgkmcnt(8)
	v_pk_mul_f32 v[44:45], v[44:45], v[206:207] op_sel_hi:[1,0]
	v_pk_mul_f32 v[46:47], v[46:47], v[206:207] op_sel_hi:[1,0]
	v_pk_mul_f32 v[48:49], v[48:49], v[206:207] op_sel_hi:[1,0]
	v_pk_mul_f32 v[50:51], v[50:51], v[206:207] op_sel_hi:[1,0]
	v_pk_mul_f32 v[52:53], v[52:53], v[206:207] op_sel_hi:[1,0]
	v_pk_mul_f32 v[54:55], v[54:55], v[206:207] op_sel_hi:[1,0]
	v_pk_mul_f32 v[56:57], v[56:57], v[206:207] op_sel_hi:[1,0]
	v_pk_mul_f32 v[58:59], v[58:59], v[206:207] op_sel_hi:[1,0]
	v_cvt_pk_bf16_f32 v78, v20, v21
	v_cvt_pk_bf16_f32 v79, v22, v23
	v_cvt_pk_bf16_f32 v80, v24, v25
	v_cvt_pk_bf16_f32 v81, v26, v27
	v_cvt_pk_bf16_f32 v82, v28, v29
	v_cvt_pk_bf16_f32 v83, v30, v31
	v_cvt_pk_bf16_f32 v84, v32, v33
	v_cvt_pk_bf16_f32 v85, v34, v35
	v_pk_mul_f32 v[20:21], v[20:21], v[190:191]
	v_pk_mul_f32 v[22:23], v[22:23], v[192:193]
	v_pk_mul_f32 v[24:25], v[24:25], v[194:195]
	v_pk_mul_f32 v[26:27], v[26:27], v[196:197]
	v_pk_mul_f32 v[28:29], v[28:29], v[198:199]
	v_pk_mul_f32 v[30:31], v[30:31], v[200:201]
	v_pk_mul_f32 v[32:33], v[32:33], v[202:203]
	v_pk_mul_f32 v[34:35], v[34:35], v[204:205]
	v_cvt_pk_bf16_f32 v86, v20, v21
	v_cvt_pk_bf16_f32 v87, v22, v23
	v_cvt_pk_bf16_f32 v88, v24, v25
	v_cvt_pk_bf16_f32 v89, v26, v27
	v_cvt_pk_bf16_f32 v90, v28, v29
	v_cvt_pk_bf16_f32 v91, v30, v31
	v_cvt_pk_bf16_f32 v92, v32, v33
	v_cvt_pk_bf16_f32 v93, v34, v35
	s_waitcnt lgkmcnt(4)
	v_mfma_f32_16x16x32_bf16 v[44:47], v[158:161], v[86:89], v[44:47]
	v_mfma_f32_16x16x32_bf16 v[48:51], v[166:169], v[86:89], v[48:51]
	v_mfma_f32_16x16x32_bf16 v[52:55], v[174:177], v[86:89], v[52:55]
	v_mfma_f32_16x16x32_bf16 v[56:59], v[182:185], v[86:89], v[56:59]
	ds_read_b128 v[94:97], v62 offset:24576
	ds_read_b128 v[98:101], v62 offset:25600
	ds_read_b128 v[102:105], v62 offset:26624
	ds_read_b128 v[106:109], v62 offset:27648
	s_waitcnt lgkmcnt(4)
	v_mfma_f32_16x16x32_bf16 v[44:47], v[162:165], v[90:93], v[44:47]
	v_mfma_f32_16x16x32_bf16 v[48:51], v[170:173], v[90:93], v[48:51]
	v_mfma_f32_16x16x32_bf16 v[52:55], v[178:181], v[90:93], v[52:55]
	v_mfma_f32_16x16x32_bf16 v[56:59], v[186:189], v[90:93], v[56:59]
	ds_read_b128 v[110:113], v62 offset:28672
	ds_read_b128 v[114:117], v62 offset:29696
	ds_read_b128 v[118:121], v62 offset:30720
	ds_read_b128 v[122:125], v62 offset:31744
	ds_read_b128 v[126:129], v9 offset:40960
	ds_read_b128 v[130:133], v9 offset:41024
	ds_read_b128 v[134:137], v9 offset:41088
	ds_read_b128 v[138:141], v9 offset:41152
	s_waitcnt lgkmcnt(8)
	v_mfma_f32_16x16x32_bf16 v[142:145], v[94:97], v[78:81], 0
	v_mfma_f32_16x16x32_bf16 v[142:145], v[98:101], v[82:85], v[142:145]
	v_mfma_f32_16x16x32_bf16 v[146:149], v[102:105], v[78:81], 0
	v_mfma_f32_16x16x32_bf16 v[146:149], v[106:109], v[82:85], v[146:149]
	v_cvt_pk_bf16_f32 v0, v44, v45
	v_cvt_pk_bf16_f32 v1, v46, v47
	v_cvt_pk_bf16_f32 v2, v48, v49
	v_cvt_pk_bf16_f32 v3, v50, v51
	v_cvt_pk_bf16_f32 v4, v52, v53
	v_cvt_pk_bf16_f32 v5, v54, v55
	v_cvt_pk_bf16_f32 v6, v56, v57
	v_cvt_pk_bf16_f32 v7, v58, v59
	s_waitcnt lgkmcnt(4)
	v_mfma_f32_16x16x32_bf16 v[150:153], v[110:113], v[78:81], 0
	v_mfma_f32_16x16x32_bf16 v[150:153], v[114:117], v[82:85], v[150:153]
	v_mfma_f32_16x16x32_bf16 v[154:157], v[118:121], v[78:81], 0
	v_mfma_f32_16x16x32_bf16 v[154:157], v[122:125], v[82:85], v[154:157]
	v_mad_i64_i32 v[208:209], s[4:5], v11, s39, v[42:43]
	v_add_u32_e32 v62, 16, v11
	v_mad_i64_i32 v[210:211], s[4:5], v62, s39, v[42:43]
	v_add_u32_e32 v62, 32, v11
	v_mad_i64_i32 v[212:213], s[4:5], v62, s39, v[42:43]
	v_add_u32_e32 v62, 48, v11
	v_mad_i64_i32 v[62:63], s[4:5], v62, s39, v[42:43]
	s_waitcnt lgkmcnt(0)
	v_pk_fma_f32 v[36:37], v[36:37], v[126:127], v[142:143]
	v_pk_fma_f32 v[38:39], v[38:39], v[128:129], v[144:145]
	v_pk_fma_f32 v[66:67], v[66:67], v[130:131], v[146:147]
	v_pk_fma_f32 v[68:69], v[68:69], v[132:133], v[148:149]
	v_cvt_pk_bf16_f32 v36, v36, v37
	v_cvt_pk_bf16_f32 v38, v38, v39
	v_cvt_pk_bf16_f32 v66, v66, v67
	v_cvt_pk_bf16_f32 v68, v68, v69
	global_store_short v[208:209], v36, off sc1
	global_store_short_d16_hi v[208:209], v36, off offset:768 sc1
	global_store_short v[208:209], v38, off offset:1536 sc1
	global_store_short_d16_hi v[208:209], v38, off offset:2304 sc1
	global_store_short v[210:211], v66, off sc1
	global_store_short_d16_hi v[210:211], v66, off offset:768 sc1
	global_store_short v[210:211], v68, off offset:1536 sc1
	global_store_short_d16_hi v[210:211], v68, off offset:2304 sc1
	v_pk_fma_f32 v[70:71], v[70:71], v[134:135], v[150:151]
	v_pk_fma_f32 v[72:73], v[72:73], v[136:137], v[152:153]
	v_pk_fma_f32 v[74:75], v[74:75], v[138:139], v[154:155]
	v_pk_fma_f32 v[76:77], v[76:77], v[140:141], v[156:157]
	v_cvt_pk_bf16_f32 v70, v70, v71
	v_cvt_pk_bf16_f32 v72, v72, v73
	v_cvt_pk_bf16_f32 v74, v74, v75
	v_cvt_pk_bf16_f32 v76, v76, v77
	global_store_short v[212:213], v70, off sc1
	global_store_short_d16_hi v[212:213], v70, off offset:768 sc1
	global_store_short v[212:213], v72, off offset:1536 sc1
	global_store_short_d16_hi v[212:213], v72, off offset:2304 sc1
	global_store_short v[62:63], v74, off sc1
	global_store_short_d16_hi v[62:63], v74, off offset:768 sc1
	global_store_short v[62:63], v76, off offset:1536 sc1
	global_store_short_d16_hi v[62:63], v76, off offset:2304 sc1
	s_mov_b64 s[2:3], 0

.LBB0_221:
	s_or_b64 exec, exec, s[0:1]
	s_waitcnt lgkmcnt(0)
	v_lshl_add_u32 v34, v151, 2, s79
	ds_read_b128 v[38:41], v34
	ds_read_b128 v[42:45], v34 offset:32
	ds_read_b128 v[46:49], v34 offset:64
	ds_read_b128 v[50:53], v34 offset:96
	v_lshlrev_b32_e32 v90, 4, v148
	v_and_b32_e32 v90, 48, v90
	v_lshlrev_b32_e32 v90, 2, v90
	global_load_dwordx4 v[74:77], v90, s[52:53]
	global_load_dwordx4 v[78:81], v90, s[52:53] offset:32
	global_load_dwordx4 v[82:85], v90, s[52:53] offset:16
	global_load_dwordx4 v[86:89], v90, s[52:53] offset:48
	s_waitcnt lgkmcnt(0)
	v_lshrrev_b32_e32 v94, 2, v93
	v_and_b32_e32 v95, 15, v93
	v_and_b32_e32 v94, -4, v94
	v_mov_b32_e32 v96, 0x405132
	v_lshrrev_b32_e32 v94, v94, v96
	v_readlane_b32 vcc_lo, v254, 37
	v_lshlrev_b32_e32 v95, 7, v95
	v_and_b32_e32 v94, 7, v94
	v_readlane_b32 vcc_hi, v251, 13
	v_or_b32_e32 v95, v95, v149
	v_or_b32_e32 v95, vcc_lo, v95
	v_or_b32_e32 v95, s33, v95
	v_lshlrev_b32_e32 v94, 7, v94
	v_bfe_u32 v97, v148, 5, 1
	v_mov_b32_e32 v96, 0x1080
	v_lshl_add_u32 v94, vcc_hi, 1, v94
	v_mov_b64_e32 v[98:99], s[72:73]
	v_lshl_add_u32 v94, v97, 4, v94
	v_mad_u64_u32 v[98:99], vcc, v95, v96, v[98:99]
	v_mov_b32_e32 v95, 0
	s_nop 0
	v_lshl_add_u64 v[98:99], v[98:99], 0, v[94:95]
	global_load_dwordx4 v[100:103], v[98:99], off
	global_load_dwordx4 v[104:107], v[98:99], off offset:32
	v_lshlrev_b32_e32 v37, 2, v149
	v_readlane_b32 s0, v251, 19
	s_waitcnt lgkmcnt(0)
	v_readlane_b32 s1, v254, 37
	v_mul_f32_e32 v54, v16, v38
	v_mul_f32_e32 v55, v0, v38
	v_or_b32_e32 v56, s1, v151
	v_mul_u32_u24_e32 v56, 0x110, v56
	v_add3_u32 v56, s0, v56, v37
	ds_write2_b32 v56, v54, v55 offset1:32
	v_readlane_b32 s1, v254, 23
	v_mul_f32_e32 v57, v17, v39
	v_mul_f32_e32 v58, v1, v39
	v_or_b32_e32 v59, s1, v151
	v_mul_u32_u24_e32 v59, 0x110, v59
	v_add3_u32 v59, s0, v59, v37
	ds_write2_b32 v59, v57, v58 offset1:32
	v_readlane_b32 s1, v254, 24
	v_mul_f32_e32 v54, v18, v40
	v_mul_f32_e32 v55, v2, v40
	v_or_b32_e32 v56, s1, v151
	v_mul_u32_u24_e32 v56, 0x110, v56
	v_add3_u32 v56, s0, v56, v37
	ds_write2_b32 v56, v54, v55 offset1:32
	v_readlane_b32 s1, v254, 25
	v_mul_f32_e32 v57, v19, v41
	v_mul_f32_e32 v58, v3, v41
	v_or_b32_e32 v59, s1, v151
	v_mul_u32_u24_e32 v59, 0x110, v59
	v_add3_u32 v59, s0, v59, v37
	ds_write2_b32 v59, v57, v58 offset1:32
	v_readlane_b32 s1, v254, 26
	v_mul_f32_e32 v54, v20, v42
	v_mul_f32_e32 v55, v4, v42
	v_or_b32_e32 v56, s1, v151
	v_mul_u32_u24_e32 v56, 0x110, v56
	v_add3_u32 v56, s0, v56, v37
	ds_write2_b32 v56, v54, v55 offset1:32
	v_readlane_b32 s1, v254, 27
	v_mul_f32_e32 v57, v21, v43
	v_mul_f32_e32 v58, v5, v43
	v_or_b32_e32 v59, s1, v151
	v_mul_u32_u24_e32 v59, 0x110, v59
	v_add3_u32 v59, s0, v59, v37
	ds_write2_b32 v59, v57, v58 offset1:32
	v_readlane_b32 s1, v254, 28
	v_mul_f32_e32 v54, v22, v44
	v_mul_f32_e32 v55, v6, v44
	v_or_b32_e32 v56, s1, v151
	v_mul_u32_u24_e32 v56, 0x110, v56
	v_add3_u32 v56, s0, v56, v37
	ds_write2_b32 v56, v54, v55 offset1:32
	v_readlane_b32 s1, v254, 29
	v_mul_f32_e32 v57, v23, v45
	v_mul_f32_e32 v58, v7, v45
	v_or_b32_e32 v59, s1, v151
	v_mul_u32_u24_e32 v59, 0x110, v59
	v_add3_u32 v59, s0, v59, v37
	ds_write2_b32 v59, v57, v58 offset1:32
	v_readlane_b32 s1, v254, 30
	v_mul_f32_e32 v54, v24, v46
	v_mul_f32_e32 v55, v8, v46
	v_or_b32_e32 v56, s1, v151
	v_mul_u32_u24_e32 v56, 0x110, v56
	v_add3_u32 v56, s0, v56, v37
	ds_write2_b32 v56, v54, v55 offset1:32
	v_readlane_b32 s1, v254, 31
	v_mul_f32_e32 v57, v25, v47
	v_mul_f32_e32 v58, v9, v47
	v_or_b32_e32 v59, s1, v151
	v_mul_u32_u24_e32 v59, 0x110, v59
	v_add3_u32 v59, s0, v59, v37
	ds_write2_b32 v59, v57, v58 offset1:32
	v_readlane_b32 s1, v254, 32
	v_mul_f32_e32 v54, v26, v48
	v_mul_f32_e32 v55, v10, v48
	v_or_b32_e32 v56, s1, v151
	v_mul_u32_u24_e32 v56, 0x110, v56
	v_add3_u32 v56, s0, v56, v37
	ds_write2_b32 v56, v54, v55 offset1:32
	v_readlane_b32 s1, v254, 33
	v_mul_f32_e32 v57, v27, v49
	v_mul_f32_e32 v58, v11, v49
	v_or_b32_e32 v59, s1, v151
	v_mul_u32_u24_e32 v59, 0x110, v59
	v_add3_u32 v59, s0, v59, v37
	ds_write2_b32 v59, v57, v58 offset1:32
	v_readlane_b32 s1, v254, 34
	v_mul_f32_e32 v54, v28, v50
	v_mul_f32_e32 v55, v12, v50
	v_or_b32_e32 v56, s1, v151
	v_mul_u32_u24_e32 v56, 0x110, v56
	v_add3_u32 v56, s0, v56, v37
	ds_write2_b32 v56, v54, v55 offset1:32
	v_readlane_b32 s1, v254, 35
	v_mul_f32_e32 v57, v29, v51
	v_mul_f32_e32 v58, v13, v51
	v_or_b32_e32 v59, s1, v151
	v_mul_u32_u24_e32 v59, 0x110, v59
	v_add3_u32 v59, s0, v59, v37
	ds_write2_b32 v59, v57, v58 offset1:32
	v_readlane_b32 s1, v254, 36
	v_mul_f32_e32 v54, v30, v52
	v_mul_f32_e32 v55, v14, v52
	v_or_b32_e32 v56, s1, v151
	v_mul_u32_u24_e32 v56, 0x110, v56
	v_add3_u32 v56, s0, v56, v37
	ds_write2_b32 v56, v54, v55 offset1:32
	v_readlane_b32 s1, v254, 38
	v_mul_f32_e32 v57, v31, v53
	v_mul_f32_e32 v58, v15, v53
	v_or_b32_e32 v59, s1, v151
	v_mul_u32_u24_e32 v59, 0x110, v59
	v_add3_u32 v59, s0, v59, v37
	ds_write2_b32 v59, v57, v58 offset1:32
	v_ashrrev_i32_e32 v50, 2, v148
	v_lshlrev_b32_e32 v0, 4, v148
	v_and_b32_e32 v52, 48, v0
	v_lshlrev_b32_e32 v16, 2, v52
	s_waitcnt lgkmcnt(0)
	s_barrier
	s_movk_i32 s0, 0x110
	v_mul_lo_u32 v17, v50, s0
	v_add3_u32 v46, 0, v17, v16
	ds_read_b128 v[16:19], v46 offset:32
	ds_read_b128 v[20:23], v46 offset:48
	ds_read_b128 v[24:27], v46 offset:34864
	ds_read_b128 v[28:31], v46
	ds_read_b128 v[34:37], v46 offset:16
	ds_read_b128 v[38:41], v46 offset:34832
	ds_read_b128 v[42:45], v46 offset:34848
	ds_read_b128 v[46:49], v46 offset:34816
	s_waitcnt lgkmcnt(5)
	v_pk_fma_f32 v[20:21], v[110:111], v[24:25], v[20:21] neg_lo:[1,0,0] neg_hi:[1,0,0]
	v_pk_fma_f32 v[22:23], v[110:111], v[26:27], v[22:23] neg_lo:[1,0,0] neg_hi:[1,0,0]
	s_waitcnt lgkmcnt(2)
	v_pk_fma_f32 v[34:35], v[110:111], v[38:39], v[34:35] neg_lo:[1,0,0] neg_hi:[1,0,0]
	v_pk_fma_f32 v[36:37], v[110:111], v[40:41], v[36:37] neg_lo:[1,0,0] neg_hi:[1,0,0]
	s_waitcnt lgkmcnt(0)
	v_pk_fma_f32 v[28:29], v[110:111], v[46:47], v[28:29] neg_lo:[1,0,0] neg_hi:[1,0,0]
	v_pk_fma_f32 v[30:31], v[110:111], v[48:49], v[30:31] neg_lo:[1,0,0] neg_hi:[1,0,0]
	v_pk_mul_f32 v[46:47], v[28:29], v[28:29]
	v_pk_mul_f32 v[48:49], v[30:31], v[30:31]
	v_add_f32_e32 v46, v46, v47
	v_add_f32_e32 v46, v46, v48
	v_pk_mul_f32 v[38:39], v[34:35], v[34:35]
	v_add_f32_e32 v46, v46, v49
	v_add_f32_e32 v38, v46, v38
	v_pk_mul_f32 v[40:41], v[36:37], v[36:37]
	v_add_f32_e32 v38, v38, v39
	v_pk_fma_f32 v[16:17], v[110:111], v[42:43], v[16:17] neg_lo:[1,0,0] neg_hi:[1,0,0]
	v_add_f32_e32 v38, v38, v40
	v_pk_mul_f32 v[42:43], v[16:17], v[16:17]
	v_add_f32_e32 v38, v38, v41
	v_pk_fma_f32 v[18:19], v[110:111], v[44:45], v[18:19] neg_lo:[1,0,0] neg_hi:[1,0,0]
	v_add_f32_e32 v38, v38, v42
	v_pk_mul_f32 v[44:45], v[18:19], v[18:19]
	v_add_f32_e32 v38, v38, v43
	v_add_f32_e32 v38, v38, v44
	v_pk_mul_f32 v[24:25], v[20:21], v[20:21]
	v_add_f32_e32 v38, v38, v45
	v_add_f32_e32 v24, v38, v24
	v_pk_mul_f32 v[26:27], v[22:23], v[22:23]
	v_add_f32_e32 v24, v24, v25
	v_add_f32_e32 v24, v24, v26
	v_add_f32_e32 v24, v24, v27
	ds_swizzle_b32 v25, v24 offset:swizzle(SWAP,1)
	s_mov_b32 s0, 0x800000
	v_ashrrev_i32_e32 v51, 31, v50
	s_waitcnt lgkmcnt(0)
	v_add_f32_e32 v24, v24, v25
	ds_swizzle_b32 v25, v24 offset:swizzle(SWAP,2)
	s_waitcnt lgkmcnt(0)
	v_add_f32_e32 v24, v24, v25
	v_mov_b32_e32 v25, 0x3727c5ac
	v_fmamk_f32 v24, v24, 0x3c800000, v25
	v_mul_f32_e32 v25, 0x4b800000, v24
	v_cmp_gt_f32_e32 vcc, s0, v24
	s_add_u32 s0, s37, s33
	s_addc_u32 s1, 0, 0
	v_cndmask_b32_e32 v24, v24, v25, vcc
	v_rsq_f32_e32 v24, v24
	s_nop 0
	v_mul_f32_e32 v25, 0x45800000, v24
	v_cndmask_b32_e32 v24, v24, v25, vcc
	v_mul_f32_e32 v24, v147, v24
	v_pk_mul_f32 v[16:17], v[16:17], v[24:25] op_sel_hi:[1,0]
	v_pk_mul_f32 v[18:19], v[18:19], v[24:25] op_sel_hi:[1,0]
	v_pk_mul_f32 v[26:27], v[28:29], v[24:25] op_sel_hi:[1,0]
	v_pk_mul_f32 v[28:29], v[30:31], v[24:25] op_sel_hi:[1,0]
	v_pk_mul_f32 v[30:31], v[34:35], v[24:25] op_sel_hi:[1,0]
	v_pk_mul_f32 v[34:35], v[36:37], v[24:25] op_sel_hi:[1,0]
	v_pk_mul_f32 v[20:21], v[20:21], v[24:25] op_sel_hi:[1,0]
	s_waitcnt vmcnt(5)
	v_pk_mul_f32 v[0:1], v[74:75], v[26:27]
	s_waitcnt vmcnt(4)
	v_pk_mul_f32 v[4:5], v[78:79], v[16:17]
	v_pk_mul_f32 v[16:17], v[22:23], v[24:25] op_sel_hi:[1,0]
	v_pk_mul_f32 v[6:7], v[80:81], v[18:19]
	s_waitcnt vmcnt(2)
	v_pk_mul_f32 v[14:15], v[16:17], v[88:89]
	v_lshl_add_u64 v[16:17], s[0:1], 0, v[50:51]
	v_readlane_b32 s0, v250, 15
	v_lshlrev_b64 v[16:17], 11, v[16:17]
	v_readlane_b32 s12, v250, 27
	v_readlane_b32 s13, v250, 28
	v_readlane_b32 s1, v250, 16
	v_lshlrev_b32_e32 v18, 1, v52
	v_lshl_add_u64 v[16:17], s[12:13], 0, v[16:17]
	v_lshl_add_u64 v[16:17], v[16:17], 0, s[34:35]
	v_mov_b32_e32 v19, v65
	v_lshl_add_u64 v[16:17], v[16:17], 0, v[18:19]
	s_mov_b64 s[0:1], 0x2000200
	v_pk_mul_f32 v[2:3], v[76:77], v[28:29]
	v_pk_mul_f32 v[8:9], v[82:83], v[30:31]
	v_lshl_add_u64 v[18:19], v[16:17], 0, s[0:1]
	s_brev_b32 s0, 64
	v_pk_mul_f32 v[10:11], v[34:35], v[84:85]
	v_cvt_pk_bf16_f32 v0, v0, v1
	v_cvt_pk_bf16_f32 v1, v2, v3
	v_cvt_pk_bf16_f32 v2, v8, v9
	v_add_co_u32_e32 v8, vcc, s0, v16
	v_pk_mul_f32 v[12:13], v[86:87], v[20:21]
	v_cvt_pk_bf16_f32 v3, v10, v11
	v_addc_co_u32_e32 v9, vcc, 0, v17, vcc
	global_store_dwordx4 v[8:9], v[0:3], off offset:512 sc1
	s_mov_b64 s[0:1], 0
	v_readlane_b32 s2, v250, 17
	v_cvt_pk_bf16_f32 v0, v4, v5
	v_cvt_pk_bf16_f32 v1, v6, v7
	v_cvt_pk_bf16_f32 v2, v12, v13
	v_cvt_pk_bf16_f32 v3, v14, v15
	v_readlane_b32 s3, v250, 18
	v_readlane_b32 s4, v250, 19
	v_readlane_b32 s5, v250, 20
	v_readlane_b32 s6, v250, 21
	v_readlane_b32 s7, v250, 22
	v_readlane_b32 s8, v250, 23
	v_readlane_b32 s9, v250, 24
	v_readlane_b32 s10, v250, 25
	v_readlane_b32 s11, v250, 26
	v_readlane_b32 s14, v250, 29
	v_readlane_b32 s15, v250, 30
	global_store_dwordx4 v[18:19], v[0:3], off offset:16 sc1
	s_barrier

.LBB0_229:
	s_or_b32 s34, s0, s28
	v_lshl_add_u64 v[70:71], s[34:35], 0, v[114:115]
	v_mad_u64_u32 v[8:9], s[0:1], v70, s39, v[52:53]
	v_mad_i32_i24 v9, v71, s39, v9
	global_load_dwordx4 v[44:47], v[8:9], off
	v_mad_u64_u32 v[8:9], s[0:1], v70, s39, v[54:55]
	v_mad_i32_i24 v9, v71, s39, v9
	v_mov_b64_e32 v[16:17], s[18:19]
	global_load_dwordx4 v[48:51], v[8:9], off
	v_mad_u64_u32 v[8:9], s[0:1], v70, s4, v[16:17]
	v_mad_i32_i24 v9, v71, s4, v9
	s_mov_b32 s3, s35
	v_lshl_add_u64 v[8:9], v[8:9], 0, s[2:3]
	v_lshl_add_u64 v[8:9], v[8:9], 0, v[64:65]
	v_add_co_u32_e32 v8, vcc, s7, v8
	s_or_b32 s0, s34, 64
	s_nop 0
	v_addc_co_u32_e32 v9, vcc, 0, v9, vcc
	global_load_dwordx4 v[72:75], v[8:9], off offset:2304
	s_mov_b32 s1, s35
	v_lshl_add_u64 v[60:61], s[0:1], 0, v[114:115]
	v_mad_u64_u32 v[8:9], s[0:1], v60, s39, v[52:53]
	v_mad_i32_i24 v9, v61, s39, v9
	global_load_dwordx4 v[32:35], v[8:9], off
	v_mad_u64_u32 v[8:9], s[0:1], v60, s39, v[54:55]
	v_mad_i32_i24 v9, v61, s39, v9
	global_load_dwordx4 v[36:39], v[8:9], off
	v_mad_u64_u32 v[8:9], s[0:1], v60, s4, v[16:17]
	v_mad_i32_i24 v9, v61, s4, v9
	v_lshl_add_u64 v[8:9], v[8:9], 0, s[2:3]
	v_lshl_add_u64 v[8:9], v[8:9], 0, v[64:65]
	v_add_co_u32_e32 v8, vcc, s7, v8
	s_or_b32 s0, s34, 0x80
	s_mov_b32 s1, s35
	s_or_b32 s34, s34, 0xc0
	v_addc_co_u32_e32 v9, vcc, 0, v9, vcc
	v_lshl_add_u64 v[58:59], s[0:1], 0, v[114:115]
	v_lshl_add_u64 v[56:57], s[34:35], 0, v[114:115]
	global_load_dwordx4 v[40:43], v[8:9], off offset:2304
	v_mad_u64_u32 v[8:9], s[0:1], v58, s39, v[52:53]
	v_mad_u64_u32 v[12:13], s[0:1], v56, s39, v[54:55]
	v_mad_i32_i24 v9, v59, s39, v9
	v_mad_i32_i24 v13, v57, s39, v13
	global_load_dwordx4 v[20:23], v[8:9], off
	v_lshlrev_b64 v[70:71], 11, v[70:71]
	global_load_dwordx4 v[12:15], v[12:13], off
	v_mad_u64_u32 v[8:9], s[0:1], v58, s39, v[54:55]
	v_mad_i32_i24 v9, v59, s39, v9
	global_load_dwordx4 v[24:27], v[8:9], off
	v_mad_u64_u32 v[8:9], s[0:1], v58, s4, v[16:17]
	v_mad_i32_i24 v9, v59, s4, v9
	v_lshl_add_u64 v[8:9], v[8:9], 0, s[2:3]
	v_mad_u64_u32 v[16:17], s[0:1], v56, s4, v[16:17]
	v_lshl_add_u64 v[8:9], v[8:9], 0, v[64:65]
	v_mad_i32_i24 v17, v57, s4, v17
	v_add_co_u32_e32 v8, vcc, s7, v8
	v_lshl_add_u64 v[16:17], v[16:17], 0, s[2:3]
	s_nop 0
	v_addc_co_u32_e32 v9, vcc, 0, v9, vcc
	v_lshl_add_u64 v[16:17], v[16:17], 0, v[64:65]
	v_add_co_u32_e32 v16, vcc, s7, v16
	v_lshl_add_u64 v[70:71], s[16:17], 0, v[70:71]
	s_nop 0
	v_addc_co_u32_e32 v17, vcc, 0, v17, vcc
	v_lshl_add_u64 v[70:71], v[70:71], 0, s[2:3]
	global_load_dwordx4 v[28:31], v[8:9], off offset:2304
	v_mad_u64_u32 v[8:9], s[0:1], v56, s39, v[52:53]
	v_mad_i32_i24 v9, v57, s39, v9
	s_waitcnt vmcnt(9)
	v_lshlrev_b32_e32 v62, 16, v47
	v_and_b32_e32 v63, 0xffff0000, v47
	global_load_dwordx4 v[8:11], v[8:9], off
	s_waitcnt vmcnt(9)
	v_lshlrev_b32_e32 v66, 16, v51
	v_and_b32_e32 v67, 0xffff0000, v51
	v_pk_add_f32 v[62:63], v[62:63], v[66:67]
	v_lshlrev_b32_e32 v66, 16, v46
	v_and_b32_e32 v67, 0xffff0000, v46
	v_lshlrev_b32_e32 v46, 16, v50
	v_and_b32_e32 v47, 0xffff0000, v50
	v_pk_add_f32 v[46:47], v[66:67], v[46:47]
	v_pk_mul_f32 v[78:79], v[62:63], v[62:63]
	v_pk_mul_f32 v[80:81], v[46:47], v[46:47]
	global_load_dwordx4 v[16:19], v[16:17], off offset:2304
	s_waitcnt vmcnt(9)
	v_lshlrev_b32_e32 v68, 16, v74
	v_and_b32_e32 v69, 0xffff0000, v74
	v_mul_f32_e32 v50, 0xbfb8aa3b, v68
	v_mul_f32_e32 v51, 0xbfb8aa3b, v69
	v_exp_f32_e32 v50, v50
	v_exp_f32_e32 v51, v51
	v_lshlrev_b32_e32 v76, 16, v75
	v_and_b32_e32 v77, 0xffff0000, v75
	v_pk_add_f32 v[50:51], v[50:51], 1.0 op_sel_hi:[1,0]
	s_nop 0
	v_div_scale_f32 v66, s[0:1], v51, v51, v69
	v_rcp_f32_e32 v67, v66
	s_nop 0
	v_fma_f32 v74, -v66, v67, 1.0
	v_fmac_f32_e32 v67, v74, v67
	v_div_scale_f32 v74, vcc, v69, v51, v69
	v_mul_f32_e32 v75, v74, v67
	v_fma_f32 v82, -v66, v75, v74
	v_fmac_f32_e32 v75, v82, v67
	v_fma_f32 v66, -v66, v75, v74
	v_div_fmas_f32 v66, v66, v67, v75
	v_div_fixup_f32 v51, v66, v51, v69
	v_div_scale_f32 v66, s[0:1], v50, v50, v68
	v_rcp_f32_e32 v67, v66
	s_nop 0
	v_fma_f32 v69, -v66, v67, 1.0
	v_fmac_f32_e32 v67, v69, v67
	v_div_scale_f32 v69, vcc, v68, v50, v68
	v_mul_f32_e32 v74, v69, v67
	v_fma_f32 v75, -v66, v74, v69
	v_fmac_f32_e32 v74, v75, v67
	v_fma_f32 v66, -v66, v74, v69
	v_div_fmas_f32 v66, v66, v67, v74
	v_div_fixup_f32 v50, v66, v50, v68
	v_lshlrev_b32_e32 v66, 16, v45
	v_and_b32_e32 v67, 0xffff0000, v45
	v_lshlrev_b32_e32 v68, 16, v49
	v_and_b32_e32 v69, 0xffff0000, v49
	v_lshlrev_b32_e32 v45, 16, v73
	v_and_b32_e32 v49, 0xffff0000, v73
	v_pk_add_f32 v[66:67], v[66:67], v[68:69]
	v_mul_f32_e32 v68, 0xbfb8aa3b, v45
	v_mul_f32_e32 v69, 0xbfb8aa3b, v49
	v_exp_f32_e32 v68, v68
	v_exp_f32_e32 v69, v69
	v_pk_mul_f32 v[84:85], v[66:67], v[66:67]
	v_pk_add_f32 v[68:69], v[68:69], 1.0 op_sel_hi:[1,0]
	s_nop 0
	v_div_scale_f32 v73, s[0:1], v69, v69, v49
	v_rcp_f32_e32 v74, v73
	s_nop 0
	v_fma_f32 v75, -v73, v74, 1.0
	v_fmac_f32_e32 v74, v75, v74
	v_div_scale_f32 v75, vcc, v49, v69, v49
	v_mul_f32_e32 v82, v75, v74
	v_fma_f32 v83, -v73, v82, v75
	v_fmac_f32_e32 v82, v83, v74
	v_fma_f32 v73, -v73, v82, v75
	v_div_fmas_f32 v73, v73, v74, v82
	v_div_fixup_f32 v69, v73, v69, v49
	v_div_scale_f32 v49, s[0:1], v68, v68, v45
	v_rcp_f32_e32 v73, v49
	s_nop 0
	v_fma_f32 v74, -v49, v73, 1.0
	v_fmac_f32_e32 v73, v74, v73
	v_div_scale_f32 v74, vcc, v45, v68, v45
	v_mul_f32_e32 v75, v74, v73
	v_fma_f32 v82, -v49, v75, v74
	v_fmac_f32_e32 v75, v82, v73
	v_fma_f32 v49, -v49, v75, v74
	v_div_fmas_f32 v49, v49, v73, v75
	v_lshlrev_b32_e32 v73, 16, v72
	v_and_b32_e32 v72, 0xffff0000, v72
	v_div_fixup_f32 v68, v49, v68, v45
	v_lshlrev_b32_e32 v74, 16, v44
	v_and_b32_e32 v75, 0xffff0000, v44
	v_lshlrev_b32_e32 v44, 16, v48
	v_and_b32_e32 v45, 0xffff0000, v48
	v_mul_f32_e32 v48, 0xbfb8aa3b, v73
	v_mul_f32_e32 v49, 0xbfb8aa3b, v72
	v_exp_f32_e32 v48, v48
	v_exp_f32_e32 v49, v49
	v_pk_add_f32 v[44:45], v[74:75], v[44:45]
	v_pk_add_f32 v[48:49], v[48:49], 1.0 op_sel_hi:[1,0]
	s_nop 0
	v_div_scale_f32 v74, s[0:1], v49, v49, v72
	v_rcp_f32_e32 v75, v74
	v_pk_mul_f32 v[86:87], v[44:45], v[44:45]
	v_fma_f32 v82, -v74, v75, 1.0
	v_fmac_f32_e32 v75, v82, v75
	v_div_scale_f32 v82, vcc, v72, v49, v72
	v_mul_f32_e32 v83, v82, v75
	v_fma_f32 v88, -v74, v83, v82
	v_fmac_f32_e32 v83, v88, v75
	v_fma_f32 v74, -v74, v83, v82
	v_div_fmas_f32 v74, v74, v75, v83
	v_div_fixup_f32 v49, v74, v49, v72
	v_div_scale_f32 v72, s[0:1], v48, v48, v73
	v_rcp_f32_e32 v74, v72
	s_nop 0
	v_fma_f32 v75, -v72, v74, 1.0
	v_fmac_f32_e32 v74, v75, v74
	v_div_scale_f32 v75, vcc, v73, v48, v73
	v_mul_f32_e32 v82, v75, v74
	v_fma_f32 v83, -v72, v82, v75
	v_fmac_f32_e32 v82, v83, v74
	v_fma_f32 v72, -v72, v82, v75
	v_div_fmas_f32 v72, v72, v74, v82
	v_div_fixup_f32 v48, v72, v48, v73
	v_mul_f32_e32 v72, 0xbfb8aa3b, v76
	v_mul_f32_e32 v73, 0xbfb8aa3b, v77
	v_exp_f32_e32 v72, v72
	v_exp_f32_e32 v73, v73
	s_nop 0
	v_pk_add_f32 v[72:73], v[72:73], 1.0 op_sel_hi:[1,0]
	s_nop 0
	v_div_scale_f32 v74, s[0:1], v73, v73, v77
	v_rcp_f32_e32 v75, v74
	s_nop 0
	v_fma_f32 v82, -v74, v75, 1.0
	v_fmac_f32_e32 v75, v82, v75
	v_div_scale_f32 v82, vcc, v77, v73, v77
	v_mul_f32_e32 v83, v82, v75
	v_fma_f32 v88, -v74, v83, v82
	v_fmac_f32_e32 v83, v88, v75
	v_fma_f32 v74, -v74, v83, v82
	v_div_fmas_f32 v74, v74, v75, v83
	v_div_fixup_f32 v73, v74, v73, v77
	v_div_scale_f32 v74, s[0:1], v72, v72, v76
	v_rcp_f32_e32 v75, v74
	s_nop 0
	v_fma_f32 v77, -v74, v75, 1.0
	v_fmac_f32_e32 v75, v77, v75
	v_div_scale_f32 v77, vcc, v76, v72, v76
	v_mul_f32_e32 v82, v77, v75
	v_fma_f32 v83, -v74, v82, v77
	v_fmac_f32_e32 v82, v83, v75
	v_fma_f32 v74, -v74, v82, v77
	v_div_fmas_f32 v74, v74, v75, v82
	v_div_fixup_f32 v72, v74, v72, v76
	v_lshl_add_u64 v[74:75], v[70:71], 0, v[64:65]
	s_waitcnt vmcnt(8)
	v_lshlrev_b32_e32 v70, 16, v35
	v_and_b32_e32 v71, 0xffff0000, v35
	s_waitcnt vmcnt(7)
	v_lshlrev_b32_e32 v76, 16, v39
	v_and_b32_e32 v77, 0xffff0000, v39
	s_waitcnt vmcnt(6)
	v_lshlrev_b32_e32 v82, 16, v43
	v_and_b32_e32 v83, 0xffff0000, v43
	v_lshlrev_b32_e32 v43, 16, v42
	v_and_b32_e32 v42, 0xffff0000, v42
	v_pk_add_f32 v[70:71], v[70:71], v[76:77]
	v_lshlrev_b32_e32 v76, 16, v34
	v_and_b32_e32 v77, 0xffff0000, v34
	v_lshlrev_b32_e32 v34, 16, v38
	v_and_b32_e32 v35, 0xffff0000, v38
	v_mul_f32_e32 v38, 0xbfb8aa3b, v43
	v_mul_f32_e32 v39, 0xbfb8aa3b, v42
	v_exp_f32_e32 v38, v38
	v_exp_f32_e32 v39, v39
	v_pk_add_f32 v[34:35], v[76:77], v[34:35]
	v_pk_mul_f32 v[88:89], v[70:71], v[70:71]
	v_pk_mul_f32 v[90:91], v[34:35], v[34:35]
	v_pk_add_f32 v[38:39], v[38:39], 1.0 op_sel_hi:[1,0]
	s_nop 0
	v_div_scale_f32 v76, s[0:1], v39, v39, v42
	v_rcp_f32_e32 v77, v76
	s_nop 0
	v_fma_f32 v92, -v76, v77, 1.0
	v_fmac_f32_e32 v77, v92, v77
	v_div_scale_f32 v92, vcc, v42, v39, v42
	v_mul_f32_e32 v93, v92, v77
	v_fma_f32 v94, -v76, v93, v92
	v_fmac_f32_e32 v93, v94, v77
	v_fma_f32 v76, -v76, v93, v92
	v_div_fmas_f32 v76, v76, v77, v93
	v_div_fixup_f32 v39, v76, v39, v42
	v_div_scale_f32 v42, s[0:1], v38, v38, v43
	v_rcp_f32_e32 v76, v42
	s_nop 0
	v_fma_f32 v77, -v42, v76, 1.0
	v_fmac_f32_e32 v76, v77, v76
	v_div_scale_f32 v77, vcc, v43, v38, v43
	v_mul_f32_e32 v92, v77, v76
	v_fma_f32 v93, -v42, v92, v77
	v_fmac_f32_e32 v92, v93, v76
	v_fma_f32 v42, -v42, v92, v77
	v_div_fmas_f32 v42, v42, v76, v92
	v_div_fixup_f32 v38, v42, v38, v43
	v_lshlrev_b32_e32 v42, 16, v33
	v_and_b32_e32 v43, 0xffff0000, v33
	v_lshlrev_b32_e32 v33, 16, v41
	v_lshlrev_b32_e32 v76, 16, v37
	v_and_b32_e32 v77, 0xffff0000, v37
	v_and_b32_e32 v37, 0xffff0000, v41
	v_mul_f32_e32 v41, 0xbfb8aa3b, v33
	v_pk_add_f32 v[42:43], v[42:43], v[76:77]
	v_exp_f32_e32 v76, v41
	v_mul_f32_e32 v41, 0xbfb8aa3b, v37
	v_exp_f32_e32 v77, v41
	v_pk_mul_f32 v[92:93], v[42:43], v[42:43]
	v_pk_add_f32 v[76:77], v[76:77], 1.0 op_sel_hi:[1,0]
	s_nop 0
	v_div_scale_f32 v41, s[0:1], v77, v77, v37
	v_rcp_f32_e32 v94, v41
	s_nop 0
	v_fma_f32 v95, -v41, v94, 1.0
	v_fmac_f32_e32 v94, v95, v94
	v_div_scale_f32 v95, vcc, v37, v77, v37
	v_mul_f32_e32 v96, v95, v94
	v_fma_f32 v97, -v41, v96, v95
	v_fmac_f32_e32 v96, v97, v94
	v_fma_f32 v41, -v41, v96, v95
	v_div_fmas_f32 v41, v41, v94, v96
	v_div_fixup_f32 v77, v41, v77, v37
	v_div_scale_f32 v37, s[0:1], v76, v76, v33
	v_rcp_f32_e32 v41, v37
	v_and_b32_e32 v97, 0xffff0000, v40
	v_fma_f32 v94, -v37, v41, 1.0
	v_fmac_f32_e32 v41, v94, v41
	v_div_scale_f32 v94, vcc, v33, v76, v33
	v_mul_f32_e32 v95, v94, v41
	v_fma_f32 v96, -v37, v95, v94
	v_fmac_f32_e32 v95, v96, v41
	v_fma_f32 v37, -v37, v95, v94
	v_div_fmas_f32 v37, v37, v41, v95
	v_div_fixup_f32 v76, v37, v76, v33
	v_lshlrev_b32_e32 v94, 16, v32
	v_and_b32_e32 v95, 0xffff0000, v32
	v_lshlrev_b32_e32 v32, 16, v36
	v_and_b32_e32 v33, 0xffff0000, v36
	v_pk_add_f32 v[32:33], v[94:95], v[32:33]
	v_lshlrev_b32_e32 v96, 16, v40
	v_pk_mul_f32 v[36:37], v[32:33], v[32:33]
	v_mov_b32_e32 v41, v86
	v_mov_b32_e32 v40, v36
	v_mov_b32_e32 v86, v37
	v_mul_f32_e32 v36, 0xbfb8aa3b, v96
	v_mul_f32_e32 v37, 0xbfb8aa3b, v97
	v_exp_f32_e32 v36, v36
	v_exp_f32_e32 v37, v37
	v_pk_add_f32 v[40:41], v[40:41], v[86:87]
	v_pk_add_f32 v[36:37], v[36:37], 1.0 op_sel_hi:[1,0]
	s_nop 0
	v_div_scale_f32 v86, s[0:1], v37, v37, v97
	v_rcp_f32_e32 v87, v86
	s_nop 0
	v_fma_f32 v94, -v86, v87, 1.0
	v_fmac_f32_e32 v87, v94, v87
	v_div_scale_f32 v94, vcc, v97, v37, v97
	v_mul_f32_e32 v95, v94, v87
	v_fma_f32 v98, -v86, v95, v94
	v_fmac_f32_e32 v95, v98, v87
	v_fma_f32 v86, -v86, v95, v94
	v_div_fmas_f32 v86, v86, v87, v95
	v_div_fixup_f32 v37, v86, v37, v97
	v_div_scale_f32 v86, s[0:1], v36, v36, v96
	v_rcp_f32_e32 v87, v86
	s_mov_b32 s0, 0x358637bd
	v_fma_f32 v94, -v86, v87, 1.0
	v_fmac_f32_e32 v87, v94, v87
	v_div_scale_f32 v94, vcc, v96, v36, v96
	v_mul_f32_e32 v95, v94, v87
	v_fma_f32 v97, -v86, v95, v94
	v_fmac_f32_e32 v95, v97, v87
	v_fma_f32 v86, -v86, v95, v94
	v_div_fmas_f32 v86, v86, v87, v95
	v_div_fixup_f32 v36, v86, v36, v96
	v_mov_b32_e32 v86, v92
	v_mov_b32_e32 v87, v84
	v_pk_add_f32 v[40:41], v[86:87], v[40:41]
	v_mov_b32_e32 v84, v93
	v_pk_add_f32 v[40:41], v[84:85], v[40:41]
	v_mov_b32_e32 v84, v90
	v_mov_b32_e32 v85, v80
	v_pk_add_f32 v[40:41], v[84:85], v[40:41]
	v_mov_b32_e32 v80, v91
	v_pk_add_f32 v[40:41], v[80:81], v[40:41]
	v_mov_b32_e32 v80, v88
	v_mov_b32_e32 v81, v78
	v_pk_add_f32 v[40:41], v[80:81], v[40:41]
	v_mov_b32_e32 v78, v89
	v_pk_add_f32 v[40:41], v[78:79], v[40:41]
	ds_swizzle_b32 v79, v41 offset:swizzle(SWAP,1)
	ds_swizzle_b32 v78, v40 offset:swizzle(SWAP,1)
	s_waitcnt lgkmcnt(0)
	v_pk_add_f32 v[40:41], v[40:41], v[78:79]
	ds_swizzle_b32 v79, v41 offset:swizzle(SWAP,2)
	ds_swizzle_b32 v78, v40 offset:swizzle(SWAP,2)
	s_waitcnt lgkmcnt(0)
	v_pk_add_f32 v[40:41], v[40:41], v[78:79]
	ds_swizzle_b32 v79, v41 offset:swizzle(SWAP,4)
	ds_swizzle_b32 v78, v40 offset:swizzle(SWAP,4)
	s_waitcnt lgkmcnt(0)
	v_pk_add_f32 v[78:79], v[40:41], v[78:79]
	v_mov_b64_e32 v[40:41], s[0:1]
	v_pk_fma_f32 v[78:79], v[78:79], s[8:9], v[40:41] op_sel_hi:[1,0,0]
	s_nop 0
	v_mul_f32_e32 v80, 0x4b800000, v79
	v_cmp_gt_f32_e64 s[0:1], s5, v79
	v_cmp_gt_f32_e32 vcc, s5, v78
	s_nop 0
	v_cndmask_b32_e64 v79, v79, v80, s[0:1]
	v_rsq_f32_e32 v79, v79
	s_nop 0
	v_mul_f32_e32 v80, 0x45800000, v79
	v_cndmask_b32_e64 v80, v79, v80, s[0:1]
	v_pk_mul_f32 v[44:45], v[44:45], v[80:81] op_sel_hi:[1,0]
	v_pk_mul_f32 v[46:47], v[46:47], v[80:81] op_sel_hi:[1,0]
	v_pk_mul_f32 v[44:45], v[4:5], v[44:45]
	v_pk_mul_f32 v[46:47], v[0:1], v[46:47]
	v_pk_mul_f32 v[44:45], v[48:49], v[44:45]
	v_pk_mul_f32 v[48:49], v[66:67], v[80:81] op_sel_hi:[1,0]
	v_pk_mul_f32 v[46:47], v[50:51], v[46:47]
	v_pk_mul_f32 v[48:49], v[6:7], v[48:49]
	v_pk_mul_f32 v[50:51], v[62:63], v[80:81] op_sel_hi:[1,0]
	v_pk_mul_f32 v[48:49], v[68:69], v[48:49]
	v_pk_mul_f32 v[50:51], v[2:3], v[50:51]
	v_cvt_pk_bf16_f32 v44, v44, v45
	v_pk_mul_f32 v[50:51], v[72:73], v[50:51]
	v_cvt_pk_bf16_f32 v45, v48, v49
	v_add_co_u32_e64 v48, s[0:1], s6, v74
	v_cvt_pk_bf16_f32 v46, v46, v47
	v_cvt_pk_bf16_f32 v47, v50, v51
	v_addc_co_u32_e64 v49, s[0:1], 0, v75, s[0:1]
	global_store_dwordx4 v[48:49], v[44:47], off offset:1280 sc1
	s_waitcnt vmcnt(1)
	v_lshlrev_b32_e32 v68, 16, v19
	v_and_b32_e32 v69, 0xffff0000, v19
	v_mul_f32_e32 v44, 0x4b800000, v78
	v_cndmask_b32_e32 v44, v78, v44, vcc
	v_rsq_f32_e32 v44, v44
	s_nop 0
	v_mul_f32_e32 v45, 0x45800000, v44
	v_cndmask_b32_e32 v44, v44, v45, vcc
	v_pk_mul_f32 v[34:35], v[34:35], v[44:45] op_sel_hi:[1,0]
	v_pk_mul_f32 v[32:33], v[32:33], v[44:45] op_sel_hi:[1,0]
	v_pk_mul_f32 v[34:35], v[0:1], v[34:35]
	v_pk_mul_f32 v[32:33], v[4:5], v[32:33]
	v_pk_mul_f32 v[34:35], v[38:39], v[34:35]
	v_mul_f32_e32 v38, 0xbfb8aa3b, v82
	v_mul_f32_e32 v39, 0xbfb8aa3b, v83
	v_exp_f32_e32 v38, v38
	v_exp_f32_e32 v39, v39
	v_pk_mul_f32 v[32:33], v[36:37], v[32:33]
	v_pk_mul_f32 v[36:37], v[42:43], v[44:45] op_sel_hi:[1,0]
	v_pk_mul_f32 v[42:43], v[70:71], v[44:45] op_sel_hi:[1,0]
	v_pk_add_f32 v[38:39], v[38:39], 1.0 op_sel_hi:[1,0]
	v_pk_mul_f32 v[36:37], v[6:7], v[36:37]
	v_div_scale_f32 v44, s[0:1], v39, v39, v83
	v_rcp_f32_e32 v45, v44
	v_pk_mul_f32 v[36:37], v[76:77], v[36:37]
	v_cvt_pk_bf16_f32 v32, v32, v33
	v_cvt_pk_bf16_f32 v33, v36, v37
	v_fma_f32 v46, -v44, v45, 1.0
	v_fmac_f32_e32 v45, v46, v45
	v_div_scale_f32 v46, vcc, v83, v39, v83
	v_mul_f32_e32 v47, v46, v45
	v_fma_f32 v48, -v44, v47, v46
	v_fmac_f32_e32 v47, v48, v45
	v_fma_f32 v44, -v44, v47, v46
	v_div_fmas_f32 v44, v44, v45, v47
	v_div_fixup_f32 v39, v44, v39, v83
	v_div_scale_f32 v44, s[0:1], v38, v38, v82
	v_rcp_f32_e32 v45, v44
	v_lshlrev_b64 v[36:37], 11, v[60:61]
	v_lshl_add_u64 v[36:37], s[16:17], 0, v[36:37]
	v_lshl_add_u64 v[36:37], v[36:37], 0, s[2:3]
	v_fma_f32 v46, -v44, v45, 1.0
	v_fmac_f32_e32 v45, v46, v45
	v_div_scale_f32 v46, vcc, v82, v38, v82
	v_mul_f32_e32 v47, v46, v45
	v_fma_f32 v48, -v44, v47, v46
	v_fmac_f32_e32 v47, v48, v45
	v_fma_f32 v44, -v44, v47, v46
	v_div_fmas_f32 v44, v44, v45, v47
	v_pk_mul_f32 v[42:43], v[2:3], v[42:43]
	v_div_fixup_f32 v38, v44, v38, v82
	v_lshl_add_u64 v[36:37], v[36:37], 0, v[64:65]
	v_pk_mul_f32 v[38:39], v[38:39], v[42:43]
	v_add_co_u32_e32 v36, vcc, s6, v36
	v_cvt_pk_bf16_f32 v34, v34, v35
	v_cvt_pk_bf16_f32 v35, v38, v39
	v_addc_co_u32_e32 v37, vcc, 0, v37, vcc
	v_lshlrev_b32_e32 v38, 16, v30
	v_and_b32_e32 v39, 0xffff0000, v30
	global_store_dwordx4 v[36:37], v[32:35], off offset:1280 sc1
	v_lshlrev_b32_e32 v36, 16, v22
	v_and_b32_e32 v37, 0xffff0000, v22
	v_lshlrev_b32_e32 v32, 16, v23
	v_and_b32_e32 v33, 0xffff0000, v23
	v_lshlrev_b32_e32 v34, 16, v27
	v_and_b32_e32 v35, 0xffff0000, v27
	v_lshlrev_b32_e32 v22, 16, v26
	v_and_b32_e32 v23, 0xffff0000, v26
	v_mul_f32_e32 v26, 0xbfb8aa3b, v38
	v_mul_f32_e32 v27, 0xbfb8aa3b, v39
	v_exp_f32_e32 v26, v26
	v_exp_f32_e32 v27, v27
	v_pk_add_f32 v[22:23], v[36:37], v[22:23]
	v_lshlrev_b32_e32 v46, 16, v31
	v_and_b32_e32 v47, 0xffff0000, v31
	v_pk_add_f32 v[26:27], v[26:27], 1.0 op_sel_hi:[1,0]
	v_and_b32_e32 v61, 0xffff0000, v18
	v_div_scale_f32 v36, s[0:1], v27, v27, v39
	v_rcp_f32_e32 v37, v36
	v_mul_f32_e32 v19, 0xbfb8aa3b, v61
	v_exp_f32_e32 v19, v19
	v_pk_mul_f32 v[30:31], v[22:23], v[22:23]
	v_fma_f32 v42, -v36, v37, 1.0
	v_fmac_f32_e32 v37, v42, v37
	v_div_scale_f32 v42, vcc, v39, v27, v39
	v_mul_f32_e32 v43, v42, v37
	v_fma_f32 v44, -v36, v43, v42
	v_fmac_f32_e32 v43, v44, v37
	v_fma_f32 v36, -v36, v43, v42
	v_div_fmas_f32 v36, v36, v37, v43
	v_div_fixup_f32 v27, v36, v27, v39
	v_div_scale_f32 v36, s[0:1], v26, v26, v38
	v_rcp_f32_e32 v37, v36
	v_pk_add_f32 v[32:33], v[32:33], v[34:35]
	v_fma_f32 v39, -v36, v37, 1.0
	v_fmac_f32_e32 v37, v39, v37
	v_div_scale_f32 v39, vcc, v38, v26, v38
	v_mul_f32_e32 v42, v39, v37
	v_fma_f32 v43, -v36, v42, v39
	v_fmac_f32_e32 v42, v43, v37
	v_fma_f32 v36, -v36, v42, v39
	v_div_fmas_f32 v36, v36, v37, v42
	v_div_fixup_f32 v26, v36, v26, v38
	v_lshlrev_b32_e32 v36, 16, v21
	v_and_b32_e32 v37, 0xffff0000, v21
	v_lshlrev_b32_e32 v21, 16, v29
	v_lshlrev_b32_e32 v38, 16, v25
	v_and_b32_e32 v39, 0xffff0000, v25
	v_and_b32_e32 v25, 0xffff0000, v29
	v_mul_f32_e32 v29, 0xbfb8aa3b, v21
	v_exp_f32_e32 v42, v29
	v_mul_f32_e32 v29, 0xbfb8aa3b, v25
	v_exp_f32_e32 v43, v29
	v_pk_add_f32 v[36:37], v[36:37], v[38:39]
	v_pk_mul_f32 v[34:35], v[32:33], v[32:33]
	v_pk_mul_f32 v[38:39], v[36:37], v[36:37]
	v_pk_add_f32 v[42:43], v[42:43], 1.0 op_sel_hi:[1,0]
	s_nop 0
	v_div_scale_f32 v29, s[0:1], v43, v43, v25
	v_rcp_f32_e32 v44, v29
	s_nop 0
	v_fma_f32 v45, -v29, v44, 1.0
	v_fmac_f32_e32 v44, v45, v44
	v_div_scale_f32 v45, vcc, v25, v43, v25
	v_mul_f32_e32 v48, v45, v44
	v_fma_f32 v49, -v29, v48, v45
	v_fmac_f32_e32 v48, v49, v44
	v_fma_f32 v29, -v29, v48, v45
	v_div_fmas_f32 v29, v29, v44, v48
	v_div_fixup_f32 v43, v29, v43, v25
	v_div_scale_f32 v25, s[0:1], v42, v42, v21
	v_rcp_f32_e32 v29, v25
	v_and_b32_e32 v49, 0xffff0000, v28
	v_fma_f32 v44, -v25, v29, 1.0
	v_fmac_f32_e32 v29, v44, v29
	v_div_scale_f32 v44, vcc, v21, v42, v21
	v_mul_f32_e32 v45, v44, v29
	v_fma_f32 v48, -v25, v45, v44
	v_fmac_f32_e32 v45, v48, v29
	v_fma_f32 v25, -v25, v45, v44
	v_lshlrev_b32_e32 v48, 16, v28
	v_div_fmas_f32 v25, v25, v29, v45
	v_mul_f32_e32 v28, 0xbfb8aa3b, v48
	v_mul_f32_e32 v29, 0xbfb8aa3b, v49
	v_exp_f32_e32 v28, v28
	v_exp_f32_e32 v29, v29
	v_div_fixup_f32 v42, v25, v42, v21
	v_lshlrev_b32_e32 v44, 16, v20
	v_and_b32_e32 v45, 0xffff0000, v20
	v_lshlrev_b32_e32 v20, 16, v24
	v_and_b32_e32 v21, 0xffff0000, v24
	v_pk_add_f32 v[28:29], v[28:29], 1.0 op_sel_hi:[1,0]
	v_pk_add_f32 v[20:21], v[44:45], v[20:21]
	v_div_scale_f32 v44, s[0:1], v29, v29, v49
	v_rcp_f32_e32 v45, v44
	v_pk_mul_f32 v[24:25], v[20:21], v[20:21]
	v_fma_f32 v50, -v44, v45, 1.0
	v_fmac_f32_e32 v45, v50, v45
	v_div_scale_f32 v50, vcc, v49, v29, v49
	v_mul_f32_e32 v51, v50, v45
	v_fma_f32 v60, -v44, v51, v50
	v_fmac_f32_e32 v51, v60, v45
	v_fma_f32 v44, -v44, v51, v50
	v_div_fmas_f32 v44, v44, v45, v51
	v_div_fixup_f32 v29, v44, v29, v49
	v_div_scale_f32 v44, s[0:1], v28, v28, v48
	v_rcp_f32_e32 v45, v44
	s_nop 0
	v_fma_f32 v49, -v44, v45, 1.0
	v_fmac_f32_e32 v45, v49, v45
	v_div_scale_f32 v49, vcc, v48, v28, v48
	v_mul_f32_e32 v50, v49, v45
	v_fma_f32 v51, -v44, v50, v49
	v_fmac_f32_e32 v50, v51, v45
	v_fma_f32 v44, -v44, v50, v49
	v_div_fmas_f32 v44, v44, v45, v50
	v_div_fixup_f32 v28, v44, v28, v48
	v_mul_f32_e32 v44, 0xbfb8aa3b, v46
	v_mul_f32_e32 v45, 0xbfb8aa3b, v47
	v_exp_f32_e32 v44, v44
	v_exp_f32_e32 v45, v45
	s_nop 0
	v_pk_add_f32 v[44:45], v[44:45], 1.0 op_sel_hi:[1,0]
	s_nop 0
	v_div_scale_f32 v48, s[0:1], v45, v45, v47
	v_rcp_f32_e32 v49, v48
	s_nop 0
	v_fma_f32 v50, -v48, v49, 1.0
	v_fmac_f32_e32 v49, v50, v49
	v_div_scale_f32 v50, vcc, v47, v45, v47
	v_mul_f32_e32 v51, v50, v49
	v_fma_f32 v60, -v48, v51, v50
	v_fmac_f32_e32 v51, v60, v49
	v_fma_f32 v48, -v48, v51, v50
	v_div_fmas_f32 v48, v48, v49, v51
	v_div_fixup_f32 v45, v48, v45, v47
	v_div_scale_f32 v47, s[0:1], v44, v44, v46
	v_rcp_f32_e32 v48, v47
	v_lshlrev_b32_e32 v60, 16, v18
	v_mul_f32_e32 v18, 0xbfb8aa3b, v60
	v_exp_f32_e32 v18, v18
	v_fma_f32 v49, -v47, v48, 1.0
	v_fmac_f32_e32 v48, v49, v48
	v_div_scale_f32 v49, vcc, v46, v44, v46
	v_mul_f32_e32 v50, v49, v48
	v_fma_f32 v51, -v47, v50, v49
	v_fmac_f32_e32 v50, v51, v48
	v_fma_f32 v47, -v47, v50, v49
	v_div_fmas_f32 v47, v47, v48, v50
	v_div_fixup_f32 v44, v47, v44, v46
	v_lshlrev_b64 v[46:47], 11, v[58:59]
	v_lshlrev_b32_e32 v48, 16, v11
	v_and_b32_e32 v49, 0xffff0000, v11
	v_lshlrev_b32_e32 v58, 16, v10
	v_and_b32_e32 v59, 0xffff0000, v10
	v_lshlrev_b32_e32 v10, 16, v14
	v_and_b32_e32 v11, 0xffff0000, v14
	v_pk_add_f32 v[18:19], v[18:19], 1.0 op_sel_hi:[1,0]
	v_lshlrev_b32_e32 v50, 16, v15
	v_and_b32_e32 v51, 0xffff0000, v15
	v_pk_add_f32 v[14:15], v[58:59], v[10:11]
	v_div_scale_f32 v58, s[0:1], v19, v19, v61
	v_rcp_f32_e32 v59, v58
	v_pk_mul_f32 v[10:11], v[14:15], v[14:15]
	v_pk_add_f32 v[48:49], v[48:49], v[50:51]
	v_lshl_add_u64 v[46:47], s[16:17], 0, v[46:47]
	v_fma_f32 v62, -v58, v59, 1.0
	v_fmac_f32_e32 v59, v62, v59
	v_div_scale_f32 v62, vcc, v61, v19, v61
	v_mul_f32_e32 v63, v62, v59
	v_fma_f32 v66, -v58, v63, v62
	v_fmac_f32_e32 v63, v66, v59
	v_fma_f32 v58, -v58, v63, v62
	v_div_fmas_f32 v58, v58, v59, v63
	v_div_fixup_f32 v19, v58, v19, v61
	v_div_scale_f32 v58, s[0:1], v18, v18, v60
	v_rcp_f32_e32 v59, v58
	v_pk_mul_f32 v[50:51], v[48:49], v[48:49]
	v_lshl_add_u64 v[46:47], v[46:47], 0, s[2:3]
	v_lshl_add_u64 v[46:47], v[46:47], 0, v[64:65]
	v_fma_f32 v61, -v58, v59, 1.0
	v_fmac_f32_e32 v59, v61, v59
	v_div_scale_f32 v61, vcc, v60, v18, v60
	v_mul_f32_e32 v62, v61, v59
	v_fma_f32 v63, -v58, v62, v61
	v_fmac_f32_e32 v62, v63, v59
	v_fma_f32 v58, -v58, v62, v61
	v_div_fmas_f32 v58, v58, v59, v62
	v_div_fixup_f32 v18, v58, v18, v60
	v_lshlrev_b32_e32 v58, 16, v9
	v_and_b32_e32 v59, 0xffff0000, v9
	v_lshlrev_b32_e32 v9, 16, v17
	v_lshlrev_b32_e32 v60, 16, v13
	v_and_b32_e32 v61, 0xffff0000, v13
	v_and_b32_e32 v13, 0xffff0000, v17
	v_mul_f32_e32 v17, 0xbfb8aa3b, v9
	v_exp_f32_e32 v62, v17
	v_mul_f32_e32 v17, 0xbfb8aa3b, v13
	v_exp_f32_e32 v63, v17
	v_pk_add_f32 v[58:59], v[58:59], v[60:61]
	v_pk_add_f32 v[62:63], v[62:63], 1.0 op_sel_hi:[1,0]
	s_nop 0
	v_div_scale_f32 v17, s[0:1], v63, v63, v13
	v_rcp_f32_e32 v66, v17
	v_pk_mul_f32 v[60:61], v[58:59], v[58:59]
	v_fma_f32 v67, -v17, v66, 1.0
	v_fmac_f32_e32 v66, v67, v66
	v_div_scale_f32 v67, vcc, v13, v63, v13
	v_mul_f32_e32 v70, v67, v66
	v_fma_f32 v71, -v17, v70, v67
	v_fmac_f32_e32 v70, v71, v66
	v_fma_f32 v17, -v17, v70, v67
	v_div_fmas_f32 v17, v17, v66, v70
	v_div_fixup_f32 v63, v17, v63, v13
	v_div_scale_f32 v13, s[0:1], v62, v62, v9
	v_rcp_f32_e32 v17, v13
	v_and_b32_e32 v71, 0xffff0000, v16
	v_fma_f32 v66, -v13, v17, 1.0
	v_fmac_f32_e32 v17, v66, v17
	v_div_scale_f32 v66, vcc, v9, v62, v9
	v_mul_f32_e32 v67, v66, v17
	v_fma_f32 v70, -v13, v67, v66
	v_fmac_f32_e32 v67, v70, v17
	v_fma_f32 v13, -v13, v67, v66
	v_div_fmas_f32 v13, v13, v17, v67
	v_div_fixup_f32 v62, v13, v62, v9
	v_lshlrev_b32_e32 v66, 16, v8
	v_and_b32_e32 v67, 0xffff0000, v8
	v_lshlrev_b32_e32 v8, 16, v12
	v_and_b32_e32 v9, 0xffff0000, v12
	v_pk_add_f32 v[12:13], v[66:67], v[8:9]
	v_lshlrev_b32_e32 v70, 16, v16
	v_pk_mul_f32 v[8:9], v[12:13], v[12:13]
	v_mov_b32_e32 v17, v24
	v_mov_b32_e32 v16, v8
	v_mov_b32_e32 v24, v9
	v_pk_add_f32 v[8:9], v[16:17], v[24:25]
	v_mul_f32_e32 v16, 0xbfb8aa3b, v70
	v_mul_f32_e32 v17, 0xbfb8aa3b, v71
	v_exp_f32_e32 v16, v16
	v_exp_f32_e32 v17, v17
	s_nop 0
	v_pk_add_f32 v[16:17], v[16:17], 1.0 op_sel_hi:[1,0]
	s_nop 0
	v_div_scale_f32 v24, s[0:1], v17, v17, v71
	v_rcp_f32_e32 v25, v24
	s_nop 0
	v_fma_f32 v66, -v24, v25, 1.0
	v_fmac_f32_e32 v25, v66, v25
	v_div_scale_f32 v66, vcc, v71, v17, v71
	v_mul_f32_e32 v67, v66, v25
	v_fma_f32 v72, -v24, v67, v66
	v_fmac_f32_e32 v67, v72, v25
	v_fma_f32 v24, -v24, v67, v66
	v_div_fmas_f32 v24, v24, v25, v67
	v_div_fixup_f32 v17, v24, v17, v71
	v_div_scale_f32 v24, s[0:1], v16, v16, v70
	v_rcp_f32_e32 v25, v24
	s_nop 0
	v_fma_f32 v66, -v24, v25, 1.0
	v_fmac_f32_e32 v25, v66, v25
	v_div_scale_f32 v66, vcc, v70, v16, v70
	v_mul_f32_e32 v67, v66, v25
	v_fma_f32 v71, -v24, v67, v66
	v_fmac_f32_e32 v67, v71, v25
	v_fma_f32 v24, -v24, v67, v66
	v_div_fmas_f32 v24, v24, v25, v67
	v_div_fixup_f32 v16, v24, v16, v70
	v_mov_b32_e32 v24, v60
	v_mov_b32_e32 v25, v38
	v_pk_add_f32 v[8:9], v[24:25], v[8:9]
	v_mov_b32_e32 v38, v61
	v_pk_add_f32 v[8:9], v[38:39], v[8:9]
	v_mov_b32_e32 v24, v10
	v_mov_b32_e32 v25, v30
	v_pk_add_f32 v[8:9], v[24:25], v[8:9]
	v_mov_b32_e32 v30, v11
	v_pk_add_f32 v[8:9], v[30:31], v[8:9]
	v_mov_b32_e32 v10, v50
	v_mov_b32_e32 v11, v34
	v_pk_add_f32 v[8:9], v[10:11], v[8:9]
	v_mov_b32_e32 v34, v51
	v_pk_add_f32 v[8:9], v[34:35], v[8:9]
	ds_swizzle_b32 v11, v9 offset:swizzle(SWAP,1)
	ds_swizzle_b32 v10, v8 offset:swizzle(SWAP,1)
	s_waitcnt lgkmcnt(0)
	v_pk_add_f32 v[8:9], v[8:9], v[10:11]
	ds_swizzle_b32 v11, v9 offset:swizzle(SWAP,2)
	ds_swizzle_b32 v10, v8 offset:swizzle(SWAP,2)
	s_waitcnt lgkmcnt(0)
	v_pk_add_f32 v[8:9], v[8:9], v[10:11]
	ds_swizzle_b32 v11, v9 offset:swizzle(SWAP,4)
	ds_swizzle_b32 v10, v8 offset:swizzle(SWAP,4)
	s_waitcnt lgkmcnt(0)
	v_pk_add_f32 v[8:9], v[8:9], v[10:11]
	s_nop 0
	v_pk_fma_f32 v[24:25], v[8:9], s[8:9], v[40:41] op_sel_hi:[1,0,0]
	s_nop 0
	v_mul_f32_e32 v8, 0x4b800000, v25
	v_cmp_gt_f32_e64 s[0:1], s5, v25
	v_cmp_gt_f32_e32 vcc, s5, v24
	s_nop 0
	v_cndmask_b32_e64 v8, v25, v8, s[0:1]
	v_rsq_f32_e32 v8, v8
	s_nop 0
	v_mul_f32_e32 v9, 0x45800000, v8
	v_cndmask_b32_e64 v8, v8, v9, s[0:1]
	v_pk_mul_f32 v[10:11], v[20:21], v[8:9] op_sel_hi:[1,0]
	v_pk_mul_f32 v[20:21], v[36:37], v[8:9] op_sel_hi:[1,0]
	v_pk_mul_f32 v[22:23], v[22:23], v[8:9] op_sel_hi:[1,0]
	v_pk_mul_f32 v[20:21], v[6:7], v[20:21]
	v_pk_mul_f32 v[8:9], v[32:33], v[8:9] op_sel_hi:[1,0]
	v_pk_mul_f32 v[10:11], v[4:5], v[10:11]
	v_pk_mul_f32 v[20:21], v[42:43], v[20:21]
	v_pk_mul_f32 v[22:23], v[0:1], v[22:23]
	v_pk_mul_f32 v[8:9], v[2:3], v[8:9]
	v_pk_mul_f32 v[10:11], v[28:29], v[10:11]
	v_pk_mul_f32 v[22:23], v[26:27], v[22:23]
	v_pk_mul_f32 v[26:27], v[44:45], v[8:9]
	v_cvt_pk_bf16_f32 v9, v20, v21
	v_add_co_u32_e64 v20, s[0:1], s6, v46
	v_cvt_pk_bf16_f32 v8, v10, v11
	v_cvt_pk_bf16_f32 v10, v22, v23
	v_cvt_pk_bf16_f32 v11, v26, v27
	v_addc_co_u32_e64 v21, s[0:1], 0, v47, s[0:1]
	global_store_dwordx4 v[20:21], v[8:11], off offset:1280 sc1
	s_nop 1
	v_mul_f32_e32 v8, 0x4b800000, v24
	v_cndmask_b32_e32 v8, v24, v8, vcc
	v_rsq_f32_e32 v8, v8
	s_nop 0
	v_mul_f32_e32 v9, 0x45800000, v8
	v_cndmask_b32_e32 v8, v8, v9, vcc
	v_pk_mul_f32 v[10:11], v[12:13], v[8:9] op_sel_hi:[1,0]
	v_pk_mul_f32 v[12:13], v[58:59], v[8:9] op_sel_hi:[1,0]
	v_pk_mul_f32 v[10:11], v[4:5], v[10:11]
	v_pk_mul_f32 v[14:15], v[14:15], v[8:9] op_sel_hi:[1,0]
	v_pk_mul_f32 v[10:11], v[16:17], v[10:11]
	v_mul_f32_e32 v9, 0xbfb8aa3b, v68
	v_mul_f32_e32 v17, 0xbfb8aa3b, v69
	v_exp_f32_e32 v16, v9
	v_exp_f32_e32 v17, v17
	v_pk_mul_f32 v[14:15], v[0:1], v[14:15]
	v_pk_mul_f32 v[12:13], v[6:7], v[12:13]
	v_pk_mul_f32 v[14:15], v[18:19], v[14:15]
	v_pk_add_f32 v[16:17], v[16:17], 1.0 op_sel_hi:[1,0]
	v_pk_mul_f32 v[8:9], v[48:49], v[8:9] op_sel_hi:[1,0]
	v_div_scale_f32 v18, s[0:1], v17, v17, v69
	v_rcp_f32_e32 v19, v18
	v_pk_mul_f32 v[12:13], v[62:63], v[12:13]
	v_pk_mul_f32 v[8:9], v[2:3], v[8:9]
	v_fma_f32 v20, -v18, v19, 1.0
	v_fmac_f32_e32 v19, v20, v19
	v_div_scale_f32 v20, vcc, v69, v17, v69
	v_mul_f32_e32 v21, v20, v19
	v_fma_f32 v22, -v18, v21, v20
	v_fmac_f32_e32 v21, v22, v19
	v_fma_f32 v18, -v18, v21, v20
	v_div_fmas_f32 v18, v18, v19, v21
	v_div_fixup_f32 v17, v18, v17, v69
	v_div_scale_f32 v18, s[0:1], v16, v16, v68
	v_rcp_f32_e32 v19, v18
	s_movk_i32 s0, 0x100
	v_fma_f32 v20, -v18, v19, 1.0
	v_fmac_f32_e32 v19, v20, v19
	v_div_scale_f32 v20, vcc, v68, v16, v68
	v_mul_f32_e32 v21, v20, v19
	v_fma_f32 v22, -v18, v21, v20
	v_fmac_f32_e32 v21, v22, v19
	v_fma_f32 v18, -v18, v21, v20
	v_div_fmas_f32 v18, v18, v19, v21
	v_div_fixup_f32 v16, v18, v16, v68
	v_pk_mul_f32 v[16:17], v[16:17], v[8:9]
	v_cvt_pk_bf16_f32 v9, v12, v13
	v_lshlrev_b64 v[12:13], 11, v[56:57]
	v_lshl_add_u64 v[12:13], s[16:17], 0, v[12:13]
	v_lshl_add_u64 v[12:13], v[12:13], 0, s[2:3]
	v_lshl_add_u64 v[12:13], v[12:13], 0, v[64:65]
	v_add_co_u32_e32 v12, vcc, 0x2000000, v12
	v_cvt_pk_bf16_f32 v8, v10, v11
	s_nop 0
	v_addc_co_u32_e32 v13, vcc, 0, v13, vcc
	v_cvt_pk_bf16_f32 v10, v14, v15
	v_cvt_pk_bf16_f32 v11, v16, v17
	s_and_b64 vcc, exec, s[22:23]
	s_mov_b64 s[22:23], 0
	global_store_dwordx4 v[12:13], v[8:11], off offset:1280 sc1
	s_cbranch_vccnz .LBB0_229
	s_and_saveexec_b64 s[0:1], s[44:45]
	s_cbranch_execz .LBB0_147
	s_mov_b64 s[22:23], exec
	v_mbcnt_lo_u32_b32 v0, s22, 0
	v_mbcnt_hi_u32_b32 v0, s23, v0
	v_cmp_eq_u32_e32 vcc, 0, v0
	s_and_saveexec_b64 s[2:3], vcc
	s_cbranch_execz .LBB0_146
	s_bcnt1_i32_b64 s4, s[22:23]
	v_mov_b32_e32 v1, s4
	global_atomic_add v1, v65, v1, s[76:77] sc0
	s_branch .LBB0_146

.LBB0_248:
	v_add_u32_e32 v58, v68, v69
	s_waitcnt vmcnt(0)
	ds_write2_b32 v58, v4, v5 offset1:1
	ds_write2_b32 v58, v6, v7 offset0:2 offset1:3
	v_add_u32_e32 v4, 0x420, v58
	ds_write2_b32 v4, v0, v1 offset1:1
	v_add_u32_e32 v0, 0x428, v58
	ds_write2_b32 v0, v2, v3 offset1:1
	v_add_u32_e32 v0, 0x840, v58
	ds_write2_b32 v0, v12, v13 offset1:1
	v_add_u32_e32 v0, 0x848, v58
	ds_write2_b32 v0, v14, v15 offset1:1
	v_add_u32_e32 v0, 0xc60, v58
	ds_write2_b32 v0, v8, v9 offset1:1
	v_add_u32_e32 v0, 0xc68, v58
	ds_write2_b32 v0, v10, v11 offset1:1
	v_add_u32_e32 v0, 0x1080, v58
	ds_write2_b32 v0, v20, v21 offset1:1
	v_add_u32_e32 v0, 0x1088, v58
	ds_write2_b32 v0, v22, v23 offset1:1
	v_add_u32_e32 v0, 0x14a0, v58
	ds_write2_b32 v0, v16, v17 offset1:1
	v_add_u32_e32 v0, 0x14a8, v58
	ds_write2_b32 v0, v18, v19 offset1:1
	v_add_u32_e32 v0, 0x18c0, v58
	ds_write2_b32 v0, v28, v29 offset1:1
	v_add_u32_e32 v0, 0x18c8, v58
	ds_write2_b32 v0, v30, v31 offset1:1
	v_add_u32_e32 v0, 0x1ce0, v58
	ds_write2_b32 v0, v24, v25 offset1:1
	v_add_u32_e32 v0, 0x1ce8, v58
	ds_write2_b32 v0, v26, v27 offset1:1
	s_waitcnt lgkmcnt(0)
	ds_read2_b32 v[4:5], v71 offset0:33 offset1:41
	ds_read2_b32 v[6:7], v71 offset1:8
	ds_read2_b32 v[8:9], v71 offset0:66 offset1:74
	ds_read2_b32 v[10:11], v71 offset0:99 offset1:107
	ds_read2_b32 v[12:13], v71 offset0:132 offset1:140
	ds_read2_b32 v[14:15], v71 offset0:165 offset1:173
	ds_read2_b32 v[16:17], v71 offset0:198 offset1:206
	ds_read2_b32 v[18:19], v71 offset0:231 offset1:239
	v_add_u32_e32 v22, s4, v32
	s_ashr_i32 s29, s28, 31
	v_ashrrev_i32_e32 v23, 31, v22
	v_lshl_add_u64 v[20:21], s[28:29], 1, v[56:57]
	v_lshlrev_b64 v[22:23], 11, v[22:23]
	s_waitcnt lgkmcnt(6)
	v_cvt_pk_bf16_f32 v0, v6, v4
	s_waitcnt lgkmcnt(4)
	v_cvt_pk_bf16_f32 v1, v8, v10
	s_waitcnt lgkmcnt(2)
	v_cvt_pk_bf16_f32 v2, v12, v14
	s_waitcnt lgkmcnt(0)
	v_cvt_pk_bf16_f32 v3, v16, v18
	v_lshl_add_u64 v[22:23], v[20:21], 0, v[22:23]
	v_add_u32_e32 v4, s4, v34
	global_store_dwordx4 v[22:23], v[0:3], off sc1
	s_nop 1
	v_cvt_pk_bf16_f32 v0, v7, v5
	v_ashrrev_i32_e32 v5, 31, v4
	v_cvt_pk_bf16_f32 v1, v9, v11
	v_cvt_pk_bf16_f32 v2, v13, v15
	v_cvt_pk_bf16_f32 v3, v17, v19
	v_lshlrev_b64 v[4:5], 11, v[4:5]
	ds_read2_b32 v[6:7], v71 offset0:16 offset1:24
	ds_read2_b32 v[8:9], v71 offset0:49 offset1:57
	ds_read2_b32 v[10:11], v71 offset0:82 offset1:90
	ds_read2_b32 v[12:13], v71 offset0:115 offset1:123
	ds_read2_b32 v[14:15], v71 offset0:148 offset1:156
	ds_read2_b32 v[16:17], v71 offset0:181 offset1:189
	ds_read2_b32 v[18:19], v71 offset0:214 offset1:222
	ds_read2_b32 v[22:23], v71 offset0:247 offset1:255
	v_lshl_add_u64 v[4:5], v[20:21], 0, v[4:5]
	global_store_dwordx4 v[4:5], v[0:3], off sc1
	v_add_u32_e32 v4, s4, v36
	v_ashrrev_i32_e32 v5, 31, v4
	v_lshlrev_b64 v[4:5], 11, v[4:5]
	s_waitcnt lgkmcnt(6)
	v_cvt_pk_bf16_f32 v0, v6, v8
	s_waitcnt lgkmcnt(4)
	v_cvt_pk_bf16_f32 v1, v10, v12
	s_waitcnt lgkmcnt(2)
	v_cvt_pk_bf16_f32 v2, v14, v16
	s_waitcnt lgkmcnt(0)
	v_cvt_pk_bf16_f32 v3, v18, v22
	v_lshl_add_u64 v[4:5], v[20:21], 0, v[4:5]
	global_store_dwordx4 v[4:5], v[0:3], off sc1
	v_add_u32_e32 v4, s4, v38
	v_ashrrev_i32_e32 v5, 31, v4
	v_lshlrev_b64 v[4:5], 11, v[4:5]
	v_cvt_pk_bf16_f32 v0, v7, v9
	v_cvt_pk_bf16_f32 v1, v11, v13
	v_cvt_pk_bf16_f32 v2, v15, v17
	v_cvt_pk_bf16_f32 v3, v19, v23
	v_lshl_add_u64 v[4:5], v[20:21], 0, v[4:5]
	global_store_dwordx4 v[4:5], v[0:3], off sc1
	s_waitcnt lgkmcnt(0)

.LBB0_276:
	v_mov_b32_e32 v61, v0
	v_pk_mul_f32 v[4:5], v[28:29], v[60:61] op_sel_hi:[1,0]
	v_add_u32_e32 v3, 0x1080, v2
	v_pk_mul_f32 v[0:1], v[30:31], v[60:61] op_sel_hi:[1,0]
	ds_write2_b32 v3, v4, v5 offset1:1
	v_add_u32_e32 v3, 0x1088, v2
	ds_write2_b32 v3, v0, v1 offset1:1
	v_pk_mul_f32 v[0:1], v[16:17], v[60:61] op_sel:[0,1]
	v_add_u32_e32 v3, 0x14a0, v2
	ds_write2_b32 v3, v0, v1 offset1:1
	v_pk_mul_f32 v[0:1], v[18:19], v[60:61] op_sel:[0,1]
	v_add_u32_e32 v2, 0x14a8, v2
	ds_write2_b32 v2, v0, v1 offset1:1
	s_waitcnt lgkmcnt(0)
	ds_read2_b32 v[6:7], v71 offset0:33 offset1:41
	ds_read2_b32 v[8:9], v71 offset1:8
	ds_read2_b32 v[10:11], v71 offset0:66 offset1:74
	ds_read2_b32 v[12:13], v71 offset0:99 offset1:107
	ds_read2_b32 v[14:15], v71 offset0:132 offset1:140
	ds_read2_b32 v[16:17], v71 offset0:165 offset1:173
	ds_read2_b32 v[18:19], v71 offset0:198 offset1:206
	ds_read2_b32 v[20:21], v71 offset0:231 offset1:239
	v_add_u32_e32 v22, s5, v32
	v_ashrrev_i32_e32 v23, 31, v22
	v_lshl_add_u64 v[4:5], s[34:35], 1, v[48:49]
	v_lshlrev_b64 v[22:23], 11, v[22:23]
	s_waitcnt lgkmcnt(6)
	v_cvt_pk_bf16_f32 v0, v8, v6
	s_waitcnt lgkmcnt(4)
	v_cvt_pk_bf16_f32 v1, v10, v12
	s_waitcnt lgkmcnt(2)
	v_cvt_pk_bf16_f32 v2, v14, v16
	s_waitcnt lgkmcnt(0)
	v_cvt_pk_bf16_f32 v3, v18, v20
	v_lshl_add_u64 v[22:23], v[4:5], 0, v[22:23]
	v_add_u32_e32 v6, s5, v34
	global_store_dwordx4 v[22:23], v[0:3], off sc1
	v_add_u32_e32 v22, s5, v36
	v_ashrrev_i32_e32 v23, 31, v22
	v_cvt_pk_bf16_f32 v0, v9, v7
	v_ashrrev_i32_e32 v7, 31, v6
	v_lshlrev_b64 v[6:7], 11, v[6:7]
	v_cvt_pk_bf16_f32 v1, v11, v13
	v_cvt_pk_bf16_f32 v2, v15, v17
	v_cvt_pk_bf16_f32 v3, v19, v21
	v_lshl_add_u64 v[6:7], v[4:5], 0, v[6:7]
	global_store_dwordx4 v[6:7], v[0:3], off sc1
	ds_read2_b32 v[6:7], v71 offset0:16 offset1:24
	ds_read2_b32 v[8:9], v71 offset0:49 offset1:57
	ds_read2_b32 v[10:11], v71 offset0:82 offset1:90
	ds_read2_b32 v[12:13], v71 offset0:115 offset1:123
	ds_read2_b32 v[14:15], v71 offset0:148 offset1:156
	ds_read2_b32 v[16:17], v71 offset0:181 offset1:189
	ds_read2_b32 v[18:19], v71 offset0:214 offset1:222
	ds_read2_b32 v[20:21], v71 offset0:247 offset1:255
	v_lshlrev_b64 v[22:23], 11, v[22:23]
	s_waitcnt lgkmcnt(6)
	v_cvt_pk_bf16_f32 v0, v6, v8
	s_waitcnt lgkmcnt(4)
	v_cvt_pk_bf16_f32 v1, v10, v12
	s_waitcnt lgkmcnt(2)
	v_cvt_pk_bf16_f32 v2, v14, v16
	s_waitcnt lgkmcnt(0)
	v_cvt_pk_bf16_f32 v3, v18, v20
	v_lshl_add_u64 v[22:23], v[4:5], 0, v[22:23]
	v_add_u32_e32 v6, s5, v38
	global_store_dwordx4 v[22:23], v[0:3], off sc1
	s_mov_b64 s[0:1], 0
	s_nop 0
	v_cvt_pk_bf16_f32 v0, v7, v9
	v_ashrrev_i32_e32 v7, 31, v6
	v_lshlrev_b64 v[6:7], 11, v[6:7]
	v_cvt_pk_bf16_f32 v1, v11, v13
	v_cvt_pk_bf16_f32 v2, v15, v17
	v_cvt_pk_bf16_f32 v3, v19, v21
	v_lshl_add_u64 v[4:5], v[4:5], 0, v[6:7]
	global_store_dwordx4 v[4:5], v[0:3], off sc1
	s_waitcnt lgkmcnt(0)

.LBB0_298:
	s_cmpk_gt_i32 s36, 0x1ff
	s_mov_b64 s[0:1], -1
	s_cbranch_scc0 .LBB0_312
	s_lshl_b32 s4, s36, 5
	s_cmpk_gt_u32 s36, 0x9ff
	s_cbranch_scc0 .LBB0_301
	s_lshl_b32 s0, s36, 1
	s_and_b32 s0, s0, 0x7fffffc0
	s_add_i32 s34, s0, 0xffffec00
	s_and_b32 s0, s4, 0x3e0
	v_or_b32_e32 v1, s0, v67
	v_add_u32_e32 v0, s34, v32
	v_lshlrev_b32_e32 v64, 2, v1
	v_ashrrev_i32_e32 v1, 31, v0
	v_lshl_add_u64 v[2:3], s[46:47], 0, v[64:65]
	v_lshlrev_b64 v[0:1], 12, v[0:1]
	v_lshl_add_u64 v[28:29], v[2:3], 0, v[0:1]
	s_mov_b32 s1, 0x8000
	v_add_co_u32_e32 v4, vcc, s1, v28
	global_load_dwordx4 v[0:3], v[28:29], off
	s_nop 0
	v_addc_co_u32_e32 v5, vcc, 0, v29, vcc
	s_mov_b32 s1, 0x10000
	global_load_dwordx4 v[4:7], v[4:5], off
	v_add_co_u32_e32 v8, vcc, s1, v28
	s_mov_b32 s1, 0x18000
	s_nop 0
	v_addc_co_u32_e32 v9, vcc, 0, v29, vcc
	global_load_dwordx4 v[8:11], v[8:9], off
	v_add_co_u32_e32 v12, vcc, s1, v28
	s_mov_b32 s1, 0x20000
	s_nop 0
	v_addc_co_u32_e32 v13, vcc, 0, v29, vcc
	global_load_dwordx4 v[12:15], v[12:13], off
	v_add_co_u32_e32 v16, vcc, s1, v28
	s_mov_b32 s1, 0x28000
	s_nop 0
	v_addc_co_u32_e32 v17, vcc, 0, v29, vcc
	global_load_dwordx4 v[16:19], v[16:17], off
	v_add_co_u32_e32 v20, vcc, s1, v28
	s_mov_b32 s1, 0x30000
	s_nop 0
	v_addc_co_u32_e32 v21, vcc, 0, v29, vcc
	global_load_dwordx4 v[20:23], v[20:21], off
	v_add_co_u32_e32 v24, vcc, s1, v28
	s_mov_b32 s1, 0x38000
	s_nop 0
	v_addc_co_u32_e32 v25, vcc, 0, v29, vcc
	global_load_dwordx4 v[24:27], v[24:25], off
	v_add_co_u32_e32 v28, vcc, s1, v28
	v_add_u32_e32 v58, v68, v69
	s_nop 0
	v_addc_co_u32_e32 v29, vcc, 0, v29, vcc
	global_load_dwordx4 v[28:31], v[28:29], off
	s_waitcnt vmcnt(7)
	ds_write2_b32 v58, v0, v1 offset1:1
	ds_write2_b32 v58, v2, v3 offset0:2 offset1:3
	v_add_u32_e32 v0, 0x420, v58
	s_waitcnt vmcnt(6)
	ds_write2_b32 v0, v4, v5 offset1:1
	v_add_u32_e32 v0, 0x428, v58
	ds_write2_b32 v0, v6, v7 offset1:1
	v_add_u32_e32 v0, 0x840, v58
	s_waitcnt vmcnt(5)
	ds_write2_b32 v0, v8, v9 offset1:1
	v_add_u32_e32 v0, 0x848, v58
	ds_write2_b32 v0, v10, v11 offset1:1
	v_add_u32_e32 v0, 0xc60, v58
	s_waitcnt vmcnt(4)
	ds_write2_b32 v0, v12, v13 offset1:1
	v_add_u32_e32 v0, 0xc68, v58
	ds_write2_b32 v0, v14, v15 offset1:1
	v_add_u32_e32 v0, 0x1080, v58
	s_waitcnt vmcnt(3)
	ds_write2_b32 v0, v16, v17 offset1:1
	v_add_u32_e32 v0, 0x1088, v58
	ds_write2_b32 v0, v18, v19 offset1:1
	v_add_u32_e32 v0, 0x14a0, v58
	s_waitcnt vmcnt(2)
	ds_write2_b32 v0, v20, v21 offset1:1
	v_add_u32_e32 v0, 0x14a8, v58
	ds_write2_b32 v0, v22, v23 offset1:1
	v_add_u32_e32 v0, 0x18c0, v58
	v_add_u32_e32 v22, s0, v32
	v_ashrrev_i32_e32 v23, 31, v22
	s_waitcnt vmcnt(1)
	ds_write2_b32 v0, v24, v25 offset1:1
	v_add_u32_e32 v0, 0x18c8, v58
	ds_write2_b32 v0, v26, v27 offset1:1
	v_add_u32_e32 v0, 0x1ce0, v58
	v_lshlrev_b64 v[22:23], 13, v[22:23]
	s_waitcnt vmcnt(0)
	ds_write2_b32 v0, v28, v29 offset1:1
	v_add_u32_e32 v0, 0x1ce8, v58
	ds_write2_b32 v0, v30, v31 offset1:1
	s_waitcnt lgkmcnt(0)
	ds_read2_b32 v[6:7], v71 offset0:33 offset1:41
	ds_read2_b32 v[8:9], v71 offset1:8
	ds_read2_b32 v[10:11], v71 offset0:66 offset1:74
	ds_read2_b32 v[12:13], v71 offset0:99 offset1:107
	ds_read2_b32 v[14:15], v71 offset0:132 offset1:140
	ds_read2_b32 v[16:17], v71 offset0:165 offset1:173
	ds_read2_b32 v[18:19], v71 offset0:198 offset1:206
	ds_read2_b32 v[20:21], v71 offset0:231 offset1:239
	v_lshl_add_u64 v[0:1], s[34:35], 1, v[52:53]
	s_waitcnt lgkmcnt(6)
	v_cvt_pk_bf16_f32 v2, v8, v6
	s_waitcnt lgkmcnt(4)
	v_cvt_pk_bf16_f32 v3, v10, v12
	s_waitcnt lgkmcnt(2)
	v_cvt_pk_bf16_f32 v4, v14, v16
	s_waitcnt lgkmcnt(0)
	v_cvt_pk_bf16_f32 v5, v18, v20
	v_lshl_add_u64 v[22:23], v[0:1], 0, v[22:23]
	v_add_u32_e32 v6, s0, v34
	global_store_dwordx4 v[22:23], v[2:5], off sc1
	v_add_u32_e32 v22, s0, v36
	v_ashrrev_i32_e32 v23, 31, v22
	v_cvt_pk_bf16_f32 v2, v9, v7
	v_ashrrev_i32_e32 v7, 31, v6
	v_lshlrev_b64 v[6:7], 13, v[6:7]
	v_cvt_pk_bf16_f32 v3, v11, v13
	v_cvt_pk_bf16_f32 v4, v15, v17
	v_cvt_pk_bf16_f32 v5, v19, v21
	v_lshl_add_u64 v[6:7], v[0:1], 0, v[6:7]
	global_store_dwordx4 v[6:7], v[2:5], off sc1
	ds_read2_b32 v[6:7], v71 offset0:16 offset1:24
	ds_read2_b32 v[8:9], v71 offset0:49 offset1:57
	ds_read2_b32 v[10:11], v71 offset0:82 offset1:90
	ds_read2_b32 v[12:13], v71 offset0:115 offset1:123
	ds_read2_b32 v[14:15], v71 offset0:148 offset1:156
	ds_read2_b32 v[16:17], v71 offset0:181 offset1:189
	ds_read2_b32 v[18:19], v71 offset0:214 offset1:222
	ds_read2_b32 v[20:21], v71 offset0:247 offset1:255
	v_lshlrev_b64 v[22:23], 13, v[22:23]
	s_waitcnt lgkmcnt(6)
	v_cvt_pk_bf16_f32 v2, v6, v8
	s_waitcnt lgkmcnt(4)
	v_cvt_pk_bf16_f32 v3, v10, v12
	s_waitcnt lgkmcnt(2)
	v_cvt_pk_bf16_f32 v4, v14, v16
	s_waitcnt lgkmcnt(0)
	v_cvt_pk_bf16_f32 v5, v18, v20
	v_lshl_add_u64 v[22:23], v[0:1], 0, v[22:23]
	v_add_u32_e32 v6, s0, v38
	global_store_dwordx4 v[22:23], v[2:5], off sc1
	s_mov_b64 s[0:1], 0
	s_nop 0
	v_cvt_pk_bf16_f32 v2, v7, v9
	v_ashrrev_i32_e32 v7, 31, v6
	v_lshlrev_b64 v[6:7], 13, v[6:7]
	v_cvt_pk_bf16_f32 v3, v11, v13
	v_cvt_pk_bf16_f32 v4, v15, v17
	v_cvt_pk_bf16_f32 v5, v19, v21
	v_lshl_add_u64 v[0:1], v[0:1], 0, v[6:7]
	global_store_dwordx4 v[0:1], v[2:5], off sc1
	s_waitcnt lgkmcnt(0)

.LBB0_310:
	v_add_u32_e32 v8, 0x1080, v24
	ds_write2_b32 v8, v4, v5 offset1:1
	v_add_u32_e32 v4, 0x1088, v24
	ds_write2_b32 v4, v6, v7 offset1:1
	s_waitcnt vmcnt(0)
	v_pk_mul_f32 v[0:1], v[0:1], v[16:17] op_sel_hi:[1,0]
	v_add_u32_e32 v4, 0x14a0, v24
	ds_write2_b32 v4, v0, v1 offset1:1
	v_pk_mul_f32 v[0:1], v[2:3], v[16:17] op_sel_hi:[1,0]
	v_add_u32_e32 v2, 0x14a8, v24
	ds_write2_b32 v2, v0, v1 offset1:1
	s_waitcnt lgkmcnt(0)
	ds_read2_b32 v[6:7], v71 offset0:33 offset1:41
	ds_read2_b32 v[8:9], v71 offset1:8
	ds_read2_b32 v[10:11], v71 offset0:66 offset1:74
	ds_read2_b32 v[12:13], v71 offset0:99 offset1:107
	ds_read2_b32 v[14:15], v71 offset0:132 offset1:140
	ds_read2_b32 v[16:17], v71 offset0:165 offset1:173
	ds_read2_b32 v[18:19], v71 offset0:198 offset1:206
	ds_read2_b32 v[20:21], v71 offset0:231 offset1:239
	v_add_u32_e32 v22, s4, v32
	s_lshl_b32 s34, s5, 1
	v_ashrrev_i32_e32 v23, 31, v22
	v_lshl_add_u64 v[4:5], v[54:55], 0, s[34:35]
	v_lshlrev_b64 v[22:23], 11, v[22:23]
	s_waitcnt lgkmcnt(6)
	v_cvt_pk_bf16_f32 v0, v8, v6
	s_waitcnt lgkmcnt(4)
	v_cvt_pk_bf16_f32 v1, v10, v12
	s_waitcnt lgkmcnt(2)
	v_cvt_pk_bf16_f32 v2, v14, v16
	s_waitcnt lgkmcnt(0)
	v_cvt_pk_bf16_f32 v3, v18, v20
	v_lshl_add_u64 v[22:23], v[4:5], 0, v[22:23]
	v_add_u32_e32 v6, s4, v34
	global_store_dwordx4 v[22:23], v[0:3], off sc1
	v_add_u32_e32 v22, s4, v36
	v_ashrrev_i32_e32 v23, 31, v22
	v_cvt_pk_bf16_f32 v0, v9, v7
	v_ashrrev_i32_e32 v7, 31, v6
	v_lshlrev_b64 v[6:7], 11, v[6:7]
	v_cvt_pk_bf16_f32 v1, v11, v13
	v_cvt_pk_bf16_f32 v2, v15, v17
	v_cvt_pk_bf16_f32 v3, v19, v21
	v_lshl_add_u64 v[6:7], v[4:5], 0, v[6:7]
	global_store_dwordx4 v[6:7], v[0:3], off sc1
	ds_read2_b32 v[6:7], v71 offset0:16 offset1:24
	ds_read2_b32 v[8:9], v71 offset0:49 offset1:57
	ds_read2_b32 v[10:11], v71 offset0:82 offset1:90
	ds_read2_b32 v[12:13], v71 offset0:115 offset1:123
	ds_read2_b32 v[14:15], v71 offset0:148 offset1:156
	ds_read2_b32 v[16:17], v71 offset0:181 offset1:189
	ds_read2_b32 v[18:19], v71 offset0:214 offset1:222
	ds_read2_b32 v[20:21], v71 offset0:247 offset1:255
	v_lshlrev_b64 v[22:23], 11, v[22:23]
	s_waitcnt lgkmcnt(6)
	v_cvt_pk_bf16_f32 v0, v6, v8
	s_waitcnt lgkmcnt(4)
	v_cvt_pk_bf16_f32 v1, v10, v12
	s_waitcnt lgkmcnt(2)
	v_cvt_pk_bf16_f32 v2, v14, v16
	s_waitcnt lgkmcnt(0)
	v_cvt_pk_bf16_f32 v3, v18, v20
	v_lshl_add_u64 v[22:23], v[4:5], 0, v[22:23]
	v_add_u32_e32 v6, s4, v38
	global_store_dwordx4 v[22:23], v[0:3], off sc1
	s_nop 1
	v_cvt_pk_bf16_f32 v0, v7, v9
	v_ashrrev_i32_e32 v7, 31, v6
	v_lshlrev_b64 v[6:7], 11, v[6:7]
	v_cvt_pk_bf16_f32 v1, v11, v13
	v_cvt_pk_bf16_f32 v2, v15, v17
	v_cvt_pk_bf16_f32 v3, v19, v21
	v_lshl_add_u64 v[4:5], v[4:5], 0, v[6:7]
	global_store_dwordx4 v[4:5], v[0:3], off sc1
	s_waitcnt lgkmcnt(0)

.LBB0_338:
	v_add_u32_e32 v4, 0x1080, v24
	ds_write2_b32 v4, v12, v13 offset1:1
	v_add_u32_e32 v4, 0x1088, v24
	ds_write2_b32 v4, v10, v11 offset1:1
	s_waitcnt vmcnt(0)
	v_pk_mul_f32 v[0:1], v[0:1], v[8:9] op_sel_hi:[1,0]
	v_add_u32_e32 v4, 0x14a0, v24
	ds_write2_b32 v4, v0, v1 offset1:1
	v_pk_mul_f32 v[0:1], v[2:3], v[8:9] op_sel_hi:[1,0]
	v_add_u32_e32 v2, 0x14a8, v24
	ds_write2_b32 v2, v0, v1 offset1:1
	s_waitcnt lgkmcnt(0)
	ds_read2_b32 v[6:7], v71 offset0:33 offset1:41
	ds_read2_b32 v[8:9], v71 offset1:8
	ds_read2_b32 v[10:11], v71 offset0:66 offset1:74
	ds_read2_b32 v[12:13], v71 offset0:99 offset1:107
	ds_read2_b32 v[14:15], v71 offset0:132 offset1:140
	ds_read2_b32 v[16:17], v71 offset0:165 offset1:173
	ds_read2_b32 v[18:19], v71 offset0:198 offset1:206
	ds_read2_b32 v[20:21], v71 offset0:231 offset1:239
	v_add_u32_e32 v22, s4, v32
	v_ashrrev_i32_e32 v23, 31, v22
	v_lshl_add_u64 v[4:5], s[28:29], 1, v[50:51]
	v_lshlrev_b64 v[22:23], 11, v[22:23]
	s_waitcnt lgkmcnt(6)
	v_cvt_pk_bf16_f32 v0, v8, v6
	s_waitcnt lgkmcnt(4)
	v_cvt_pk_bf16_f32 v1, v10, v12
	s_waitcnt lgkmcnt(2)
	v_cvt_pk_bf16_f32 v2, v14, v16
	s_waitcnt lgkmcnt(0)
	v_cvt_pk_bf16_f32 v3, v18, v20
	v_lshl_add_u64 v[22:23], v[4:5], 0, v[22:23]
	v_add_u32_e32 v6, s4, v34
	global_store_dwordx4 v[22:23], v[0:3], off sc1
	v_add_u32_e32 v22, s4, v36
	v_ashrrev_i32_e32 v23, 31, v22
	v_cvt_pk_bf16_f32 v0, v9, v7
	v_ashrrev_i32_e32 v7, 31, v6
	v_lshlrev_b64 v[6:7], 11, v[6:7]
	v_cvt_pk_bf16_f32 v1, v11, v13
	v_cvt_pk_bf16_f32 v2, v15, v17
	v_cvt_pk_bf16_f32 v3, v19, v21
	v_lshl_add_u64 v[6:7], v[4:5], 0, v[6:7]
	global_store_dwordx4 v[6:7], v[0:3], off sc1
	ds_read2_b32 v[6:7], v71 offset0:16 offset1:24
	ds_read2_b32 v[8:9], v71 offset0:49 offset1:57
	ds_read2_b32 v[10:11], v71 offset0:82 offset1:90
	ds_read2_b32 v[12:13], v71 offset0:115 offset1:123
	ds_read2_b32 v[14:15], v71 offset0:148 offset1:156
	ds_read2_b32 v[16:17], v71 offset0:181 offset1:189
	ds_read2_b32 v[18:19], v71 offset0:214 offset1:222
	ds_read2_b32 v[20:21], v71 offset0:247 offset1:255
	v_lshlrev_b64 v[22:23], 11, v[22:23]
	s_waitcnt lgkmcnt(6)
	v_cvt_pk_bf16_f32 v0, v6, v8
	s_waitcnt lgkmcnt(4)
	v_cvt_pk_bf16_f32 v1, v10, v12
	s_waitcnt lgkmcnt(2)
	v_cvt_pk_bf16_f32 v2, v14, v16
	s_waitcnt lgkmcnt(0)
	v_cvt_pk_bf16_f32 v3, v18, v20
	v_lshl_add_u64 v[22:23], v[4:5], 0, v[22:23]
	v_add_u32_e32 v6, s4, v38
	global_store_dwordx4 v[22:23], v[0:3], off sc1
	s_nop 1
	v_cvt_pk_bf16_f32 v0, v7, v9
	v_ashrrev_i32_e32 v7, 31, v6
	v_lshlrev_b64 v[6:7], 11, v[6:7]
	v_cvt_pk_bf16_f32 v1, v11, v13
	v_cvt_pk_bf16_f32 v2, v15, v17
	v_cvt_pk_bf16_f32 v3, v19, v21
	v_lshl_add_u64 v[4:5], v[4:5], 0, v[6:7]
	global_store_dwordx4 v[4:5], v[0:3], off sc1
	s_waitcnt lgkmcnt(0)
	s_cbranch_execnz .LBB0_249
	s_branch .LBB0_298

.LBB0_347:
	s_nop 6
	v_bfe_u32 v0, v80, 3, 6
	s_movk_i32 s4, 0x110
	v_bfe_u32 v1, v80, 2, 1
	v_mad_u32_u24 v8, v0, s4, 0
	v_lshrrev_b32_e32 v0, 6, v80
	v_and_or_b32 v0, v0, 6, v1
	v_and_b32_e32 v2, 3, v80
	v_lshlrev_b32_e32 v64, 10, v0
	v_lshlrev_b32_e32 v9, 6, v1
	v_lshlrev_b32_e32 v10, 3, v2
	v_lshl_add_u64 v[0:1], s[2:3], 0, v[64:65]
	v_lshlrev_b32_e32 v2, 8, v2
	v_lshlrev_b32_e32 v3, 1, v80
	s_movk_i32 s2, 0xf0
	v_and_or_b32 v64, v3, s2, v2
	v_lshl_add_u64 v[0:1], v[0:1], 0, v[64:65]
	s_mov_b64 s[2:3], 0x4000
	v_ashrrev_i32_e32 v6, 9, v80
	v_lshl_add_u64 v[4:5], v[0:1], 0, s[2:3]
	v_mul_i32_i24_e32 v0, 0x4400, v6
	v_add3_u32 v0, v8, v0, v9
	s_mov_b32 s2, 0x14a80
	v_add3_u32 v0, v0, v10, s2
	s_waitcnt lgkmcnt(0)
	s_barrier
	ds_read2_b64 v[0:3], v0 offset1:4
	v_mul_hi_i32_i24_e32 v7, 0x6000, v6
	v_mul_i32_i24_e32 v6, 0x6000, v6
	v_lshl_add_u64 v[6:7], v[4:5], 0, v[6:7]
	s_add_i32 s53, s53, s52
	s_waitcnt lgkmcnt(0)
	v_xor_b32_e32 v0, 0x80008000, v0
	v_xor_b32_e32 v1, 0x80008000, v1
	v_xor_b32_e32 v2, 0x80008000, v2
	v_xor_b32_e32 v3, 0x80008000, v3
	global_store_dwordx4 v[6:7], v[0:3], off sc1
	s_and_b64 vcc, exec, s[22:23]
	s_nop 0
	v_add_u32_e32 v0, 0x200, v80
	v_ashrrev_i32_e32 v6, 9, v0
	v_mul_i32_i24_e32 v0, 0x4400, v6
	v_add3_u32 v0, v8, v0, v9
	v_add3_u32 v0, v0, v10, s2
	ds_read2_b64 v[0:3], v0 offset1:4
	v_mul_hi_i32_i24_e32 v7, 0x6000, v6
	v_mul_i32_i24_e32 v6, 0x6000, v6
	v_lshl_add_u64 v[4:5], v[4:5], 0, v[6:7]
	s_waitcnt lgkmcnt(0)
	v_xor_b32_e32 v0, 0x80008000, v0
	v_xor_b32_e32 v1, 0x80008000, v1
	v_xor_b32_e32 v2, 0x80008000, v2
	v_xor_b32_e32 v3, 0x80008000, v3
	global_store_dwordx4 v[4:5], v[0:3], off sc1
	s_waitcnt vmcnt(63) expcnt(7) lgkmcnt(15)
	s_barrier
	s_cbranch_vccnz .LBB0_557

.LBB0_494:
	s_mul_i32 s2, s54, 0x10400
	v_readlane_b32 s4, v250, 48
	s_mul_hi_i32 s3, s54, 0x10400
	s_add_u32 s2, s4, s2
	v_readlane_b32 s4, v250, 49
	s_addc_u32 s3, s4, s3
	v_readlane_b32 s4, v252, 6
	v_readlane_b32 s5, v252, 7
	s_mov_b64 s[22:23], -1
	s_and_b64 vcc, exec, s[4:5]
	s_waitcnt lgkmcnt(0)
	s_barrier
	s_cbranch_vccz .LBB0_500
	s_and_b64 vcc, exec, s[42:43]
	s_cbranch_vccnz .LBB0_499
	v_add_u32_e32 v0, 0xffffff00, v80
	v_and_b32_e32 v2, 3, v80
	v_bfe_u32 v1, v80, 2, 1
	v_lshlrev_b32_e32 v3, 2, v2
	v_lshlrev_b32_e32 v11, 8, v2
	v_ashrrev_i32_e32 v13, 3, v0
	v_lshrrev_b32_e32 v2, 6, v0
	s_mov_b32 s9, 0x3ffffe
	s_movk_i32 s4, 0x90
	v_lshl_or_b32 v10, v1, 5, v3
	v_and_or_b32 v2, v2, s9, v1
	v_lshlrev_b32_e32 v3, 4, v13
	v_mul_lo_u32 v14, v13, s4
	v_lshlrev_b32_e32 v12, 1, v10
	v_lshlrev_b32_e32 v2, 10, v2
	v_and_b32_e32 v3, 0xf0, v3
	v_add_u32_e32 v15, 0, v14
	v_or3_b32 v6, v2, v3, v11
	v_add_u32_e32 v2, v15, v12
	v_add_u32_e32 v2, 0x2000, v2
	ds_read2_b64 v[2:5], v2 offset0:128 offset1:132
	v_ashrrev_i32_e32 v7, 31, v6
	v_lshl_add_u64 v[8:9], s[2:3], 0, v[6:7]
	s_movk_i32 s4, 0xff72
	v_mul_u32_u24_e32 v10, 0x90, v10
	s_waitcnt lgkmcnt(0)
	global_store_dwordx4 v[8:9], v[2:5], off sc1
	s_add_u32 s22, s2, 0x2000
	s_addc_u32 s23, s3, 0
	v_mul_lo_u32 v2, v13, s4
	v_add3_u32 v2, v15, v2, v10
	ds_read_u16 v3, v2
	ds_read_u16 v4, v2 offset:144
	ds_read_u16 v5, v2 offset:288
	ds_read_u16 v8, v2 offset:432
	ds_read_u16 v9, v2 offset:2304
	ds_read_u16 v13, v2 offset:2448
	ds_read_u16 v15, v2 offset:2592
	ds_read_u16 v52, v2 offset:2736
	v_readlane_b32 s8, v254, 55
	s_waitcnt lgkmcnt(6)
	v_lshl_or_b32 v2, v4, 16, v3
	s_waitcnt lgkmcnt(4)
	v_lshl_or_b32 v3, v8, 16, v5
	s_waitcnt lgkmcnt(2)
	v_lshl_or_b32 v4, v13, 16, v9
	s_waitcnt lgkmcnt(0)
	v_lshl_or_b32 v5, v52, 16, v15
	v_lshl_add_u64 v[8:9], s[22:23], 0, v[6:7]
	v_add3_u32 v13, s8, v14, v12
	global_store_dwordx4 v[8:9], v[2:5], off sc1
	ds_read2_b64 v[2:5], v13 offset1:4
	s_add_u32 s4, s2, 0x6000
	s_addc_u32 s5, s3, 0
	v_lshl_add_u64 v[8:9], s[4:5], 0, v[6:7]
	s_add_u32 s6, s2, 0xc000
	s_waitcnt lgkmcnt(0)
	global_store_dwordx4 v[8:9], v[2:5], off sc1
	s_addc_u32 s7, s3, 0
	v_lshl_add_u64 v[6:7], s[6:7], 0, v[6:7]
	v_add_u32_e32 v2, 0x2000, v13
	ds_read2_b64 v[2:5], v2 offset0:128 offset1:132
	s_waitcnt lgkmcnt(0)
	global_store_dwordx4 v[6:7], v[2:5], off sc1
	s_nop 1
	v_lshrrev_b32_e32 v2, 6, v80
	v_and_or_b32 v1, v2, s9, v1
	v_lshlrev_b32_e32 v2, 4, v58
	v_lshlrev_b32_e32 v1, 10, v1
	v_and_b32_e32 v2, 0xf0, v2
	v_or3_b32 v6, v1, v2, v11
	v_add_u32_e32 v1, v60, v12
	v_add_u32_e32 v1, 0x2000, v1
	ds_read2_b64 v[2:5], v1 offset0:128 offset1:132
	v_ashrrev_i32_e32 v7, 31, v6
	v_lshl_add_u64 v[8:9], s[2:3], 0, v[6:7]
	v_lshlrev_b32_e32 v1, 1, v58
	v_add3_u32 v1, 0, v1, v10
	s_waitcnt lgkmcnt(0)
	global_store_dwordx4 v[8:9], v[2:5], off sc1
	ds_read_u16 v2, v1
	ds_read_u16 v3, v1 offset:144
	ds_read_u16 v4, v1 offset:288
	ds_read_u16 v5, v1 offset:432
	ds_read_u16 v8, v1 offset:2304
	ds_read_u16 v9, v1 offset:2448
	ds_read_u16 v10, v1 offset:2592
	ds_read_u16 v1, v1 offset:2736
	s_waitcnt lgkmcnt(6)
	v_lshl_or_b32 v2, v3, 16, v2
	s_waitcnt lgkmcnt(4)
	v_lshl_or_b32 v3, v5, 16, v4
	s_waitcnt lgkmcnt(2)
	v_lshl_or_b32 v4, v9, 16, v8
	v_lshl_add_u64 v[8:9], s[22:23], 0, v[6:7]
	s_waitcnt lgkmcnt(0)
	v_lshl_or_b32 v5, v1, 16, v10
	v_add3_u32 v1, s8, v59, v12
	global_store_dwordx4 v[8:9], v[2:5], off sc1
	ds_read2_b64 v[2:5], v1 offset1:4
	v_lshl_add_u64 v[8:9], s[4:5], 0, v[6:7]
	v_add_u32_e32 v1, 0x2000, v1
	s_movk_i32 s4, 0x180
	v_lshl_add_u64 v[6:7], s[6:7], 0, v[6:7]
	s_waitcnt lgkmcnt(0)
	global_store_dwordx4 v[8:9], v[2:5], off sc1
	ds_read2_b64 v[2:5], v1 offset0:128 offset1:132
	v_cmp_gt_i32_e32 vcc, s4, v80
	s_waitcnt lgkmcnt(0)
	global_store_dwordx4 v[6:7], v[2:5], off sc1
	s_and_saveexec_b64 s[22:23], vcc
	s_cbranch_execz .LBB0_498
	v_cmp_gt_u32_e32 vcc, 64, v0
	v_mov_b32_e32 v1, 0x21f00
	v_mov_b32_e32 v2, 0x21efc
	v_cndmask_b32_e32 v1, v1, v2, vcc
	v_add_u32_e32 v1, 0, v1
	ds_read_b32 v6, v1
	v_lshlrev_b32_e32 v1, 3, v0
	v_and_b32_e32 v0, 0x3fffffc0, v0
	v_lshlrev_b32_e32 v0, 2, v0
	v_lshlrev_b32_e32 v64, 2, v81
	v_add3_u32 v0, s28, v0, v64
	v_and_b32_e32 v2, 0xfffffe00, v1
	ds_read2st64_b32 v[0:1], v0 offset0:4 offset1:6
	v_ashrrev_i32_e32 v3, 31, v2
	v_lshl_add_u64 v[2:3], s[2:3], 0, v[2:3]
	v_lshl_add_u64 v[2:3], v[2:3], 0, v[64:65]
	s_mov_b64 s[4:5], 0x10000
	s_waitcnt lgkmcnt(0)
	v_sub_f32_e32 v0, v6, v0
	v_mul_f32_e32 v0, 0x3fb8aa3b, v0
	v_exp_f32_e32 v0, v0
	v_lshl_add_u64 v[4:5], v[2:3], 0, s[4:5]
	v_add_co_u32_e32 v2, vcc, 0x10000, v2
	s_nop 1
	v_addc_co_u32_e32 v3, vcc, 0, v3, vcc
	global_store_dword v[2:3], v1, off sc1
	global_store_dword v[4:5], v0, off offset:256 sc1

.LBB0_538:
	v_lshlrev_b32_e32 v81, 3, v81
	s_andn2_b64 vcc, exec, s[44:45]
	v_or_b32_e32 v85, s90, v81
	s_cbranch_vccnz .LBB0_540
	global_store_dwordx2 v85, v[70:71], s[36:37] sc1
	v_pk_mov_b32 v[70:71], v[14:15], v[14:15] op_sel:[1,0]
	v_pk_mov_b32 v[96:97], v[12:13], v[12:13] op_sel:[1,0]
	v_mov_b32_e32 v90, s90
	s_movk_i32 s4, 0x780
	v_cvt_pk_bf16_f32 v70, v70, v71
	v_cvt_pk_bf16_f32 v71, v96, v97
	v_bitop3_b32 v90, v81, s4, v90 bitop3:0x36
	global_store_dwordx2 v90, v[70:71], s[28:29] sc1

.LBB0_542:
	s_andn2_b64 vcc, exec, s[44:45]
	s_cbranch_vccnz .LBB0_544
	global_store_dwordx2 v85, v[70:71], s[36:37] offset:512 sc1
	v_pk_mov_b32 v[70:71], v[58:59], v[58:59] op_sel:[1,0]
	v_pk_mov_b32 v[88:89], v[56:57], v[56:57] op_sel:[1,0]
	v_cvt_pk_bf16_f32 v70, v70, v71
	v_cvt_pk_bf16_f32 v71, v88, v89
	v_mov_b32_e32 v88, s90
	s_movk_i32 s4, 0x580
	v_bitop3_b32 v88, v81, s4, v88 bitop3:0x36
	global_store_dwordx2 v88, v[70:71], s[28:29] sc1

.LBB0_546:
	s_andn2_b64 vcc, exec, s[44:45]
	s_cbranch_vccnz .LBB0_548
	global_store_dwordx2 v85, v[70:71], s[36:37] offset:1024 sc1
	v_pk_mov_b32 v[70:71], v[62:63], v[62:63] op_sel:[1,0]
	v_pk_mov_b32 v[76:77], v[60:61], v[60:61] op_sel:[1,0]
	v_cvt_pk_bf16_f32 v70, v70, v71
	v_cvt_pk_bf16_f32 v71, v76, v77
	v_mov_b32_e32 v76, s90
	s_movk_i32 s4, 0x380
	v_bitop3_b32 v76, v81, s4, v76 bitop3:0x36
	global_store_dwordx2 v76, v[70:71], s[28:29] sc1

.LBB0_550:
	s_andn2_b64 vcc, exec, s[44:45]
	s_cbranch_vccnz .LBB0_347
	s_nop 6
	v_pk_mov_b32 v[2:3], v[2:3], v[2:3] op_sel:[1,0]
	v_pk_mov_b32 v[0:1], v[0:1], v[0:1] op_sel:[1,0]
	v_cvt_pk_bf16_f32 v2, v2, v3
	v_cvt_pk_bf16_f32 v3, v0, v1
	v_mov_b32_e32 v0, s90
	s_movk_i32 s4, 0x180
	v_bitop3_b32 v0, v81, s4, v0 bitop3:0x36
	global_store_dwordx2 v85, v[4:5], s[36:37] offset:1536 sc1
	global_store_dwordx2 v0, v[2:3], s[28:29] sc1
	s_branch .LBB0_347

.LBB0_617:
	s_or_b64 exec, exec, s[28:29]
	v_add_u32_e32 v150, s2, v148
	v_add_u32_e32 v148, 0x80, v150
	v_ashrrev_i32_e32 v149, 31, v148
	v_lshlrev_b64 v[148:149], 11, v[148:149]
	s_waitcnt lgkmcnt(0)
	s_barrier
	v_lshl_add_u64 v[148:149], v[146:147], 0, v[148:149]
	global_load_dwordx4 v[190:193], v[148:149], off
	global_load_dwordx4 v[186:189], v[148:149], off offset:256
	v_add_u32_e32 v148, 0x90, v150
	v_ashrrev_i32_e32 v149, 31, v148
	v_lshlrev_b64 v[148:149], 11, v[148:149]
	v_lshl_add_u64 v[148:149], v[146:147], 0, v[148:149]
	global_load_dwordx4 v[174:177], v[148:149], off
	global_load_dwordx4 v[170:173], v[148:149], off offset:256
	v_add_u32_e32 v148, 0xa0, v150
	v_ashrrev_i32_e32 v149, 31, v148
	v_lshlrev_b64 v[148:149], 11, v[148:149]
	v_lshl_add_u64 v[148:149], v[146:147], 0, v[148:149]
	global_load_dwordx4 v[158:161], v[148:149], off
	global_load_dwordx4 v[154:157], v[148:149], off offset:256
	v_add_u32_e32 v148, 0xb0, v150
	v_ashrrev_i32_e32 v149, 31, v148
	v_lshlrev_b64 v[148:149], 11, v[148:149]
	v_lshl_add_u64 v[146:147], v[146:147], 0, v[148:149]
	global_load_dwordx4 v[150:153], v[146:147], off
	s_nop 0
	global_load_dwordx4 v[146:149], v[146:147], off offset:256
	s_waitcnt lgkmcnt(0)
	v_cmp_eq_u32_e64 s[46:47], 0, v64
	v_lshl_add_u32 v64, v248, 2, 0
	ds_read_b32 v232, v64 offset:8192
	v_add_u32_e32 v228, s52, v248
	v_ashrrev_i32_e32 v229, 31, v228
	v_readlane_b32 s0, v252, 32
	v_lshlrev_b64 v[210:211], 10, v[228:229]
	v_readlane_b32 s1, v252, 33
	v_lshl_add_u64 v[230:231], v[210:211], 0, v[226:227]
	s_waitcnt vmcnt(0)
	v_lshlrev_b32_e32 v210, 16, v206
	v_and_b32_e32 v211, 0xffff0000, v206
	v_lshlrev_b32_e32 v206, 16, v207
	v_and_b32_e32 v207, 0xffff0000, v207
	s_waitcnt lgkmcnt(0)
	v_pk_mul_f32 v[136:137], v[136:137], v[232:233] op_sel_hi:[1,0]
	v_pk_mul_f32 v[134:135], v[134:135], v[232:233] op_sel_hi:[1,0]
	s_or_b64 s[16:17], s[22:23], s[0:1]
	v_readlane_b32 s0, v250, 15
	v_pk_fma_f32 v[134:135], v[102:103], v[134:135], v[210:211]
	v_pk_fma_f32 v[136:137], v[104:105], v[136:137], v[206:207]
	s_xor_b64 s[22:23], s[16:17], -1
	v_readlane_b32 s12, v250, 27
	v_readlane_b32 s13, v250, 28
	v_cndmask_b32_e64 v137, v238, v137, s[46:47]
	v_cndmask_b32_e64 v136, v238, v136, s[46:47]
	v_cndmask_b32_e64 v135, v238, v135, s[46:47]
	v_cndmask_b32_e64 v134, v238, v134, s[46:47]
	s_mov_b64 s[28:29], -1
	s_and_b64 vcc, exec, s[22:23]
	v_lshl_add_u64 v[206:207], v[230:231], 2, s[12:13]
	v_readlane_b32 s1, v250, 16
	v_readlane_b32 s2, v250, 17
	v_readlane_b32 s3, v250, 18
	v_readlane_b32 s4, v250, 19
	v_readlane_b32 s5, v250, 20
	v_readlane_b32 s6, v250, 21
	v_readlane_b32 s7, v250, 22
	v_readlane_b32 s8, v250, 23
	v_readlane_b32 s9, v250, 24
	v_readlane_b32 s10, v250, 25
	v_readlane_b32 s11, v250, 26
	v_readlane_b32 s14, v250, 29
	v_readlane_b32 s15, v250, 30
	s_cbranch_vccz .LBB0_619
	s_mov_b64 s[28:29], 0
	global_store_dwordx4 v[206:207], v[134:137], off sc1

.LBB0_621:
	v_mov_b32_e32 v233, v232
	v_mov_b32_e32 v212, v232
	v_mov_b32_e32 v213, v232
	v_lshlrev_b32_e32 v210, 16, v208
	v_and_b32_e32 v211, 0xffff0000, v208
	v_lshlrev_b32_e32 v208, 16, v209
	v_and_b32_e32 v209, 0xffff0000, v209
	v_pk_mul_f32 v[144:145], v[144:145], v[212:213]
	v_pk_mul_f32 v[142:143], v[142:143], v[232:233]
	v_pk_fma_f32 v[144:145], v[100:101], v[144:145], v[208:209]
	v_pk_fma_f32 v[142:143], v[98:99], v[142:143], v[210:211]
	v_cndmask_b32_e64 v208, 0, 1, s[22:23]
	v_cndmask_b32_e64 v145, v238, v145, s[46:47]
	v_cndmask_b32_e64 v144, v238, v144, s[46:47]
	v_cndmask_b32_e64 v143, v238, v143, s[46:47]
	v_cndmask_b32_e64 v142, v238, v142, s[46:47]
	v_cmp_ne_u32_e64 s[48:49], 1, v208
	s_andn2_b64 vcc, exec, s[22:23]
	s_mov_b64 s[22:23], -1
	s_cbranch_vccnz .LBB0_623
	s_mov_b64 s[22:23], 0
	global_store_dwordx4 v[206:207], v[142:145], off offset:16 sc1

.LBB0_625:
	v_mov_b32_e32 v210, v232
	v_mov_b32_e32 v211, v232
	v_lshlrev_b32_e32 v208, 16, v202
	v_and_b32_e32 v209, 0xffff0000, v202
	v_lshlrev_b32_e32 v202, 16, v203
	v_and_b32_e32 v203, 0xffff0000, v203
	v_pk_mul_f32 v[140:141], v[140:141], v[210:211]
	v_pk_mul_f32 v[138:139], v[138:139], v[232:233]
	v_pk_fma_f32 v[140:141], v[92:93], v[140:141], v[202:203]
	v_pk_fma_f32 v[138:139], v[90:91], v[138:139], v[208:209]
	v_cndmask_b32_e64 v141, v238, v141, s[46:47]
	v_cndmask_b32_e64 v140, v238, v140, s[46:47]
	v_cndmask_b32_e64 v139, v238, v139, s[46:47]
	v_cndmask_b32_e64 v138, v238, v138, s[46:47]
	s_and_b64 vcc, exec, s[48:49]
	s_mov_b64 s[22:23], -1
	s_cbranch_vccnz .LBB0_627
	s_mov_b64 s[22:23], 0
	global_store_dwordx4 v[206:207], v[138:141], off offset:512 sc1

.LBB0_632:
	v_readlane_b32 s0, v250, 15
	v_readlane_b32 s12, v250, 27
	v_readlane_b32 s13, v250, 28
	v_cvt_pk_bf16_f32 v202, v134, v135
	v_cvt_pk_bf16_f32 v203, v136, v137
	v_cvt_pk_bf16_f32 v204, v142, v143
	v_cvt_pk_bf16_f32 v205, v144, v145
	v_readlane_b32 s1, v250, 16
	s_nop 0
	v_lshl_add_u64 v[206:207], v[230:231], 1, s[12:13]
	v_readlane_b32 s2, v250, 17
	v_readlane_b32 s3, v250, 18
	v_readlane_b32 s4, v250, 19
	v_readlane_b32 s5, v250, 20
	v_readlane_b32 s6, v250, 21
	v_readlane_b32 s7, v250, 22
	v_readlane_b32 s8, v250, 23
	v_readlane_b32 s9, v250, 24
	v_readlane_b32 s10, v250, 25
	v_readlane_b32 s11, v250, 26
	v_readlane_b32 s14, v250, 29
	v_readlane_b32 s15, v250, 30
	global_store_dwordx4 v[206:207], v[202:205], off sc1
	s_nop 1
	v_cvt_pk_bf16_f32 v202, v138, v139
	v_cvt_pk_bf16_f32 v203, v140, v141
	v_cvt_pk_bf16_f32 v204, v130, v131
	v_cvt_pk_bf16_f32 v205, v132, v133
	global_store_dwordx4 v[206:207], v[202:205], off offset:256 sc1
.LBB0_633:
	ds_read_b32 v204, v64 offset:8256
	s_nop 0
	v_add3_u32 v202, s52, v248, 16
	v_ashrrev_i32_e32 v203, 31, v202
	v_lshlrev_b64 v[202:203], 10, v[202:203]
	v_lshlrev_b32_e32 v206, 16, v198
	v_and_b32_e32 v207, 0xffff0000, v198
	v_lshlrev_b32_e32 v198, 16, v199
	v_and_b32_e32 v199, 0xffff0000, v199
	s_waitcnt lgkmcnt(0)
	v_pk_mul_f32 v[128:129], v[128:129], v[204:205] op_sel_hi:[1,0]
	v_pk_mul_f32 v[126:127], v[126:127], v[204:205] op_sel_hi:[1,0]
	v_readlane_b32 s0, v250, 15
	v_lshl_add_u64 v[202:203], v[202:203], 0, v[226:227]
	v_pk_fma_f32 v[126:127], v[102:103], v[126:127], v[206:207]
	v_pk_fma_f32 v[128:129], v[104:105], v[128:129], v[198:199]
	v_readlane_b32 s12, v250, 27
	v_readlane_b32 s13, v250, 28
	v_cndmask_b32_e64 v129, v238, v129, s[46:47]
	v_cndmask_b32_e64 v128, v238, v128, s[46:47]
	v_cndmask_b32_e64 v127, v238, v127, s[46:47]
	v_cndmask_b32_e64 v126, v238, v126, s[46:47]
	s_mov_b64 s[22:23], -1
	s_and_b64 vcc, exec, s[48:49]
	v_lshl_add_u64 v[198:199], v[202:203], 2, s[12:13]
	v_readlane_b32 s1, v250, 16
	v_readlane_b32 s2, v250, 17
	v_readlane_b32 s3, v250, 18
	v_readlane_b32 s4, v250, 19
	v_readlane_b32 s5, v250, 20
	v_readlane_b32 s6, v250, 21
	v_readlane_b32 s7, v250, 22
	v_readlane_b32 s8, v250, 23
	v_readlane_b32 s9, v250, 24
	v_readlane_b32 s10, v250, 25
	v_readlane_b32 s11, v250, 26
	v_readlane_b32 s14, v250, 29
	v_readlane_b32 s15, v250, 30
	s_cbranch_vccnz .LBB0_635
	s_mov_b64 s[22:23], 0
	global_store_dwordx4 v[198:199], v[126:129], off sc1

.LBB0_637:
	v_mov_b32_e32 v205, v204
	v_mov_b32_e32 v208, v204
	v_mov_b32_e32 v209, v204
	v_lshlrev_b32_e32 v206, 16, v200
	v_and_b32_e32 v207, 0xffff0000, v200
	v_lshlrev_b32_e32 v200, 16, v201
	v_and_b32_e32 v201, 0xffff0000, v201
	v_pk_mul_f32 v[124:125], v[124:125], v[208:209]
	v_pk_mul_f32 v[122:123], v[122:123], v[204:205]
	v_pk_fma_f32 v[124:125], v[100:101], v[124:125], v[200:201]
	v_pk_fma_f32 v[122:123], v[98:99], v[122:123], v[206:207]
	v_cndmask_b32_e64 v125, v238, v125, s[46:47]
	v_cndmask_b32_e64 v124, v238, v124, s[46:47]
	v_cndmask_b32_e64 v123, v238, v123, s[46:47]
	v_cndmask_b32_e64 v122, v238, v122, s[46:47]
	s_and_b64 vcc, exec, s[48:49]
	s_mov_b64 s[22:23], -1
	s_cbranch_vccnz .LBB0_639
	s_mov_b64 s[22:23], 0
	global_store_dwordx4 v[198:199], v[122:125], off offset:16 sc1

.LBB0_641:
	v_mov_b32_e32 v206, v204
	v_mov_b32_e32 v207, v204
	v_lshlrev_b32_e32 v200, 16, v194
	v_and_b32_e32 v201, 0xffff0000, v194
	v_lshlrev_b32_e32 v194, 16, v195
	v_and_b32_e32 v195, 0xffff0000, v195
	v_pk_mul_f32 v[120:121], v[120:121], v[206:207]
	v_pk_mul_f32 v[118:119], v[118:119], v[204:205]
	v_pk_fma_f32 v[120:121], v[92:93], v[120:121], v[194:195]
	v_pk_fma_f32 v[118:119], v[90:91], v[118:119], v[200:201]
	v_cndmask_b32_e64 v121, v238, v121, s[46:47]
	v_cndmask_b32_e64 v120, v238, v120, s[46:47]
	v_cndmask_b32_e64 v119, v238, v119, s[46:47]
	v_cndmask_b32_e64 v118, v238, v118, s[46:47]
	s_and_b64 vcc, exec, s[48:49]
	s_mov_b64 s[22:23], -1
	s_cbranch_vccnz .LBB0_643
	s_mov_b64 s[22:23], 0
	global_store_dwordx4 v[198:199], v[118:121], off offset:512 sc1

.LBB0_648:
	v_readlane_b32 s0, v250, 15
	v_readlane_b32 s12, v250, 27
	v_readlane_b32 s13, v250, 28
	v_cvt_pk_bf16_f32 v194, v126, v127
	v_cvt_pk_bf16_f32 v195, v128, v129
	v_cvt_pk_bf16_f32 v196, v122, v123
	v_cvt_pk_bf16_f32 v197, v124, v125
	v_readlane_b32 s1, v250, 16
	s_nop 0
	v_lshl_add_u64 v[198:199], v[202:203], 1, s[12:13]
	v_readlane_b32 s2, v250, 17
	v_readlane_b32 s3, v250, 18
	v_readlane_b32 s4, v250, 19
	v_readlane_b32 s5, v250, 20
	v_readlane_b32 s6, v250, 21
	v_readlane_b32 s7, v250, 22
	v_readlane_b32 s8, v250, 23
	v_readlane_b32 s9, v250, 24
	v_readlane_b32 s10, v250, 25
	v_readlane_b32 s11, v250, 26
	v_readlane_b32 s14, v250, 29
	v_readlane_b32 s15, v250, 30
	global_store_dwordx4 v[198:199], v[194:197], off sc1
	s_nop 1
	v_cvt_pk_bf16_f32 v194, v118, v119
	v_cvt_pk_bf16_f32 v195, v120, v121
	v_cvt_pk_bf16_f32 v196, v114, v115
	v_cvt_pk_bf16_f32 v197, v116, v117
	global_store_dwordx4 v[198:199], v[194:197], off offset:256 sc1
.LBB0_649:
	ds_read_b32 v196, v64 offset:8320
	s_nop 0
	v_add3_u32 v194, s52, v248, 32
	v_ashrrev_i32_e32 v195, 31, v194
	v_lshlrev_b64 v[194:195], 10, v[194:195]
	v_lshlrev_b32_e32 v198, 16, v182
	v_and_b32_e32 v199, 0xffff0000, v182
	v_lshlrev_b32_e32 v182, 16, v183
	v_and_b32_e32 v183, 0xffff0000, v183
	s_waitcnt lgkmcnt(0)
	v_pk_mul_f32 v[112:113], v[112:113], v[196:197] op_sel_hi:[1,0]
	v_pk_mul_f32 v[110:111], v[110:111], v[196:197] op_sel_hi:[1,0]
	v_readlane_b32 s4, v250, 15
	v_lshl_add_u64 v[194:195], v[194:195], 0, v[226:227]
	v_pk_fma_f32 v[110:111], v[102:103], v[110:111], v[198:199]
	v_pk_fma_f32 v[112:113], v[104:105], v[112:113], v[182:183]
	v_readlane_b32 s16, v250, 27
	v_readlane_b32 s17, v250, 28
	v_cndmask_b32_e64 v113, v238, v113, s[46:47]
	v_cndmask_b32_e64 v112, v238, v112, s[46:47]
	v_cndmask_b32_e64 v111, v238, v111, s[46:47]
	v_cndmask_b32_e64 v110, v238, v110, s[46:47]
	s_mov_b64 s[0:1], -1
	s_and_b64 vcc, exec, s[48:49]
	v_lshl_add_u64 v[182:183], v[194:195], 2, s[16:17]
	v_readlane_b32 s5, v250, 16
	v_readlane_b32 s6, v250, 17
	v_readlane_b32 s7, v250, 18
	v_readlane_b32 s8, v250, 19
	v_readlane_b32 s9, v250, 20
	v_readlane_b32 s10, v250, 21
	v_readlane_b32 s11, v250, 22
	v_readlane_b32 s12, v250, 23
	v_readlane_b32 s13, v250, 24
	v_readlane_b32 s14, v250, 25
	v_readlane_b32 s15, v250, 26
	v_readlane_b32 s18, v250, 29
	v_readlane_b32 s19, v250, 30
	s_cbranch_vccnz .LBB0_651
	s_mov_b64 s[0:1], 0
	global_store_dwordx4 v[182:183], v[110:113], off sc1

.LBB0_653:
	v_mov_b32_e32 v197, v196
	v_mov_b32_e32 v200, v196
	v_mov_b32_e32 v201, v196
	v_lshlrev_b32_e32 v198, 16, v184
	v_and_b32_e32 v199, 0xffff0000, v184
	v_lshlrev_b32_e32 v184, 16, v185
	v_and_b32_e32 v185, 0xffff0000, v185
	v_pk_mul_f32 v[108:109], v[108:109], v[200:201]
	v_pk_mul_f32 v[106:107], v[106:107], v[196:197]
	v_pk_fma_f32 v[108:109], v[100:101], v[108:109], v[184:185]
	v_pk_fma_f32 v[106:107], v[98:99], v[106:107], v[198:199]
	v_cndmask_b32_e64 v109, v238, v109, s[46:47]
	v_cndmask_b32_e64 v108, v238, v108, s[46:47]
	v_cndmask_b32_e64 v107, v238, v107, s[46:47]
	v_cndmask_b32_e64 v106, v238, v106, s[46:47]
	s_and_b64 vcc, exec, s[48:49]
	s_mov_b64 s[0:1], -1
	s_cbranch_vccnz .LBB0_655
	s_mov_b64 s[0:1], 0
	global_store_dwordx4 v[182:183], v[106:109], off offset:16 sc1

.LBB0_657:
	v_mov_b32_e32 v198, v196
	v_mov_b32_e32 v199, v196
	v_lshlrev_b32_e32 v184, 16, v178
	v_and_b32_e32 v185, 0xffff0000, v178
	v_lshlrev_b32_e32 v178, 16, v179
	v_and_b32_e32 v179, 0xffff0000, v179
	v_pk_mul_f32 v[96:97], v[96:97], v[198:199]
	v_pk_mul_f32 v[94:95], v[94:95], v[196:197]
	v_pk_fma_f32 v[96:97], v[92:93], v[96:97], v[178:179]
	v_pk_fma_f32 v[94:95], v[90:91], v[94:95], v[184:185]
	v_cndmask_b32_e64 v97, v238, v97, s[46:47]
	v_cndmask_b32_e64 v96, v238, v96, s[46:47]
	v_cndmask_b32_e64 v95, v238, v95, s[46:47]
	v_cndmask_b32_e64 v94, v238, v94, s[46:47]
	s_and_b64 vcc, exec, s[48:49]
	s_mov_b64 s[0:1], -1
	s_cbranch_vccnz .LBB0_659
	s_mov_b64 s[0:1], 0
	global_store_dwordx4 v[182:183], v[94:97], off offset:512 sc1

.LBB0_664:
	v_readlane_b32 s0, v250, 15
	v_readlane_b32 s12, v250, 27
	v_readlane_b32 s13, v250, 28
	v_cvt_pk_bf16_f32 v178, v110, v111
	v_cvt_pk_bf16_f32 v179, v112, v113
	v_cvt_pk_bf16_f32 v180, v106, v107
	v_cvt_pk_bf16_f32 v181, v108, v109
	v_readlane_b32 s1, v250, 16
	s_nop 0
	v_lshl_add_u64 v[182:183], v[194:195], 1, s[12:13]
	v_readlane_b32 s2, v250, 17
	v_readlane_b32 s3, v250, 18
	v_readlane_b32 s4, v250, 19
	v_readlane_b32 s5, v250, 20
	v_readlane_b32 s6, v250, 21
	v_readlane_b32 s7, v250, 22
	v_readlane_b32 s8, v250, 23
	v_readlane_b32 s9, v250, 24
	v_readlane_b32 s10, v250, 25
	v_readlane_b32 s11, v250, 26
	v_readlane_b32 s14, v250, 29
	v_readlane_b32 s15, v250, 30
	global_store_dwordx4 v[182:183], v[178:181], off sc1
	s_nop 1
	v_cvt_pk_bf16_f32 v178, v94, v95
	v_cvt_pk_bf16_f32 v179, v96, v97
	v_cvt_pk_bf16_f32 v180, v86, v87
	v_cvt_pk_bf16_f32 v181, v88, v89
	global_store_dwordx4 v[182:183], v[178:181], off offset:256 sc1
.LBB0_665:
	ds_read_b32 v180, v64 offset:8384
	s_nop 0
	v_add3_u32 v178, s52, v248, 48
	v_ashrrev_i32_e32 v179, 31, v178
	v_lshlrev_b64 v[178:179], 10, v[178:179]
	v_lshlrev_b32_e32 v182, 16, v166
	v_and_b32_e32 v183, 0xffff0000, v166
	v_lshlrev_b32_e32 v166, 16, v167
	v_and_b32_e32 v167, 0xffff0000, v167
	s_waitcnt lgkmcnt(0)
	v_pk_mul_f32 v[80:81], v[80:81], v[180:181] op_sel_hi:[1,0]
	v_pk_mul_f32 v[78:79], v[78:79], v[180:181] op_sel_hi:[1,0]
	v_readlane_b32 s4, v250, 15
	v_lshl_add_u64 v[178:179], v[178:179], 0, v[226:227]
	v_pk_fma_f32 v[78:79], v[102:103], v[78:79], v[182:183]
	v_pk_fma_f32 v[80:81], v[104:105], v[80:81], v[166:167]
	v_readlane_b32 s16, v250, 27
	v_readlane_b32 s17, v250, 28
	v_cndmask_b32_e64 v81, v238, v81, s[46:47]
	v_cndmask_b32_e64 v80, v238, v80, s[46:47]
	v_cndmask_b32_e64 v79, v238, v79, s[46:47]
	v_cndmask_b32_e64 v78, v238, v78, s[46:47]
	s_mov_b64 s[0:1], -1
	s_and_b64 vcc, exec, s[48:49]
	v_lshl_add_u64 v[166:167], v[178:179], 2, s[16:17]
	v_readlane_b32 s5, v250, 16
	v_readlane_b32 s6, v250, 17
	v_readlane_b32 s7, v250, 18
	v_readlane_b32 s8, v250, 19
	v_readlane_b32 s9, v250, 20
	v_readlane_b32 s10, v250, 21
	v_readlane_b32 s11, v250, 22
	v_readlane_b32 s12, v250, 23
	v_readlane_b32 s13, v250, 24
	v_readlane_b32 s14, v250, 25
	v_readlane_b32 s15, v250, 26
	v_readlane_b32 s18, v250, 29
	v_readlane_b32 s19, v250, 30
	s_cbranch_vccnz .LBB0_667
	s_mov_b64 s[0:1], 0
	global_store_dwordx4 v[166:167], v[78:81], off sc1

.LBB0_669:
	v_mov_b32_e32 v181, v180
	v_mov_b32_e32 v184, v180
	v_mov_b32_e32 v185, v180
	v_lshlrev_b32_e32 v182, 16, v168
	v_and_b32_e32 v183, 0xffff0000, v168
	v_lshlrev_b32_e32 v168, 16, v169
	v_and_b32_e32 v169, 0xffff0000, v169
	v_pk_mul_f32 v[76:77], v[76:77], v[184:185]
	v_pk_mul_f32 v[74:75], v[74:75], v[180:181]
	v_pk_fma_f32 v[76:77], v[100:101], v[76:77], v[168:169]
	v_pk_fma_f32 v[74:75], v[98:99], v[74:75], v[182:183]
	v_cndmask_b32_e64 v77, v238, v77, s[46:47]
	v_cndmask_b32_e64 v76, v238, v76, s[46:47]
	v_cndmask_b32_e64 v75, v238, v75, s[46:47]
	v_cndmask_b32_e64 v74, v238, v74, s[46:47]
	s_and_b64 vcc, exec, s[48:49]
	s_mov_b64 s[0:1], -1
	s_cbranch_vccnz .LBB0_671
	s_mov_b64 s[0:1], 0
	global_store_dwordx4 v[166:167], v[74:77], off offset:16 sc1

.LBB0_673:
	v_mov_b32_e32 v182, v180
	v_mov_b32_e32 v183, v180
	v_lshlrev_b32_e32 v168, 16, v162
	v_and_b32_e32 v169, 0xffff0000, v162
	v_lshlrev_b32_e32 v162, 16, v163
	v_and_b32_e32 v163, 0xffff0000, v163
	v_pk_mul_f32 v[72:73], v[72:73], v[182:183]
	v_pk_mul_f32 v[70:71], v[70:71], v[180:181]
	v_pk_fma_f32 v[72:73], v[92:93], v[72:73], v[162:163]
	v_pk_fma_f32 v[70:71], v[90:91], v[70:71], v[168:169]
	v_cndmask_b32_e64 v73, v238, v73, s[46:47]
	v_cndmask_b32_e64 v72, v238, v72, s[46:47]
	v_cndmask_b32_e64 v71, v238, v71, s[46:47]
	v_cndmask_b32_e64 v70, v238, v70, s[46:47]
	s_and_b64 vcc, exec, s[48:49]
	s_mov_b64 s[0:1], -1
	s_cbranch_vccnz .LBB0_675
	s_mov_b64 s[0:1], 0
	global_store_dwordx4 v[166:167], v[70:73], off offset:512 sc1

.LBB0_680:
	v_readlane_b32 s0, v250, 15
	v_readlane_b32 s12, v250, 27
	v_readlane_b32 s13, v250, 28
	v_cvt_pk_bf16_f32 v162, v78, v79
	v_cvt_pk_bf16_f32 v163, v80, v81
	v_cvt_pk_bf16_f32 v164, v74, v75
	v_cvt_pk_bf16_f32 v165, v76, v77
	v_readlane_b32 s1, v250, 16
	s_nop 0
	v_lshl_add_u64 v[166:167], v[178:179], 1, s[12:13]
	v_readlane_b32 s2, v250, 17
	v_readlane_b32 s3, v250, 18
	v_readlane_b32 s4, v250, 19
	v_readlane_b32 s5, v250, 20
	v_readlane_b32 s6, v250, 21
	v_readlane_b32 s7, v250, 22
	v_readlane_b32 s8, v250, 23
	v_readlane_b32 s9, v250, 24
	v_readlane_b32 s10, v250, 25
	v_readlane_b32 s11, v250, 26
	v_readlane_b32 s14, v250, 29
	v_readlane_b32 s15, v250, 30
	global_store_dwordx4 v[166:167], v[162:165], off sc1
	s_nop 1
	v_cvt_pk_bf16_f32 v162, v70, v71
	v_cvt_pk_bf16_f32 v163, v72, v73
	v_cvt_pk_bf16_f32 v164, v66, v67
	v_cvt_pk_bf16_f32 v165, v68, v69
	global_store_dwordx4 v[166:167], v[162:165], off offset:256 sc1
.LBB0_681:
	ds_read_b32 v164, v64 offset:8704
	s_nop 0
	v_add_u32_e32 v162, 0x80, v228
	v_ashrrev_i32_e32 v163, 31, v162
	v_lshlrev_b64 v[162:163], 10, v[162:163]
	v_lshlrev_b32_e32 v166, 16, v190
	v_and_b32_e32 v167, 0xffff0000, v190
	v_lshlrev_b32_e32 v168, 16, v191
	v_and_b32_e32 v169, 0xffff0000, v191
	s_waitcnt lgkmcnt(0)
	v_pk_mul_f32 v[62:63], v[62:63], v[164:165] op_sel_hi:[1,0]
	v_pk_mul_f32 v[60:61], v[60:61], v[164:165] op_sel_hi:[1,0]
	v_readlane_b32 s4, v250, 15
	v_lshl_add_u64 v[162:163], v[162:163], 0, v[226:227]
	v_pk_fma_f32 v[60:61], v[102:103], v[60:61], v[166:167]
	v_pk_fma_f32 v[62:63], v[104:105], v[62:63], v[168:169]
	v_readlane_b32 s16, v250, 27
	v_readlane_b32 s17, v250, 28
	v_cndmask_b32_e64 v63, v238, v63, s[46:47]
	v_cndmask_b32_e64 v62, v238, v62, s[46:47]
	v_cndmask_b32_e64 v61, v238, v61, s[46:47]
	v_cndmask_b32_e64 v60, v238, v60, s[46:47]
	s_mov_b64 s[0:1], -1
	s_and_b64 vcc, exec, s[48:49]
	v_lshl_add_u64 v[166:167], v[162:163], 2, s[16:17]
	v_readlane_b32 s5, v250, 16
	v_readlane_b32 s6, v250, 17
	v_readlane_b32 s7, v250, 18
	v_readlane_b32 s8, v250, 19
	v_readlane_b32 s9, v250, 20
	v_readlane_b32 s10, v250, 21
	v_readlane_b32 s11, v250, 22
	v_readlane_b32 s12, v250, 23
	v_readlane_b32 s13, v250, 24
	v_readlane_b32 s14, v250, 25
	v_readlane_b32 s15, v250, 26
	v_readlane_b32 s18, v250, 29
	v_readlane_b32 s19, v250, 30
	s_cbranch_vccnz .LBB0_683
	s_mov_b64 s[0:1], 0
	global_store_dwordx4 v[166:167], v[60:63], off sc1

.LBB0_685:
	v_mov_b32_e32 v165, v164
	v_mov_b32_e32 v180, v164
	v_mov_b32_e32 v181, v164
	v_lshlrev_b32_e32 v168, 16, v192
	v_and_b32_e32 v169, 0xffff0000, v192
	v_lshlrev_b32_e32 v178, 16, v193
	v_and_b32_e32 v179, 0xffff0000, v193
	v_pk_mul_f32 v[58:59], v[58:59], v[180:181]
	v_pk_mul_f32 v[56:57], v[56:57], v[164:165]
	v_pk_fma_f32 v[58:59], v[100:101], v[58:59], v[178:179]
	v_pk_fma_f32 v[56:57], v[98:99], v[56:57], v[168:169]
	v_cndmask_b32_e64 v59, v238, v59, s[46:47]
	v_cndmask_b32_e64 v58, v238, v58, s[46:47]
	v_cndmask_b32_e64 v57, v238, v57, s[46:47]
	v_cndmask_b32_e64 v56, v238, v56, s[46:47]
	s_and_b64 vcc, exec, s[48:49]
	s_mov_b64 s[0:1], -1
	s_cbranch_vccnz .LBB0_687
	s_mov_b64 s[0:1], 0
	global_store_dwordx4 v[166:167], v[56:59], off offset:16 sc1

.LBB0_689:
	v_mov_b32_e32 v180, v164
	v_mov_b32_e32 v181, v164
	v_lshlrev_b32_e32 v168, 16, v186
	v_and_b32_e32 v169, 0xffff0000, v186
	v_lshlrev_b32_e32 v178, 16, v187
	v_and_b32_e32 v179, 0xffff0000, v187
	v_pk_mul_f32 v[54:55], v[54:55], v[180:181]
	v_pk_mul_f32 v[52:53], v[52:53], v[164:165]
	v_pk_fma_f32 v[54:55], v[92:93], v[54:55], v[178:179]
	v_pk_fma_f32 v[52:53], v[90:91], v[52:53], v[168:169]
	v_cndmask_b32_e64 v55, v238, v55, s[46:47]
	v_cndmask_b32_e64 v54, v238, v54, s[46:47]
	v_cndmask_b32_e64 v53, v238, v53, s[46:47]
	v_cndmask_b32_e64 v52, v238, v52, s[46:47]
	s_and_b64 vcc, exec, s[48:49]
	s_mov_b64 s[0:1], -1
	s_cbranch_vccnz .LBB0_691
	s_mov_b64 s[0:1], 0
	global_store_dwordx4 v[166:167], v[52:55], off offset:512 sc1

.LBB0_696:
	v_readlane_b32 s0, v250, 15
	v_readlane_b32 s12, v250, 27
	v_readlane_b32 s13, v250, 28
	v_cvt_pk_bf16_f32 v164, v60, v61
	v_cvt_pk_bf16_f32 v165, v62, v63
	v_cvt_pk_bf16_f32 v166, v56, v57
	v_cvt_pk_bf16_f32 v167, v58, v59
	v_readlane_b32 s1, v250, 16
	s_nop 0
	v_lshl_add_u64 v[168:169], v[162:163], 1, s[12:13]
	v_readlane_b32 s2, v250, 17
	v_readlane_b32 s3, v250, 18
	v_readlane_b32 s4, v250, 19
	v_readlane_b32 s5, v250, 20
	v_readlane_b32 s6, v250, 21
	v_readlane_b32 s7, v250, 22
	v_readlane_b32 s8, v250, 23
	v_readlane_b32 s9, v250, 24
	v_readlane_b32 s10, v250, 25
	v_readlane_b32 s11, v250, 26
	v_readlane_b32 s14, v250, 29
	v_readlane_b32 s15, v250, 30
	global_store_dwordx4 v[168:169], v[164:167], off sc1
	v_cvt_pk_bf16_f32 v162, v52, v53
	v_cvt_pk_bf16_f32 v163, v54, v55
	s_nop 1
	v_cvt_pk_bf16_f32 v164, v48, v49
	v_cvt_pk_bf16_f32 v165, v50, v51
	global_store_dwordx4 v[168:169], v[162:165], off offset:256 sc1
.LBB0_697:
	ds_read_b32 v164, v64 offset:8768
	s_nop 0
	v_add_u32_e32 v162, 0x90, v228
	v_ashrrev_i32_e32 v163, 31, v162
	v_lshlrev_b64 v[162:163], 10, v[162:163]
	v_lshlrev_b32_e32 v166, 16, v174
	v_and_b32_e32 v167, 0xffff0000, v174
	v_lshlrev_b32_e32 v168, 16, v175
	v_and_b32_e32 v169, 0xffff0000, v175
	s_waitcnt lgkmcnt(0)
	v_pk_mul_f32 v[46:47], v[46:47], v[164:165] op_sel_hi:[1,0]
	v_pk_mul_f32 v[44:45], v[44:45], v[164:165] op_sel_hi:[1,0]
	v_readlane_b32 s4, v250, 15
	v_lshl_add_u64 v[162:163], v[162:163], 0, v[226:227]
	v_pk_fma_f32 v[44:45], v[102:103], v[44:45], v[166:167]
	v_pk_fma_f32 v[46:47], v[104:105], v[46:47], v[168:169]
	v_readlane_b32 s16, v250, 27
	v_readlane_b32 s17, v250, 28
	v_cndmask_b32_e64 v47, v238, v47, s[46:47]
	v_cndmask_b32_e64 v46, v238, v46, s[46:47]
	v_cndmask_b32_e64 v45, v238, v45, s[46:47]
	v_cndmask_b32_e64 v44, v238, v44, s[46:47]
	s_mov_b64 s[0:1], -1
	s_and_b64 vcc, exec, s[48:49]
	v_lshl_add_u64 v[166:167], v[162:163], 2, s[16:17]
	v_readlane_b32 s5, v250, 16
	v_readlane_b32 s6, v250, 17
	v_readlane_b32 s7, v250, 18
	v_readlane_b32 s8, v250, 19
	v_readlane_b32 s9, v250, 20
	v_readlane_b32 s10, v250, 21
	v_readlane_b32 s11, v250, 22
	v_readlane_b32 s12, v250, 23
	v_readlane_b32 s13, v250, 24
	v_readlane_b32 s14, v250, 25
	v_readlane_b32 s15, v250, 26
	v_readlane_b32 s18, v250, 29
	v_readlane_b32 s19, v250, 30
	s_cbranch_vccnz .LBB0_699
	s_mov_b64 s[0:1], 0
	global_store_dwordx4 v[166:167], v[44:47], off sc1

.LBB0_701:
	v_mov_b32_e32 v165, v164
	v_lshlrev_b32_e32 v168, 16, v176
	v_and_b32_e32 v169, 0xffff0000, v176
	v_lshlrev_b32_e32 v174, 16, v177
	v_and_b32_e32 v175, 0xffff0000, v177
	v_mov_b32_e32 v176, v164
	v_mov_b32_e32 v177, v164
	v_pk_mul_f32 v[42:43], v[42:43], v[176:177]
	v_pk_mul_f32 v[40:41], v[40:41], v[164:165]
	v_pk_fma_f32 v[42:43], v[100:101], v[42:43], v[174:175]
	v_pk_fma_f32 v[40:41], v[98:99], v[40:41], v[168:169]
	v_cndmask_b32_e64 v43, v238, v43, s[46:47]
	v_cndmask_b32_e64 v42, v238, v42, s[46:47]
	v_cndmask_b32_e64 v41, v238, v41, s[46:47]
	v_cndmask_b32_e64 v40, v238, v40, s[46:47]
	s_and_b64 vcc, exec, s[48:49]
	s_mov_b64 s[0:1], -1
	s_cbranch_vccnz .LBB0_703
	s_mov_b64 s[0:1], 0
	global_store_dwordx4 v[166:167], v[40:43], off offset:16 sc1

.LBB0_705:
	v_mov_b32_e32 v174, v164
	v_mov_b32_e32 v175, v164
	v_lshlrev_b32_e32 v168, 16, v170
	v_and_b32_e32 v169, 0xffff0000, v170
	v_lshlrev_b32_e32 v170, 16, v171
	v_and_b32_e32 v171, 0xffff0000, v171
	v_pk_mul_f32 v[38:39], v[38:39], v[174:175]
	v_pk_mul_f32 v[36:37], v[36:37], v[164:165]
	v_pk_fma_f32 v[38:39], v[92:93], v[38:39], v[170:171]
	v_pk_fma_f32 v[36:37], v[90:91], v[36:37], v[168:169]
	v_cndmask_b32_e64 v39, v238, v39, s[46:47]
	v_cndmask_b32_e64 v38, v238, v38, s[46:47]
	v_cndmask_b32_e64 v37, v238, v37, s[46:47]
	v_cndmask_b32_e64 v36, v238, v36, s[46:47]
	s_and_b64 vcc, exec, s[48:49]
	s_mov_b64 s[0:1], -1
	s_cbranch_vccnz .LBB0_707
	s_mov_b64 s[0:1], 0
	global_store_dwordx4 v[166:167], v[36:39], off offset:512 sc1

.LBB0_712:
	v_readlane_b32 s0, v250, 15
	v_readlane_b32 s12, v250, 27
	v_readlane_b32 s13, v250, 28
	v_cvt_pk_bf16_f32 v164, v44, v45
	v_cvt_pk_bf16_f32 v165, v46, v47
	v_cvt_pk_bf16_f32 v166, v40, v41
	v_cvt_pk_bf16_f32 v167, v42, v43
	v_readlane_b32 s1, v250, 16
	s_nop 0
	v_lshl_add_u64 v[168:169], v[162:163], 1, s[12:13]
	v_readlane_b32 s2, v250, 17
	v_readlane_b32 s3, v250, 18
	v_readlane_b32 s4, v250, 19
	v_readlane_b32 s5, v250, 20
	v_readlane_b32 s6, v250, 21
	v_readlane_b32 s7, v250, 22
	v_readlane_b32 s8, v250, 23
	v_readlane_b32 s9, v250, 24
	v_readlane_b32 s10, v250, 25
	v_readlane_b32 s11, v250, 26
	v_readlane_b32 s14, v250, 29
	v_readlane_b32 s15, v250, 30
	global_store_dwordx4 v[168:169], v[164:167], off sc1
	v_cvt_pk_bf16_f32 v162, v36, v37
	v_cvt_pk_bf16_f32 v163, v38, v39
	s_nop 1
	v_cvt_pk_bf16_f32 v164, v32, v33
	v_cvt_pk_bf16_f32 v165, v34, v35
	global_store_dwordx4 v[168:169], v[162:165], off offset:256 sc1
.LBB0_713:
	ds_read_b32 v164, v64 offset:8832
	s_nop 0
	v_add_u32_e32 v162, 0xa0, v228
	v_ashrrev_i32_e32 v163, 31, v162
	v_lshlrev_b64 v[162:163], 10, v[162:163]
	v_lshlrev_b32_e32 v166, 16, v158
	v_and_b32_e32 v167, 0xffff0000, v158
	v_lshlrev_b32_e32 v158, 16, v159
	v_and_b32_e32 v159, 0xffff0000, v159
	s_waitcnt lgkmcnt(0)
	v_pk_mul_f32 v[30:31], v[30:31], v[164:165] op_sel_hi:[1,0]
	v_pk_mul_f32 v[28:29], v[28:29], v[164:165] op_sel_hi:[1,0]
	v_readlane_b32 s4, v250, 15
	v_lshl_add_u64 v[162:163], v[162:163], 0, v[226:227]
	v_pk_fma_f32 v[28:29], v[102:103], v[28:29], v[166:167]
	v_pk_fma_f32 v[30:31], v[104:105], v[30:31], v[158:159]
	v_readlane_b32 s16, v250, 27
	v_readlane_b32 s17, v250, 28
	v_cndmask_b32_e64 v31, v238, v31, s[46:47]
	v_cndmask_b32_e64 v30, v238, v30, s[46:47]
	v_cndmask_b32_e64 v29, v238, v29, s[46:47]
	v_cndmask_b32_e64 v28, v238, v28, s[46:47]
	s_mov_b64 s[0:1], -1
	s_and_b64 vcc, exec, s[48:49]
	v_lshl_add_u64 v[158:159], v[162:163], 2, s[16:17]
	v_readlane_b32 s5, v250, 16
	v_readlane_b32 s6, v250, 17
	v_readlane_b32 s7, v250, 18
	v_readlane_b32 s8, v250, 19
	v_readlane_b32 s9, v250, 20
	v_readlane_b32 s10, v250, 21
	v_readlane_b32 s11, v250, 22
	v_readlane_b32 s12, v250, 23
	v_readlane_b32 s13, v250, 24
	v_readlane_b32 s14, v250, 25
	v_readlane_b32 s15, v250, 26
	v_readlane_b32 s18, v250, 29
	v_readlane_b32 s19, v250, 30
	s_cbranch_vccnz .LBB0_715
	s_mov_b64 s[0:1], 0
	global_store_dwordx4 v[158:159], v[28:31], off sc1

.LBB0_717:
	v_mov_b32_e32 v165, v164
	v_mov_b32_e32 v168, v164
	v_mov_b32_e32 v169, v164
	v_lshlrev_b32_e32 v166, 16, v160
	v_and_b32_e32 v167, 0xffff0000, v160
	v_lshlrev_b32_e32 v160, 16, v161
	v_and_b32_e32 v161, 0xffff0000, v161
	v_pk_mul_f32 v[26:27], v[26:27], v[168:169]
	v_pk_mul_f32 v[24:25], v[24:25], v[164:165]
	v_pk_fma_f32 v[26:27], v[100:101], v[26:27], v[160:161]
	v_pk_fma_f32 v[24:25], v[98:99], v[24:25], v[166:167]
	v_cndmask_b32_e64 v27, v238, v27, s[46:47]
	v_cndmask_b32_e64 v26, v238, v26, s[46:47]
	v_cndmask_b32_e64 v25, v238, v25, s[46:47]
	v_cndmask_b32_e64 v24, v238, v24, s[46:47]
	s_and_b64 vcc, exec, s[48:49]
	s_mov_b64 s[0:1], -1
	s_cbranch_vccnz .LBB0_719
	s_mov_b64 s[0:1], 0
	global_store_dwordx4 v[158:159], v[24:27], off offset:16 sc1

.LBB0_721:
	v_mov_b32_e32 v166, v164
	v_mov_b32_e32 v167, v164
	v_lshlrev_b32_e32 v160, 16, v154
	v_and_b32_e32 v161, 0xffff0000, v154
	v_lshlrev_b32_e32 v154, 16, v155
	v_and_b32_e32 v155, 0xffff0000, v155
	v_pk_mul_f32 v[22:23], v[22:23], v[166:167]
	v_pk_mul_f32 v[20:21], v[20:21], v[164:165]
	v_pk_fma_f32 v[22:23], v[92:93], v[22:23], v[154:155]
	v_pk_fma_f32 v[20:21], v[90:91], v[20:21], v[160:161]
	v_cndmask_b32_e64 v23, v238, v23, s[46:47]
	v_cndmask_b32_e64 v22, v238, v22, s[46:47]
	v_cndmask_b32_e64 v21, v238, v21, s[46:47]
	v_cndmask_b32_e64 v20, v238, v20, s[46:47]
	s_and_b64 vcc, exec, s[48:49]
	s_mov_b64 s[0:1], -1
	s_cbranch_vccnz .LBB0_723
	s_mov_b64 s[0:1], 0
	global_store_dwordx4 v[158:159], v[20:23], off offset:512 sc1

.LBB0_728:
	v_readlane_b32 s0, v250, 15
	v_readlane_b32 s12, v250, 27
	v_readlane_b32 s13, v250, 28
	v_cvt_pk_bf16_f32 v154, v28, v29
	v_cvt_pk_bf16_f32 v155, v30, v31
	v_cvt_pk_bf16_f32 v156, v24, v25
	v_cvt_pk_bf16_f32 v157, v26, v27
	v_readlane_b32 s1, v250, 16
	s_nop 0
	v_lshl_add_u64 v[158:159], v[162:163], 1, s[12:13]
	v_readlane_b32 s2, v250, 17
	v_readlane_b32 s3, v250, 18
	v_readlane_b32 s4, v250, 19
	v_readlane_b32 s5, v250, 20
	v_readlane_b32 s6, v250, 21
	v_readlane_b32 s7, v250, 22
	v_readlane_b32 s8, v250, 23
	v_readlane_b32 s9, v250, 24
	v_readlane_b32 s10, v250, 25
	v_readlane_b32 s11, v250, 26
	v_readlane_b32 s14, v250, 29
	v_readlane_b32 s15, v250, 30
	global_store_dwordx4 v[158:159], v[154:157], off sc1
	s_nop 1
	v_cvt_pk_bf16_f32 v154, v20, v21
	v_cvt_pk_bf16_f32 v155, v22, v23
	v_cvt_pk_bf16_f32 v156, v16, v17
	v_cvt_pk_bf16_f32 v157, v18, v19
	global_store_dwordx4 v[158:159], v[154:157], off offset:256 sc1
.LBB0_729:
	ds_read_b32 v156, v64 offset:8896
	s_nop 0
	v_add_u32_e32 v154, 0xb0, v228
	v_ashrrev_i32_e32 v155, 31, v154
	v_lshlrev_b64 v[154:155], 10, v[154:155]
	v_lshlrev_b32_e32 v158, 16, v150
	v_and_b32_e32 v159, 0xffff0000, v150
	v_lshlrev_b32_e32 v150, 16, v151
	v_and_b32_e32 v151, 0xffff0000, v151
	s_waitcnt lgkmcnt(0)
	v_pk_mul_f32 v[14:15], v[14:15], v[156:157] op_sel_hi:[1,0]
	v_pk_mul_f32 v[12:13], v[12:13], v[156:157] op_sel_hi:[1,0]
	v_readlane_b32 s4, v250, 15
	v_lshl_add_u64 v[154:155], v[154:155], 0, v[226:227]
	v_pk_fma_f32 v[12:13], v[102:103], v[12:13], v[158:159]
	v_pk_fma_f32 v[14:15], v[104:105], v[14:15], v[150:151]
	v_readlane_b32 s16, v250, 27
	v_readlane_b32 s17, v250, 28
	v_cndmask_b32_e64 v15, v238, v15, s[46:47]
	v_cndmask_b32_e64 v14, v238, v14, s[46:47]
	v_cndmask_b32_e64 v13, v238, v13, s[46:47]
	v_cndmask_b32_e64 v12, v238, v12, s[46:47]
	s_mov_b64 s[0:1], -1
	s_and_b64 vcc, exec, s[48:49]
	v_lshl_add_u64 v[102:103], v[154:155], 2, s[16:17]
	v_readlane_b32 s5, v250, 16
	v_readlane_b32 s6, v250, 17
	v_readlane_b32 s7, v250, 18
	v_readlane_b32 s8, v250, 19
	v_readlane_b32 s9, v250, 20
	v_readlane_b32 s10, v250, 21
	v_readlane_b32 s11, v250, 22
	v_readlane_b32 s12, v250, 23
	v_readlane_b32 s13, v250, 24
	v_readlane_b32 s14, v250, 25
	v_readlane_b32 s15, v250, 26
	v_readlane_b32 s18, v250, 29
	v_readlane_b32 s19, v250, 30
	s_cbranch_vccnz .LBB0_731
	s_mov_b64 s[0:1], 0
	global_store_dwordx4 v[102:103], v[12:15], off sc1

.LBB0_733:
	v_mov_b32_e32 v157, v156
	v_lshlrev_b32_e32 v104, 16, v152
	v_and_b32_e32 v105, 0xffff0000, v152
	v_lshlrev_b32_e32 v150, 16, v153
	v_and_b32_e32 v151, 0xffff0000, v153
	v_mov_b32_e32 v152, v156
	v_mov_b32_e32 v153, v156
	v_pk_mul_f32 v[10:11], v[10:11], v[152:153]
	v_pk_mul_f32 v[8:9], v[8:9], v[156:157]
	v_pk_fma_f32 v[10:11], v[100:101], v[10:11], v[150:151]
	v_pk_fma_f32 v[8:9], v[98:99], v[8:9], v[104:105]
	v_cndmask_b32_e64 v11, v238, v11, s[46:47]
	v_cndmask_b32_e64 v10, v238, v10, s[46:47]
	v_cndmask_b32_e64 v9, v238, v9, s[46:47]
	v_cndmask_b32_e64 v8, v238, v8, s[46:47]
	s_and_b64 vcc, exec, s[48:49]
	s_mov_b64 s[0:1], -1
	s_cbranch_vccnz .LBB0_735
	s_mov_b64 s[0:1], 0
	global_store_dwordx4 v[102:103], v[8:11], off offset:16 sc1

.LBB0_737:
	v_mov_b32_e32 v104, v156
	v_mov_b32_e32 v105, v156
	v_lshlrev_b32_e32 v98, 16, v146
	v_and_b32_e32 v99, 0xffff0000, v146
	v_lshlrev_b32_e32 v100, 16, v147
	v_and_b32_e32 v101, 0xffff0000, v147
	v_pk_mul_f32 v[6:7], v[6:7], v[104:105]
	v_pk_mul_f32 v[4:5], v[4:5], v[156:157]
	v_pk_fma_f32 v[6:7], v[92:93], v[6:7], v[100:101]
	v_pk_fma_f32 v[4:5], v[90:91], v[4:5], v[98:99]
	v_cndmask_b32_e64 v7, v238, v7, s[46:47]
	v_cndmask_b32_e64 v6, v238, v6, s[46:47]
	v_cndmask_b32_e64 v5, v238, v5, s[46:47]
	v_cndmask_b32_e64 v4, v238, v4, s[46:47]
	s_and_b64 vcc, exec, s[48:49]
	s_mov_b64 s[0:1], -1
	s_cbranch_vccnz .LBB0_739
	s_mov_b64 s[0:1], 0
	global_store_dwordx4 v[102:103], v[4:7], off offset:512 sc1

.LBB0_744:
	v_readlane_b32 s0, v250, 15
	v_readlane_b32 s12, v250, 27
	v_readlane_b32 s13, v250, 28
	v_cvt_pk_bf16_f32 v82, v12, v13
	v_cvt_pk_bf16_f32 v83, v14, v15
	v_cvt_pk_bf16_f32 v84, v8, v9
	v_cvt_pk_bf16_f32 v85, v10, v11
	v_readlane_b32 s1, v250, 16
	s_nop 0
	v_lshl_add_u64 v[90:91], v[154:155], 1, s[12:13]
	v_readlane_b32 s2, v250, 17
	v_readlane_b32 s3, v250, 18
	v_readlane_b32 s4, v250, 19
	v_readlane_b32 s5, v250, 20
	v_readlane_b32 s6, v250, 21
	v_readlane_b32 s7, v250, 22
	v_readlane_b32 s8, v250, 23
	v_readlane_b32 s9, v250, 24
	v_readlane_b32 s10, v250, 25
	v_readlane_b32 s11, v250, 26
	v_readlane_b32 s14, v250, 29
	v_readlane_b32 s15, v250, 30
	global_store_dwordx4 v[90:91], v[82:85], off sc1
	s_nop 1
	v_cvt_pk_bf16_f32 v82, v4, v5
	v_cvt_pk_bf16_f32 v83, v6, v7
	v_cvt_pk_bf16_f32 v84, v0, v1
	v_cvt_pk_bf16_f32 v85, v2, v3
	global_store_dwordx4 v[90:91], v[82:85], off offset:256 sc1
.LBB0_745:
	s_and_b64 vcc, exec, s[50:51]
	s_cbranch_vccnz .LBB0_765
	v_mul_f32_e32 v64, v135, v135
	v_mul_f32_e32 v82, v137, v137
	v_fmac_f32_e32 v64, v134, v134
	v_fmac_f32_e32 v82, v136, v136
	v_add_f32_e32 v64, v64, v82
	v_mul_f32_e32 v82, v143, v143
	v_mul_f32_e32 v83, v145, v145
	v_fmac_f32_e32 v82, v142, v142
	v_fmac_f32_e32 v83, v144, v144
	v_add_f32_e32 v82, v82, v83
	v_add_f32_e32 v64, v64, v82
	v_mul_f32_e32 v82, v139, v139
	v_mul_f32_e32 v83, v141, v141
	v_fmac_f32_e32 v82, v138, v138
	v_fmac_f32_e32 v83, v140, v140
	v_add_f32_e32 v82, v82, v83
	v_add_f32_e32 v64, v82, v64
	v_mul_f32_e32 v82, v131, v131
	v_mul_f32_e32 v83, v133, v133
	v_fmac_f32_e32 v82, v130, v130
	v_fmac_f32_e32 v83, v132, v132
	v_add_f32_e32 v82, v82, v83
	v_add_f32_e32 v64, v82, v64
	ds_swizzle_b32 v82, v64 offset:swizzle(SWAP,16)
	s_waitcnt lgkmcnt(0)
	v_add_f32_e32 v64, v64, v82
	v_mov_b32_e32 v82, v64
	s_nop 1
	v_permlane32_swap_b32_e32 v64, v82
	s_and_saveexec_b64 s[0:1], s[42:43]
	s_lshl_b32 s3, s34, 10
	s_add_i32 s3, s53, s3
	v_add_u32_e32 v83, s3, v247
	v_add_f32_e32 v64, v64, v82
	ds_write_b32 v83, v64
	s_or_b64 exec, exec, s[0:1]
	v_mul_f32_e32 v64, v127, v127
	v_mul_f32_e32 v82, v129, v129
	v_fmac_f32_e32 v64, v126, v126
	v_fmac_f32_e32 v82, v128, v128
	v_add_f32_e32 v64, v64, v82
	v_mul_f32_e32 v82, v123, v123
	v_mul_f32_e32 v83, v125, v125
	v_fmac_f32_e32 v82, v122, v122
	v_fmac_f32_e32 v83, v124, v124
	v_add_f32_e32 v82, v82, v83
	v_add_f32_e32 v64, v64, v82
	v_mul_f32_e32 v82, v119, v119
	v_mul_f32_e32 v83, v121, v121
	v_fmac_f32_e32 v82, v118, v118
	v_fmac_f32_e32 v83, v120, v120
	v_add_f32_e32 v82, v82, v83
	v_add_f32_e32 v64, v82, v64
	v_mul_f32_e32 v82, v115, v115
	v_mul_f32_e32 v83, v117, v117
	v_fmac_f32_e32 v82, v114, v114
	v_fmac_f32_e32 v83, v116, v116
	v_add_f32_e32 v82, v82, v83
	v_add_f32_e32 v64, v82, v64
	ds_swizzle_b32 v82, v64 offset:swizzle(SWAP,16)
	s_waitcnt lgkmcnt(0)
	v_add_f32_e32 v64, v64, v82
	v_mov_b32_e32 v82, v64
	s_nop 1
	v_permlane32_swap_b32_e32 v64, v82
	s_and_saveexec_b64 s[0:1], s[42:43]
	s_lshl_b32 s3, s34, 10
	s_add_i32 s3, s53, s3
	v_add_u32_e32 v83, s3, v247
	v_add_f32_e32 v64, v64, v82
	ds_write_b32 v83, v64 offset:256
	s_or_b64 exec, exec, s[0:1]
	v_mul_f32_e32 v64, v111, v111
	v_mul_f32_e32 v82, v113, v113
	v_fmac_f32_e32 v64, v110, v110
	v_fmac_f32_e32 v82, v112, v112
	v_add_f32_e32 v64, v64, v82
	v_mul_f32_e32 v82, v107, v107
	v_mul_f32_e32 v83, v109, v109
	v_fmac_f32_e32 v82, v106, v106
	v_fmac_f32_e32 v83, v108, v108
	v_add_f32_e32 v82, v82, v83
	v_add_f32_e32 v64, v64, v82
	v_mul_f32_e32 v82, v95, v95
	v_mul_f32_e32 v83, v97, v97
	v_fmac_f32_e32 v82, v94, v94
	v_fmac_f32_e32 v83, v96, v96
	v_add_f32_e32 v82, v82, v83
	v_add_f32_e32 v64, v82, v64
	v_mul_f32_e32 v82, v87, v87
	v_mul_f32_e32 v83, v89, v89
	v_fmac_f32_e32 v82, v86, v86
	v_fmac_f32_e32 v83, v88, v88
	v_add_f32_e32 v82, v82, v83
	v_add_f32_e32 v64, v82, v64
	ds_swizzle_b32 v82, v64 offset:swizzle(SWAP,16)
	s_waitcnt lgkmcnt(0)
	v_add_f32_e32 v64, v64, v82
	v_mov_b32_e32 v82, v64
	s_nop 1
	v_permlane32_swap_b32_e32 v64, v82
	s_and_saveexec_b64 s[0:1], s[42:43]
	s_lshl_b32 s3, s34, 10
	s_add_i32 s3, s53, s3
	v_add_u32_e32 v83, s3, v247
	v_add_f32_e32 v64, v64, v82
	ds_write_b32 v83, v64 offset:512
	s_or_b64 exec, exec, s[0:1]
	v_mul_f32_e32 v64, v79, v79
	v_mul_f32_e32 v75, v75, v75
	v_fmac_f32_e32 v64, v78, v78
	v_mul_f32_e32 v78, v81, v81
	v_fmac_f32_e32 v75, v74, v74
	v_mul_f32_e32 v74, v77, v77
	v_mul_f32_e32 v71, v71, v71
	v_fmac_f32_e32 v78, v80, v80
	v_fmac_f32_e32 v74, v76, v76
	v_fmac_f32_e32 v71, v70, v70
	v_mul_f32_e32 v70, v73, v73
	v_mul_f32_e32 v67, v67, v67
	v_add_f32_e32 v64, v64, v78
	v_add_f32_e32 v74, v75, v74
	v_fmac_f32_e32 v70, v72, v72
	v_fmac_f32_e32 v67, v66, v66
	v_mul_f32_e32 v66, v69, v69
	v_add_f32_e32 v64, v64, v74
	v_add_f32_e32 v70, v71, v70
	v_fmac_f32_e32 v66, v68, v68
	v_add_f32_e32 v64, v70, v64
	v_add_f32_e32 v66, v67, v66
	v_add_f32_e32 v64, v66, v64
	ds_swizzle_b32 v66, v64 offset:swizzle(SWAP,16)
	s_waitcnt lgkmcnt(0)
	v_add_f32_e32 v64, v64, v66
	v_mov_b32_e32 v66, v64
	s_nop 1
	v_permlane32_swap_b32_e32 v64, v66
	s_and_saveexec_b64 s[0:1], s[42:43]
	s_lshl_b32 s3, s34, 10
	s_add_i32 s3, s53, s3
	v_add_u32_e32 v67, s3, v247
	v_add_f32_e32 v64, v64, v66
	ds_write_b32 v67, v64 offset:768
	s_or_b64 exec, exec, s[0:1]
	v_mul_f32_e32 v61, v61, v61
	v_mul_f32_e32 v57, v57, v57
	v_fmac_f32_e32 v61, v60, v60
	v_mul_f32_e32 v60, v63, v63
	v_fmac_f32_e32 v57, v56, v56
	v_mul_f32_e32 v56, v59, v59
	v_mul_f32_e32 v53, v53, v53
	v_fmac_f32_e32 v60, v62, v62
	v_fmac_f32_e32 v56, v58, v58
	v_fmac_f32_e32 v53, v52, v52
	v_mul_f32_e32 v52, v55, v55
	v_mul_f32_e32 v49, v49, v49
	v_add_f32_e32 v60, v61, v60
	v_add_f32_e32 v56, v57, v56
	v_fmac_f32_e32 v52, v54, v54
	v_fmac_f32_e32 v49, v48, v48
	v_mul_f32_e32 v48, v51, v51
	v_add_f32_e32 v56, v60, v56
	v_add_f32_e32 v52, v53, v52
	v_fmac_f32_e32 v48, v50, v50
	v_add_f32_e32 v52, v52, v56
	v_add_f32_e32 v48, v49, v48
	v_add_f32_e32 v48, v48, v52
	ds_swizzle_b32 v49, v48 offset:swizzle(SWAP,16)
	s_waitcnt lgkmcnt(0)
	v_add_f32_e32 v48, v48, v49
	v_mov_b32_e32 v49, v48
	s_nop 1
	v_permlane32_swap_b32_e32 v48, v49
	s_and_saveexec_b64 s[0:1], s[42:43]
	s_lshl_b32 s3, s34, 10
	s_add_i32 s3, s53, s3
	v_add_u32_e32 v50, s3, v247
	v_add_f32_e32 v48, v48, v49
	ds_write_b32 v50, v48 offset:2048
	s_or_b64 exec, exec, s[0:1]
	v_mul_f32_e32 v45, v45, v45
	v_mul_f32_e32 v41, v41, v41
	v_fmac_f32_e32 v45, v44, v44
	v_mul_f32_e32 v44, v47, v47
	v_fmac_f32_e32 v41, v40, v40
	v_mul_f32_e32 v40, v43, v43
	v_mul_f32_e32 v37, v37, v37
	v_fmac_f32_e32 v44, v46, v46
	v_fmac_f32_e32 v40, v42, v42
	v_fmac_f32_e32 v37, v36, v36
	v_mul_f32_e32 v36, v39, v39
	v_mul_f32_e32 v33, v33, v33
	v_add_f32_e32 v44, v45, v44
	v_add_f32_e32 v40, v41, v40
	v_fmac_f32_e32 v36, v38, v38
	v_fmac_f32_e32 v33, v32, v32
	v_mul_f32_e32 v32, v35, v35
	v_add_f32_e32 v40, v44, v40
	v_add_f32_e32 v36, v37, v36
	v_fmac_f32_e32 v32, v34, v34
	v_add_f32_e32 v36, v36, v40
	v_add_f32_e32 v32, v33, v32
	v_add_f32_e32 v32, v32, v36
	ds_swizzle_b32 v33, v32 offset:swizzle(SWAP,16)
	s_waitcnt lgkmcnt(0)
	v_add_f32_e32 v32, v32, v33
	v_mov_b32_e32 v33, v32
	s_nop 1
	v_permlane32_swap_b32_e32 v32, v33
	s_and_saveexec_b64 s[0:1], s[42:43]
	s_lshl_b32 s3, s34, 10
	s_add_i32 s3, s53, s3
	v_add_u32_e32 v34, s3, v247
	v_add_f32_e32 v32, v32, v33
	ds_write_b32 v34, v32 offset:2304
	s_or_b64 exec, exec, s[0:1]
	v_mul_f32_e32 v29, v29, v29
	v_mul_f32_e32 v25, v25, v25
	v_fmac_f32_e32 v29, v28, v28
	v_mul_f32_e32 v28, v31, v31
	v_fmac_f32_e32 v25, v24, v24
	v_mul_f32_e32 v24, v27, v27
	v_mul_f32_e32 v21, v21, v21
	v_fmac_f32_e32 v28, v30, v30
	v_fmac_f32_e32 v24, v26, v26
	v_fmac_f32_e32 v21, v20, v20
	v_mul_f32_e32 v20, v23, v23
	v_mul_f32_e32 v17, v17, v17
	v_add_f32_e32 v28, v29, v28
	v_add_f32_e32 v24, v25, v24
	v_fmac_f32_e32 v20, v22, v22
	v_fmac_f32_e32 v17, v16, v16
	v_mul_f32_e32 v16, v19, v19
	v_add_f32_e32 v24, v28, v24
	v_add_f32_e32 v20, v21, v20
	v_fmac_f32_e32 v16, v18, v18
	v_add_f32_e32 v20, v20, v24
	v_add_f32_e32 v16, v17, v16
	v_add_f32_e32 v16, v16, v20
	ds_swizzle_b32 v17, v16 offset:swizzle(SWAP,16)
	s_waitcnt lgkmcnt(0)
	v_add_f32_e32 v16, v16, v17
	v_mov_b32_e32 v17, v16
	s_nop 1
	v_permlane32_swap_b32_e32 v16, v17
	s_and_saveexec_b64 s[0:1], s[42:43]
	s_lshl_b32 s3, s34, 10
	s_add_i32 s3, s53, s3
	v_add_u32_e32 v18, s3, v247
	v_add_f32_e32 v16, v16, v17
	ds_write_b32 v18, v16 offset:2560
	s_or_b64 exec, exec, s[0:1]
	v_mul_f32_e32 v13, v13, v13
	v_mul_f32_e32 v9, v9, v9
	v_fmac_f32_e32 v13, v12, v12
	v_mul_f32_e32 v12, v15, v15
	v_fmac_f32_e32 v9, v8, v8
	v_mul_f32_e32 v8, v11, v11
	v_mul_f32_e32 v5, v5, v5
	v_fmac_f32_e32 v12, v14, v14
	v_fmac_f32_e32 v8, v10, v10
	v_fmac_f32_e32 v5, v4, v4
	v_mul_f32_e32 v4, v7, v7
	v_mul_f32_e32 v1, v1, v1
	v_add_f32_e32 v12, v13, v12
	v_add_f32_e32 v8, v9, v8
	v_fmac_f32_e32 v4, v6, v6
	v_fmac_f32_e32 v1, v0, v0
	v_mul_f32_e32 v0, v3, v3
	v_add_f32_e32 v8, v12, v8
	v_add_f32_e32 v4, v5, v4
	v_fmac_f32_e32 v0, v2, v2
	v_add_f32_e32 v4, v4, v8
	v_add_f32_e32 v0, v1, v0
	v_add_f32_e32 v0, v0, v4
	ds_swizzle_b32 v1, v0 offset:swizzle(SWAP,16)
	s_waitcnt lgkmcnt(0)
	v_add_f32_e32 v0, v0, v1
	v_mov_b32_e32 v1, v0
	s_nop 1
	v_permlane32_swap_b32_e32 v0, v1
	s_and_saveexec_b64 s[0:1], s[42:43]
	s_lshl_b32 s3, s34, 10
	s_add_i32 s53, s53, s3
	v_add_u32_e32 v2, s53, v247
	v_add_f32_e32 v0, v0, v1
	ds_write_b32 v2, v0 offset:2816
	s_or_b64 exec, exec, s[0:1]
	s_waitcnt lgkmcnt(0)
	s_barrier
	s_and_saveexec_b64 s[0:1], s[44:45]
	s_cbranch_execz .LBB0_764
	v_lshl_add_u32 v0, v244, 4, 0
	ds_read_b128 v[0:3], v0
	s_ashr_i32 s41, s40, 31
	s_waitcnt lgkmcnt(0)
	v_mov_b32_e32 v4, v1
	v_mov_b32_e32 v5, v2
	v_mov_b32_e32 v1, v3
	v_pk_add_f32 v[0:1], v[4:5], v[0:1]
	s_nop 0
	v_add_f32_e32 v2, v0, v1
	v_add_u32_e32 v0, s52, v244
	v_ashrrev_i32_e32 v1, 31, v0
	v_lshl_add_u64 v[0:1], v[0:1], 4, s[76:77]
	v_lshl_add_u64 v[0:1], s[40:41], 2, v[0:1]
	global_store_dword v[0:1], v2, off sc1

.LBB0_818:
	s_or_b64 exec, exec, s[0:1]
	s_waitcnt vmcnt(9)
	v_ashrrev_i32_e32 v35, 8, v50
	s_waitcnt vmcnt(1)
	v_lshlrev_b32_e32 v0, 14, v35
	v_lshlrev_b32_sdwa v1, v236, v50 dst_sel:DWORD dst_unused:UNUSED_PAD src0_sel:DWORD src1_sel:BYTE_0
	v_add3_u32 v34, 0, v0, v1
	s_waitcnt lgkmcnt(0)
	s_barrier
	ds_read_u16 v0, v34
	ds_read_u16 v1, v34 offset:16384
	ds_read_u16 v2, v34 offset:16896
	v_lshlrev_b32_e32 v35, 15, v35
	v_lshlrev_b32_sdwa v87, v246, v50 dst_sel:DWORD dst_unused:UNUSED_PAD src0_sel:DWORD src1_sel:BYTE_0
	s_waitcnt lgkmcnt(2)
	v_lshlrev_b32_e32 v97, 16, v0
	ds_read_u16 v0, v34 offset:512
	ds_read_u16 v3, v34 offset:17408
	v_fma_f32 v97, v53, v97, v86
	s_waitcnt lgkmcnt(3)
	v_lshlrev_b32_e32 v1, 16, v1
	s_waitcnt lgkmcnt(2)
	v_lshlrev_b32_e32 v2, 16, v2
	s_waitcnt lgkmcnt(1)
	v_lshlrev_b32_e32 v96, 16, v0
	ds_read_u16 v0, v34 offset:1024
	s_waitcnt vmcnt(0)
	ds_read_u16 v4, v34 offset:17920
	v_fmac_f32_e32 v97, v54, v96
	v_fma_f32 v96, v53, v96, v86
	ds_read_u16 v5, v34 offset:18432
	s_waitcnt lgkmcnt(2)
	v_lshlrev_b32_e32 v95, 16, v0
	ds_read_u16 v0, v34 offset:1536
	v_fmac_f32_e32 v97, v55, v95
	v_fmac_f32_e32 v96, v54, v95
	ds_read_u16 v6, v34 offset:18944
	v_fma_f32 v95, v53, v95, v86
	s_waitcnt lgkmcnt(1)
	v_lshlrev_b32_e32 v94, 16, v0
	ds_read_u16 v0, v34 offset:2048
	v_fmac_f32_e32 v97, v56, v94
	ds_read_u16 v7, v34 offset:19456
	v_fmac_f32_e32 v96, v55, v94
	v_fmac_f32_e32 v95, v54, v94
	s_waitcnt lgkmcnt(1)
	v_lshlrev_b32_e32 v93, 16, v0
	ds_read_u16 v0, v34 offset:2560
	ds_read_u16 v9, v34 offset:19968
	v_fma_f32 v94, v53, v94, v86
	v_fmac_f32_e32 v97, v57, v93
	v_fmac_f32_e32 v96, v56, v93
	s_waitcnt lgkmcnt(1)
	v_lshlrev_b32_e32 v92, 16, v0
	ds_read_u16 v0, v34 offset:3072
	ds_read_u16 v10, v34 offset:20480
	v_fmac_f32_e32 v95, v55, v93
	v_fmac_f32_e32 v94, v54, v93
	v_fma_f32 v93, v53, v93, v86
	s_waitcnt lgkmcnt(1)
	v_lshlrev_b32_e32 v91, 16, v0
	ds_read_u16 v0, v34 offset:3584
	ds_read_u16 v11, v34 offset:20992
	v_fmac_f32_e32 v97, v58, v92
	v_fmac_f32_e32 v96, v57, v92
	ds_read_u16 v12, v34 offset:21504
	s_waitcnt lgkmcnt(2)
	v_lshlrev_b32_e32 v90, 16, v0
	ds_read_u16 v0, v34 offset:4096
	v_fmac_f32_e32 v95, v56, v92
	v_fmac_f32_e32 v94, v55, v92
	ds_read_u16 v13, v34 offset:22016
	v_fmac_f32_e32 v93, v54, v92
	s_waitcnt lgkmcnt(1)
	v_lshlrev_b32_e32 v89, 16, v0
	ds_read_u16 v0, v34 offset:4608
	v_fma_f32 v92, v53, v92, v86
	ds_read_u16 v14, v34 offset:22528
	v_fmac_f32_e32 v97, v59, v91
	v_fmac_f32_e32 v96, v58, v91
	s_waitcnt lgkmcnt(1)
	v_lshlrev_b32_e32 v88, 16, v0
	ds_read_u16 v0, v34 offset:5120
	ds_read_u16 v15, v34 offset:23040
	v_fmac_f32_e32 v95, v57, v91
	v_fmac_f32_e32 v94, v56, v91
	v_fmac_f32_e32 v93, v55, v91
	s_waitcnt lgkmcnt(1)
	v_lshlrev_b32_e32 v64, 16, v0
	ds_read_u16 v0, v34 offset:5632
	ds_read_u16 v16, v34 offset:23552
	v_fmac_f32_e32 v92, v54, v91
	v_fma_f32 v91, v53, v91, v86
	v_fmac_f32_e32 v97, v60, v90
	s_waitcnt lgkmcnt(1)
	v_lshlrev_b32_e32 v52, 16, v0
	ds_read_u16 v0, v34 offset:6144
	ds_read_u16 v18, v34 offset:24064
	v_fmac_f32_e32 v96, v59, v90
	v_fmac_f32_e32 v95, v58, v90
	ds_read_u16 v19, v34 offset:24576
	s_waitcnt lgkmcnt(2)
	v_lshlrev_b32_e32 v51, 16, v0
	ds_read_u16 v0, v34 offset:6656
	v_fmac_f32_e32 v94, v57, v90
	v_fmac_f32_e32 v93, v56, v90
	ds_read_u16 v20, v34 offset:25088
	v_fmac_f32_e32 v92, v55, v90
	s_waitcnt lgkmcnt(1)
	v_lshlrev_b32_e32 v49, 16, v0
	ds_read_u16 v0, v34 offset:7168
	v_fmac_f32_e32 v91, v54, v90
	ds_read_u16 v21, v34 offset:25600
	v_fma_f32 v90, v53, v90, v86
	v_fmac_f32_e32 v97, v61, v89
	s_waitcnt lgkmcnt(1)
	v_lshlrev_b32_e32 v48, 16, v0
	ds_read_u16 v0, v34 offset:7680
	ds_read_u16 v22, v34 offset:26112
	v_fmac_f32_e32 v96, v60, v89
	v_fmac_f32_e32 v95, v59, v89
	v_fmac_f32_e32 v94, v58, v89
	s_waitcnt lgkmcnt(1)
	v_lshlrev_b32_e32 v47, 16, v0
	ds_read_u16 v0, v34 offset:8192
	ds_read_u16 v23, v34 offset:26624
	v_fmac_f32_e32 v93, v57, v89
	v_fmac_f32_e32 v92, v56, v89
	v_fmac_f32_e32 v91, v55, v89
	s_waitcnt lgkmcnt(1)
	v_lshlrev_b32_e32 v46, 16, v0
	ds_read_u16 v0, v34 offset:8704
	ds_read_u16 v24, v34 offset:27136
	v_fmac_f32_e32 v90, v54, v89
	v_fma_f32 v89, v53, v89, v86
	ds_read_u16 v25, v34 offset:27648
	s_waitcnt lgkmcnt(2)
	v_lshlrev_b32_e32 v45, 16, v0
	ds_read_u16 v0, v34 offset:9216
	v_fmac_f32_e32 v97, v62, v88
	v_fmac_f32_e32 v96, v61, v88
	ds_read_u16 v27, v34 offset:28160
	v_fmac_f32_e32 v95, v60, v88
	s_waitcnt lgkmcnt(1)
	v_lshlrev_b32_e32 v44, 16, v0
	ds_read_u16 v0, v34 offset:9728
	v_fmac_f32_e32 v94, v59, v88
	ds_read_u16 v28, v34 offset:28672
	v_fmac_f32_e32 v93, v58, v88
	v_fmac_f32_e32 v92, v57, v88
	s_waitcnt lgkmcnt(1)
	v_lshlrev_b32_e32 v43, 16, v0
	ds_read_u16 v0, v34 offset:10240
	ds_read_u16 v29, v34 offset:29184
	v_fmac_f32_e32 v91, v56, v88
	v_fmac_f32_e32 v90, v55, v88
	v_fmac_f32_e32 v89, v54, v88
	s_waitcnt lgkmcnt(1)
	v_lshlrev_b32_e32 v42, 16, v0
	ds_read_u16 v0, v34 offset:10752
	ds_read_u16 v30, v34 offset:29696
	v_fma_f32 v88, v53, v88, v86
	v_fmac_f32_e32 v97, v63, v64
	v_fmac_f32_e32 v96, v62, v64
	s_waitcnt lgkmcnt(1)
	v_lshlrev_b32_e32 v41, 16, v0
	ds_read_u16 v0, v34 offset:11264
	ds_read_u16 v31, v34 offset:30208
	v_fmac_f32_e32 v95, v61, v64
	v_fmac_f32_e32 v94, v60, v64
	v_fmac_f32_e32 v93, v59, v64
	s_waitcnt lgkmcnt(1)
	v_lshlrev_b32_e32 v40, 16, v0
	ds_read_u16 v0, v34 offset:11776
	v_fmac_f32_e32 v92, v58, v64
	v_fmac_f32_e32 v91, v57, v64
	v_fmac_f32_e32 v90, v56, v64
	v_fmac_f32_e32 v89, v55, v64
	s_waitcnt lgkmcnt(0)
	v_lshlrev_b32_e32 v39, 16, v0
	ds_read_u16 v0, v34 offset:12288
	v_fmac_f32_e32 v88, v54, v64
	v_fma_f32 v64, v53, v64, v86
	v_fmac_f32_e32 v97, v66, v52
	v_fmac_f32_e32 v96, v63, v52
	s_waitcnt lgkmcnt(0)
	v_lshlrev_b32_e32 v38, 16, v0
	ds_read_u16 v0, v34 offset:12800
	v_fmac_f32_e32 v95, v62, v52
	v_fmac_f32_e32 v94, v61, v52
	v_fmac_f32_e32 v93, v60, v52
	v_fmac_f32_e32 v92, v59, v52
	s_waitcnt lgkmcnt(0)
	v_lshlrev_b32_e32 v37, 16, v0
	ds_read_u16 v0, v34 offset:13312
	v_fmac_f32_e32 v91, v58, v52
	v_fmac_f32_e32 v90, v57, v52
	v_fmac_f32_e32 v89, v56, v52
	v_fmac_f32_e32 v88, v55, v52
	s_waitcnt lgkmcnt(0)
	v_lshlrev_b32_e32 v36, 16, v0
	ds_read_u16 v0, v34 offset:13824
	v_fmac_f32_e32 v64, v54, v52
	v_fma_f32 v52, v53, v52, v86
	v_fmac_f32_e32 v97, v67, v51
	v_fmac_f32_e32 v96, v66, v51
	s_waitcnt lgkmcnt(0)
	v_lshlrev_b32_e32 v33, 16, v0
	ds_read_u16 v0, v34 offset:14336
	ds_read_u16 v32, v34 offset:30720
	v_fmac_f32_e32 v95, v63, v51
	v_fmac_f32_e32 v94, v62, v51
	v_fmac_f32_e32 v93, v61, v51
	v_fmac_f32_e32 v92, v60, v51
	v_fmac_f32_e32 v91, v59, v51
	v_fmac_f32_e32 v90, v58, v51
	v_fmac_f32_e32 v89, v57, v51
	v_fmac_f32_e32 v88, v56, v51
	v_fmac_f32_e32 v64, v55, v51
	v_fmac_f32_e32 v52, v54, v51
	v_fma_f32 v51, v53, v51, v86
	v_fmac_f32_e32 v97, v68, v49
	v_fmac_f32_e32 v96, v67, v49
	v_fmac_f32_e32 v95, v66, v49
	v_fmac_f32_e32 v94, v63, v49
	v_fmac_f32_e32 v93, v62, v49
	v_fmac_f32_e32 v92, v61, v49
	v_fmac_f32_e32 v91, v60, v49
	v_fmac_f32_e32 v90, v59, v49
	v_fmac_f32_e32 v89, v58, v49
	v_fmac_f32_e32 v88, v57, v49
	v_fmac_f32_e32 v64, v56, v49
	v_fmac_f32_e32 v52, v55, v49
	v_fmac_f32_e32 v51, v54, v49
	v_fma_f32 v49, v53, v49, v86
	v_fmac_f32_e32 v97, v69, v48
	v_fmac_f32_e32 v96, v68, v48
	v_fmac_f32_e32 v95, v67, v48
	v_fmac_f32_e32 v94, v66, v48
	v_fmac_f32_e32 v93, v63, v48
	v_fmac_f32_e32 v92, v62, v48
	v_fmac_f32_e32 v91, v61, v48
	v_fmac_f32_e32 v90, v60, v48
	v_fmac_f32_e32 v89, v59, v48
	v_fmac_f32_e32 v88, v58, v48
	v_fmac_f32_e32 v64, v57, v48
	v_fmac_f32_e32 v52, v56, v48
	v_fmac_f32_e32 v51, v55, v48
	v_fmac_f32_e32 v49, v54, v48
	v_fma_f32 v48, v53, v48, v86
	s_waitcnt lgkmcnt(1)
	v_lshlrev_b32_e32 v26, 16, v0
	ds_read_u16 v0, v34 offset:14848
	v_fmac_f32_e32 v97, v70, v47
	v_fmac_f32_e32 v96, v69, v47
	v_fmac_f32_e32 v95, v68, v47
	v_fmac_f32_e32 v94, v67, v47
	v_fmac_f32_e32 v93, v66, v47
	v_fmac_f32_e32 v92, v63, v47
	v_fmac_f32_e32 v91, v62, v47
	v_fmac_f32_e32 v90, v61, v47
	v_fmac_f32_e32 v89, v60, v47
	v_fmac_f32_e32 v88, v59, v47
	v_fmac_f32_e32 v64, v58, v47
	v_fmac_f32_e32 v52, v57, v47
	v_fmac_f32_e32 v51, v56, v47
	v_fmac_f32_e32 v49, v55, v47
	v_fmac_f32_e32 v48, v54, v47
	v_fma_f32 v47, v53, v47, v86
	v_fmac_f32_e32 v97, v71, v46
	v_fmac_f32_e32 v96, v70, v46
	v_fmac_f32_e32 v95, v69, v46
	v_fmac_f32_e32 v94, v68, v46
	v_fmac_f32_e32 v93, v67, v46
	v_fmac_f32_e32 v92, v66, v46
	v_fmac_f32_e32 v91, v63, v46
	v_fmac_f32_e32 v90, v62, v46
	v_fmac_f32_e32 v89, v61, v46
	v_fmac_f32_e32 v88, v60, v46
	v_fmac_f32_e32 v64, v59, v46
	v_fmac_f32_e32 v52, v58, v46
	v_fmac_f32_e32 v51, v57, v46
	v_fmac_f32_e32 v49, v56, v46
	v_fmac_f32_e32 v48, v55, v46
	v_fmac_f32_e32 v47, v54, v46
	v_fma_f32 v46, v53, v46, v86
	v_fmac_f32_e32 v97, v72, v45
	v_fmac_f32_e32 v96, v71, v45
	v_fmac_f32_e32 v95, v70, v45
	v_fmac_f32_e32 v94, v69, v45
	v_fmac_f32_e32 v93, v68, v45
	v_fmac_f32_e32 v92, v67, v45
	v_fmac_f32_e32 v91, v66, v45
	v_fmac_f32_e32 v90, v63, v45
	v_fmac_f32_e32 v89, v62, v45
	v_fmac_f32_e32 v88, v61, v45
	v_fmac_f32_e32 v64, v60, v45
	v_fmac_f32_e32 v52, v59, v45
	v_fmac_f32_e32 v51, v58, v45
	v_fmac_f32_e32 v49, v57, v45
	v_fmac_f32_e32 v48, v56, v45
	v_fmac_f32_e32 v47, v55, v45
	v_fmac_f32_e32 v46, v54, v45
	v_fma_f32 v45, v53, v45, v86
	v_fmac_f32_e32 v97, v73, v44
	v_fmac_f32_e32 v96, v72, v44
	v_fmac_f32_e32 v95, v71, v44
	v_fmac_f32_e32 v94, v70, v44
	v_fmac_f32_e32 v93, v69, v44
	v_fmac_f32_e32 v92, v68, v44
	v_fmac_f32_e32 v91, v67, v44
	v_fmac_f32_e32 v90, v66, v44
	v_fmac_f32_e32 v89, v63, v44
	v_fmac_f32_e32 v88, v62, v44
	v_fmac_f32_e32 v64, v61, v44
	v_fmac_f32_e32 v52, v60, v44
	v_fmac_f32_e32 v51, v59, v44
	v_fmac_f32_e32 v49, v58, v44
	v_fmac_f32_e32 v48, v57, v44
	v_fmac_f32_e32 v47, v56, v44
	v_fmac_f32_e32 v46, v55, v44
	v_fmac_f32_e32 v45, v54, v44
	v_fma_f32 v44, v53, v44, v86
	v_fmac_f32_e32 v97, v74, v43
	v_fmac_f32_e32 v96, v73, v43
	v_fmac_f32_e32 v95, v72, v43
	v_fmac_f32_e32 v94, v71, v43
	v_fmac_f32_e32 v93, v70, v43
	v_fmac_f32_e32 v92, v69, v43
	v_fmac_f32_e32 v91, v68, v43
	v_fmac_f32_e32 v90, v67, v43
	v_fmac_f32_e32 v89, v66, v43
	v_fmac_f32_e32 v88, v63, v43
	v_fmac_f32_e32 v64, v62, v43
	v_fmac_f32_e32 v52, v61, v43
	v_fmac_f32_e32 v51, v60, v43
	v_fmac_f32_e32 v49, v59, v43
	v_fmac_f32_e32 v48, v58, v43
	v_fmac_f32_e32 v47, v57, v43
	v_fmac_f32_e32 v46, v56, v43
	v_fmac_f32_e32 v45, v55, v43
	v_fmac_f32_e32 v44, v54, v43
	v_fma_f32 v43, v53, v43, v86
	s_waitcnt lgkmcnt(0)
	v_lshlrev_b32_e32 v17, 16, v0
	ds_read_u16 v0, v34 offset:15360
	v_fmac_f32_e32 v97, v75, v42
	v_fmac_f32_e32 v96, v74, v42
	v_fmac_f32_e32 v95, v73, v42
	v_fmac_f32_e32 v94, v72, v42
	v_fmac_f32_e32 v93, v71, v42
	v_fmac_f32_e32 v92, v70, v42
	v_fmac_f32_e32 v91, v69, v42
	v_fmac_f32_e32 v90, v68, v42
	v_fmac_f32_e32 v89, v67, v42
	v_fmac_f32_e32 v88, v66, v42
	v_fmac_f32_e32 v64, v63, v42
	v_fmac_f32_e32 v52, v62, v42
	v_fmac_f32_e32 v51, v61, v42
	v_fmac_f32_e32 v49, v60, v42
	v_fmac_f32_e32 v48, v59, v42
	v_fmac_f32_e32 v47, v58, v42
	v_fmac_f32_e32 v46, v57, v42
	v_fmac_f32_e32 v45, v56, v42
	v_fmac_f32_e32 v44, v55, v42
	v_fmac_f32_e32 v43, v54, v42
	v_fma_f32 v42, v53, v42, v86
	v_fmac_f32_e32 v97, v76, v41
	v_fmac_f32_e32 v96, v75, v41
	v_fmac_f32_e32 v95, v74, v41
	v_fmac_f32_e32 v94, v73, v41
	v_fmac_f32_e32 v93, v72, v41
	v_fmac_f32_e32 v92, v71, v41
	v_fmac_f32_e32 v91, v70, v41
	v_fmac_f32_e32 v90, v69, v41
	v_fmac_f32_e32 v89, v68, v41
	v_fmac_f32_e32 v88, v67, v41
	v_fmac_f32_e32 v64, v66, v41
	v_fmac_f32_e32 v52, v63, v41
	v_fmac_f32_e32 v51, v62, v41
	v_fmac_f32_e32 v49, v61, v41
	v_fmac_f32_e32 v48, v60, v41
	v_fmac_f32_e32 v47, v59, v41
	v_fmac_f32_e32 v46, v58, v41
	v_fmac_f32_e32 v45, v57, v41
	v_fmac_f32_e32 v44, v56, v41
	v_fmac_f32_e32 v43, v55, v41
	v_fmac_f32_e32 v42, v54, v41
	v_fma_f32 v41, v53, v41, v86
	v_fmac_f32_e32 v97, v77, v40
	v_fmac_f32_e32 v96, v76, v40
	v_fmac_f32_e32 v95, v75, v40
	v_fmac_f32_e32 v94, v74, v40
	v_fmac_f32_e32 v93, v73, v40
	v_fmac_f32_e32 v92, v72, v40
	v_fmac_f32_e32 v91, v71, v40
	v_fmac_f32_e32 v90, v70, v40
	v_fmac_f32_e32 v89, v69, v40
	v_fmac_f32_e32 v88, v68, v40
	v_fmac_f32_e32 v64, v67, v40
	v_fmac_f32_e32 v52, v66, v40
	v_fmac_f32_e32 v51, v63, v40
	v_fmac_f32_e32 v49, v62, v40
	v_fmac_f32_e32 v48, v61, v40
	v_fmac_f32_e32 v47, v60, v40
	v_fmac_f32_e32 v46, v59, v40
	v_fmac_f32_e32 v45, v58, v40
	v_fmac_f32_e32 v44, v57, v40
	v_fmac_f32_e32 v43, v56, v40
	v_fmac_f32_e32 v42, v55, v40
	v_fmac_f32_e32 v41, v54, v40
	v_fma_f32 v40, v53, v40, v86
	v_fmac_f32_e32 v97, v78, v39
	v_fmac_f32_e32 v96, v77, v39
	v_fmac_f32_e32 v95, v76, v39
	v_fmac_f32_e32 v94, v75, v39
	v_fmac_f32_e32 v93, v74, v39
	v_fmac_f32_e32 v92, v73, v39
	v_fmac_f32_e32 v91, v72, v39
	v_fmac_f32_e32 v90, v71, v39
	v_fmac_f32_e32 v89, v70, v39
	v_fmac_f32_e32 v88, v69, v39
	v_fmac_f32_e32 v64, v68, v39
	v_fmac_f32_e32 v52, v67, v39
	v_fmac_f32_e32 v51, v66, v39
	v_fmac_f32_e32 v49, v63, v39
	v_fmac_f32_e32 v48, v62, v39
	v_fmac_f32_e32 v47, v61, v39
	v_fmac_f32_e32 v46, v60, v39
	v_fmac_f32_e32 v45, v59, v39
	v_fmac_f32_e32 v44, v58, v39
	v_fmac_f32_e32 v43, v57, v39
	v_fmac_f32_e32 v42, v56, v39
	v_fmac_f32_e32 v41, v55, v39
	v_fmac_f32_e32 v40, v54, v39
	v_fma_f32 v39, v53, v39, v86
	v_fmac_f32_e32 v97, v79, v38
	v_fmac_f32_e32 v96, v78, v38
	v_fmac_f32_e32 v95, v77, v38
	v_fmac_f32_e32 v94, v76, v38
	v_fmac_f32_e32 v93, v75, v38
	v_fmac_f32_e32 v92, v74, v38
	v_fmac_f32_e32 v91, v73, v38
	v_fmac_f32_e32 v90, v72, v38
	v_fmac_f32_e32 v89, v71, v38
	v_fmac_f32_e32 v88, v70, v38
	v_fmac_f32_e32 v64, v69, v38
	v_fmac_f32_e32 v52, v68, v38
	v_fmac_f32_e32 v51, v67, v38
	v_fmac_f32_e32 v49, v66, v38
	v_fmac_f32_e32 v48, v63, v38
	v_fmac_f32_e32 v47, v62, v38
	v_fmac_f32_e32 v46, v61, v38
	v_fmac_f32_e32 v45, v60, v38
	v_fmac_f32_e32 v44, v59, v38
	v_fmac_f32_e32 v43, v58, v38
	v_fmac_f32_e32 v42, v57, v38
	v_fmac_f32_e32 v41, v56, v38
	v_fmac_f32_e32 v40, v55, v38
	v_fmac_f32_e32 v39, v54, v38
	v_fma_f32 v38, v53, v38, v86
	s_waitcnt lgkmcnt(0)
	v_lshlrev_b32_e32 v8, 16, v0
	ds_read_u16 v0, v34 offset:15872
	v_fmac_f32_e32 v97, v80, v37
	v_fmac_f32_e32 v96, v79, v37
	v_fmac_f32_e32 v95, v78, v37
	v_fmac_f32_e32 v94, v77, v37
	v_fmac_f32_e32 v93, v76, v37
	v_fmac_f32_e32 v92, v75, v37
	v_fmac_f32_e32 v91, v74, v37
	v_fmac_f32_e32 v90, v73, v37
	v_fmac_f32_e32 v89, v72, v37
	v_fmac_f32_e32 v88, v71, v37
	v_fmac_f32_e32 v64, v70, v37
	v_fmac_f32_e32 v52, v69, v37
	v_fmac_f32_e32 v51, v68, v37
	v_fmac_f32_e32 v49, v67, v37
	v_fmac_f32_e32 v48, v66, v37
	v_fmac_f32_e32 v47, v63, v37
	v_fmac_f32_e32 v46, v62, v37
	v_fmac_f32_e32 v45, v61, v37
	v_fmac_f32_e32 v44, v60, v37
	v_fmac_f32_e32 v43, v59, v37
	v_fmac_f32_e32 v42, v58, v37
	v_fmac_f32_e32 v41, v57, v37
	v_fmac_f32_e32 v40, v56, v37
	v_fmac_f32_e32 v39, v55, v37
	v_fmac_f32_e32 v38, v54, v37
	v_fma_f32 v37, v53, v37, v86
	v_fmac_f32_e32 v97, v81, v36
	v_fmac_f32_e32 v96, v80, v36
	v_fmac_f32_e32 v95, v79, v36
	v_fmac_f32_e32 v94, v78, v36
	v_fmac_f32_e32 v93, v77, v36
	v_fmac_f32_e32 v92, v76, v36
	v_fmac_f32_e32 v91, v75, v36
	v_fmac_f32_e32 v90, v74, v36
	v_fmac_f32_e32 v89, v73, v36
	v_fmac_f32_e32 v88, v72, v36
	v_fmac_f32_e32 v64, v71, v36
	v_fmac_f32_e32 v52, v70, v36
	v_fmac_f32_e32 v51, v69, v36
	v_fmac_f32_e32 v49, v68, v36
	v_fmac_f32_e32 v48, v67, v36
	v_fmac_f32_e32 v47, v66, v36
	v_fmac_f32_e32 v46, v63, v36
	v_fmac_f32_e32 v45, v62, v36
	v_fmac_f32_e32 v44, v61, v36
	v_fmac_f32_e32 v43, v60, v36
	v_fmac_f32_e32 v42, v59, v36
	v_fmac_f32_e32 v41, v58, v36
	v_fmac_f32_e32 v40, v57, v36
	v_fmac_f32_e32 v39, v56, v36
	v_fmac_f32_e32 v38, v55, v36
	v_fmac_f32_e32 v37, v54, v36
	v_fma_f32 v36, v53, v36, v86
	v_fmac_f32_e32 v97, v82, v33
	v_fmac_f32_e32 v96, v81, v33
	v_fmac_f32_e32 v95, v80, v33
	v_fmac_f32_e32 v94, v79, v33
	v_fmac_f32_e32 v93, v78, v33
	v_fmac_f32_e32 v92, v77, v33
	v_fmac_f32_e32 v91, v76, v33
	v_fmac_f32_e32 v90, v75, v33
	v_fmac_f32_e32 v89, v74, v33
	v_fmac_f32_e32 v88, v73, v33
	v_fmac_f32_e32 v64, v72, v33
	v_fmac_f32_e32 v52, v71, v33
	v_fmac_f32_e32 v51, v70, v33
	v_fmac_f32_e32 v49, v69, v33
	v_fmac_f32_e32 v48, v68, v33
	v_fmac_f32_e32 v47, v67, v33
	v_fmac_f32_e32 v46, v66, v33
	v_fmac_f32_e32 v45, v63, v33
	v_fmac_f32_e32 v44, v62, v33
	v_fmac_f32_e32 v43, v61, v33
	v_fmac_f32_e32 v42, v60, v33
	v_fmac_f32_e32 v41, v59, v33
	v_fmac_f32_e32 v40, v58, v33
	v_fmac_f32_e32 v39, v57, v33
	v_fmac_f32_e32 v38, v56, v33
	v_fmac_f32_e32 v37, v55, v33
	v_fmac_f32_e32 v36, v54, v33
	v_fma_f32 v33, v53, v33, v86
	v_fmac_f32_e32 v97, v83, v26
	v_fmac_f32_e32 v96, v82, v26
	v_fmac_f32_e32 v95, v81, v26
	v_fmac_f32_e32 v94, v80, v26
	v_fmac_f32_e32 v93, v79, v26
	v_fmac_f32_e32 v92, v78, v26
	v_fmac_f32_e32 v91, v77, v26
	v_fmac_f32_e32 v90, v76, v26
	v_fmac_f32_e32 v89, v75, v26
	v_fmac_f32_e32 v88, v74, v26
	v_fmac_f32_e32 v64, v73, v26
	v_fmac_f32_e32 v52, v72, v26
	v_fmac_f32_e32 v51, v71, v26
	v_fmac_f32_e32 v49, v70, v26
	v_fmac_f32_e32 v48, v69, v26
	v_fmac_f32_e32 v47, v68, v26
	v_fmac_f32_e32 v46, v67, v26
	v_fmac_f32_e32 v45, v66, v26
	v_fmac_f32_e32 v44, v63, v26
	v_fmac_f32_e32 v43, v62, v26
	v_fmac_f32_e32 v42, v61, v26
	v_fmac_f32_e32 v41, v60, v26
	v_fmac_f32_e32 v40, v59, v26
	v_fmac_f32_e32 v39, v58, v26
	v_fmac_f32_e32 v38, v57, v26
	v_fmac_f32_e32 v37, v56, v26
	v_fmac_f32_e32 v36, v55, v26
	v_fmac_f32_e32 v33, v54, v26
	v_fma_f32 v26, v53, v26, v86
	v_fmac_f32_e32 v97, v84, v17
	v_fmac_f32_e32 v96, v83, v17
	v_fmac_f32_e32 v95, v82, v17
	v_fmac_f32_e32 v94, v81, v17
	v_fmac_f32_e32 v93, v80, v17
	v_fmac_f32_e32 v92, v79, v17
	v_fmac_f32_e32 v91, v78, v17
	v_fmac_f32_e32 v90, v77, v17
	v_fmac_f32_e32 v89, v76, v17
	v_fmac_f32_e32 v88, v75, v17
	v_fmac_f32_e32 v64, v74, v17
	v_fmac_f32_e32 v52, v73, v17
	v_fmac_f32_e32 v51, v72, v17
	v_fmac_f32_e32 v49, v71, v17
	v_fmac_f32_e32 v48, v70, v17
	v_fmac_f32_e32 v47, v69, v17
	v_fmac_f32_e32 v46, v68, v17
	v_fmac_f32_e32 v45, v67, v17
	v_fmac_f32_e32 v44, v66, v17
	v_fmac_f32_e32 v43, v63, v17
	v_fmac_f32_e32 v42, v62, v17
	v_fmac_f32_e32 v41, v61, v17
	v_fmac_f32_e32 v40, v60, v17
	v_fmac_f32_e32 v39, v59, v17
	v_fmac_f32_e32 v38, v58, v17
	v_fmac_f32_e32 v37, v57, v17
	v_fmac_f32_e32 v36, v56, v17
	v_fmac_f32_e32 v33, v55, v17
	v_fmac_f32_e32 v26, v54, v17
	v_fma_f32 v17, v53, v17, v86
	s_waitcnt lgkmcnt(0)
	v_lshlrev_b32_e32 v0, 16, v0
	v_fmac_f32_e32 v97, v85, v8
	v_fmac_f32_e32 v96, v84, v8
	v_fmac_f32_e32 v95, v83, v8
	v_fmac_f32_e32 v94, v82, v8
	v_fmac_f32_e32 v93, v81, v8
	v_fmac_f32_e32 v92, v80, v8
	v_fmac_f32_e32 v91, v79, v8
	v_fmac_f32_e32 v90, v78, v8
	v_fmac_f32_e32 v89, v77, v8
	v_fmac_f32_e32 v88, v76, v8
	v_fmac_f32_e32 v64, v75, v8
	v_fmac_f32_e32 v52, v74, v8
	v_fmac_f32_e32 v51, v73, v8
	v_fmac_f32_e32 v49, v72, v8
	v_fmac_f32_e32 v48, v71, v8
	v_fmac_f32_e32 v47, v70, v8
	v_fmac_f32_e32 v46, v69, v8
	v_fmac_f32_e32 v45, v68, v8
	v_fmac_f32_e32 v44, v67, v8
	v_fmac_f32_e32 v43, v66, v8
	v_fmac_f32_e32 v42, v63, v8
	v_fmac_f32_e32 v41, v62, v8
	v_fmac_f32_e32 v40, v61, v8
	v_fmac_f32_e32 v39, v60, v8
	v_fmac_f32_e32 v38, v59, v8
	v_fmac_f32_e32 v37, v58, v8
	v_fmac_f32_e32 v36, v57, v8
	v_fmac_f32_e32 v33, v56, v8
	v_fmac_f32_e32 v26, v55, v8
	v_fmac_f32_e32 v17, v54, v8
	v_fma_f32 v8, v53, v8, v86
	v_fmac_f32_e32 v96, v85, v0
	v_fmac_f32_e32 v95, v84, v0
	v_fmac_f32_e32 v94, v83, v0
	v_fmac_f32_e32 v93, v82, v0
	v_fmac_f32_e32 v92, v81, v0
	v_fmac_f32_e32 v91, v80, v0
	v_fmac_f32_e32 v90, v79, v0
	v_fmac_f32_e32 v89, v78, v0
	v_fmac_f32_e32 v88, v77, v0
	v_fmac_f32_e32 v64, v76, v0
	v_fmac_f32_e32 v52, v75, v0
	v_fmac_f32_e32 v51, v74, v0
	v_fmac_f32_e32 v49, v73, v0
	v_fmac_f32_e32 v48, v72, v0
	v_fmac_f32_e32 v47, v71, v0
	v_fmac_f32_e32 v46, v70, v0
	v_fmac_f32_e32 v45, v69, v0
	v_fmac_f32_e32 v44, v68, v0
	v_fmac_f32_e32 v43, v67, v0
	v_fmac_f32_e32 v42, v66, v0
	v_fmac_f32_e32 v41, v63, v0
	v_fmac_f32_e32 v40, v62, v0
	v_fmac_f32_e32 v39, v61, v0
	v_fmac_f32_e32 v38, v60, v0
	v_fmac_f32_e32 v37, v59, v0
	v_fmac_f32_e32 v36, v58, v0
	v_fmac_f32_e32 v33, v57, v0
	v_fmac_f32_e32 v26, v56, v0
	v_fmac_f32_e32 v17, v55, v0
	v_fmac_f32_e32 v8, v54, v0
	v_fma_f32 v0, v53, v0, v86
	v_fmac_f32_e32 v0, v54, v1
	v_lshlrev_b32_e32 v3, 16, v3
	v_fmac_f32_e32 v0, v55, v2
	v_lshlrev_b32_e32 v4, 16, v4
	v_fmac_f32_e32 v0, v56, v3
	v_lshlrev_b32_e32 v5, 16, v5
	v_fmac_f32_e32 v8, v55, v1
	v_fmac_f32_e32 v0, v57, v4
	v_lshlrev_b32_e32 v6, 16, v6
	v_fmac_f32_e32 v17, v56, v1
	v_fmac_f32_e32 v8, v56, v2
	v_fmac_f32_e32 v0, v58, v5
	v_lshlrev_b32_e32 v7, 16, v7
	v_fmac_f32_e32 v26, v57, v1
	v_fmac_f32_e32 v17, v57, v2
	v_fmac_f32_e32 v8, v57, v3
	v_fmac_f32_e32 v0, v59, v6
	v_lshlrev_b32_e32 v9, 16, v9
	v_fmac_f32_e32 v36, v59, v1
	v_fmac_f32_e32 v33, v58, v1
	v_fmac_f32_e32 v26, v58, v2
	v_fmac_f32_e32 v17, v58, v3
	v_fmac_f32_e32 v8, v58, v4
	v_fmac_f32_e32 v0, v60, v7
	v_lshlrev_b32_e32 v10, 16, v10
	v_fmac_f32_e32 v37, v60, v1
	v_fmac_f32_e32 v36, v60, v2
	v_fmac_f32_e32 v33, v59, v2
	v_fmac_f32_e32 v26, v59, v3
	v_fmac_f32_e32 v17, v59, v4
	v_fmac_f32_e32 v8, v59, v5
	v_fmac_f32_e32 v0, v61, v9
	v_lshlrev_b32_e32 v11, 16, v11
	v_fmac_f32_e32 v37, v61, v2
	v_fmac_f32_e32 v36, v61, v3
	v_fmac_f32_e32 v33, v60, v3
	v_fmac_f32_e32 v26, v60, v4
	v_fmac_f32_e32 v17, v60, v5
	v_fmac_f32_e32 v8, v60, v6
	v_fmac_f32_e32 v0, v62, v10
	v_lshlrev_b32_e32 v12, 16, v12
	v_fmac_f32_e32 v38, v61, v1
	v_fmac_f32_e32 v37, v62, v3
	v_fmac_f32_e32 v36, v62, v4
	v_fmac_f32_e32 v33, v61, v4
	v_fmac_f32_e32 v26, v61, v5
	v_fmac_f32_e32 v17, v61, v6
	v_fmac_f32_e32 v8, v61, v7
	v_fmac_f32_e32 v0, v63, v11
	v_lshlrev_b32_e32 v13, 16, v13
	v_fmac_f32_e32 v42, v67, v1
	v_fmac_f32_e32 v39, v62, v1
	v_fmac_f32_e32 v38, v62, v2
	v_fmac_f32_e32 v37, v63, v4
	v_fmac_f32_e32 v36, v63, v5
	v_fmac_f32_e32 v33, v62, v5
	v_fmac_f32_e32 v26, v62, v6
	v_fmac_f32_e32 v17, v62, v7
	v_fmac_f32_e32 v8, v62, v9
	v_fmac_f32_e32 v0, v66, v12
	v_lshlrev_b32_e32 v14, 16, v14
	v_fmac_f32_e32 v43, v68, v1
	v_fmac_f32_e32 v42, v68, v2
	v_fmac_f32_e32 v40, v63, v1
	v_fmac_f32_e32 v39, v63, v2
	v_fmac_f32_e32 v38, v63, v3
	v_fmac_f32_e32 v37, v66, v5
	v_fmac_f32_e32 v36, v66, v6
	v_fmac_f32_e32 v33, v63, v6
	v_fmac_f32_e32 v26, v63, v7
	v_fmac_f32_e32 v17, v63, v9
	v_fmac_f32_e32 v8, v63, v10
	v_fmac_f32_e32 v0, v67, v13
	v_lshlrev_b32_e32 v15, 16, v15
	v_fmac_f32_e32 v43, v69, v2
	v_fmac_f32_e32 v42, v69, v3
	v_fmac_f32_e32 v41, v66, v1
	v_fmac_f32_e32 v40, v66, v2
	v_fmac_f32_e32 v39, v66, v3
	v_fmac_f32_e32 v38, v66, v4
	v_fmac_f32_e32 v37, v67, v6
	v_fmac_f32_e32 v36, v67, v7
	v_fmac_f32_e32 v33, v66, v7
	v_fmac_f32_e32 v26, v66, v9
	v_fmac_f32_e32 v17, v66, v10
	v_fmac_f32_e32 v8, v66, v11
	v_fmac_f32_e32 v0, v68, v14
	v_lshlrev_b32_e32 v16, 16, v16
	v_fmac_f32_e32 v43, v70, v3
	v_fmac_f32_e32 v42, v70, v4
	v_fmac_f32_e32 v41, v67, v2
	v_fmac_f32_e32 v40, v67, v3
	v_fmac_f32_e32 v39, v67, v4
	v_fmac_f32_e32 v38, v67, v5
	v_fmac_f32_e32 v37, v68, v7
	v_fmac_f32_e32 v36, v68, v9
	v_fmac_f32_e32 v33, v67, v9
	v_fmac_f32_e32 v26, v67, v10
	v_fmac_f32_e32 v17, v67, v11
	v_fmac_f32_e32 v8, v67, v12
	v_fmac_f32_e32 v0, v69, v15
	v_lshlrev_b32_e32 v18, 16, v18
	v_fmac_f32_e32 v43, v71, v4
	v_fmac_f32_e32 v42, v71, v5
	v_fmac_f32_e32 v41, v68, v3
	v_fmac_f32_e32 v40, v68, v4
	v_fmac_f32_e32 v39, v68, v5
	v_fmac_f32_e32 v38, v68, v6
	v_fmac_f32_e32 v37, v69, v9
	v_fmac_f32_e32 v36, v69, v10
	v_fmac_f32_e32 v33, v68, v10
	v_fmac_f32_e32 v26, v68, v11
	v_fmac_f32_e32 v17, v68, v12
	v_fmac_f32_e32 v8, v68, v13
	v_fmac_f32_e32 v0, v70, v16
	v_lshlrev_b32_e32 v19, 16, v19
	v_fmac_f32_e32 v46, v71, v1
	v_fmac_f32_e32 v44, v69, v1
	v_fmac_f32_e32 v43, v72, v5
	v_fmac_f32_e32 v42, v72, v6
	v_fmac_f32_e32 v41, v69, v4
	v_fmac_f32_e32 v40, v69, v5
	v_fmac_f32_e32 v39, v69, v6
	v_fmac_f32_e32 v38, v69, v7
	v_fmac_f32_e32 v37, v70, v10
	v_fmac_f32_e32 v36, v70, v11
	v_fmac_f32_e32 v33, v69, v11
	v_fmac_f32_e32 v26, v69, v12
	v_fmac_f32_e32 v17, v69, v13
	v_fmac_f32_e32 v8, v69, v14
	v_fmac_f32_e32 v0, v71, v18
	v_lshlrev_b32_e32 v20, 16, v20
	v_fmac_f32_e32 v47, v72, v1
	v_fmac_f32_e32 v46, v72, v2
	v_fmac_f32_e32 v45, v70, v1
	v_fmac_f32_e32 v44, v70, v2
	v_fmac_f32_e32 v43, v73, v6
	v_fmac_f32_e32 v42, v73, v7
	v_fmac_f32_e32 v41, v70, v5
	v_fmac_f32_e32 v40, v70, v6
	v_fmac_f32_e32 v39, v70, v7
	v_fmac_f32_e32 v38, v70, v9
	v_fmac_f32_e32 v37, v71, v11
	v_fmac_f32_e32 v36, v71, v12
	v_fmac_f32_e32 v33, v70, v12
	v_fmac_f32_e32 v26, v70, v13
	v_fmac_f32_e32 v17, v70, v14
	v_fmac_f32_e32 v8, v70, v15
	v_fmac_f32_e32 v0, v72, v19
	v_lshlrev_b32_e32 v21, 16, v21
	v_fmac_f32_e32 v48, v73, v1
	v_fmac_f32_e32 v47, v73, v2
	v_fmac_f32_e32 v46, v73, v3
	v_fmac_f32_e32 v45, v71, v2
	v_fmac_f32_e32 v44, v71, v3
	v_fmac_f32_e32 v43, v74, v7
	v_fmac_f32_e32 v42, v74, v9
	v_fmac_f32_e32 v41, v71, v6
	v_fmac_f32_e32 v40, v71, v7
	v_fmac_f32_e32 v39, v71, v9
	v_fmac_f32_e32 v38, v71, v10
	v_fmac_f32_e32 v37, v72, v12
	v_fmac_f32_e32 v36, v72, v13
	v_fmac_f32_e32 v33, v71, v13
	v_fmac_f32_e32 v26, v71, v14
	v_fmac_f32_e32 v17, v71, v15
	v_fmac_f32_e32 v8, v71, v16
	v_fmac_f32_e32 v0, v73, v20
	v_lshlrev_b32_e32 v22, 16, v22
	v_fmac_f32_e32 v49, v74, v1
	v_fmac_f32_e32 v48, v74, v2
	v_fmac_f32_e32 v47, v74, v3
	v_fmac_f32_e32 v46, v74, v4
	v_fmac_f32_e32 v45, v72, v3
	v_fmac_f32_e32 v44, v72, v4
	v_fmac_f32_e32 v43, v75, v9
	v_fmac_f32_e32 v42, v75, v10
	v_fmac_f32_e32 v41, v72, v7
	v_fmac_f32_e32 v40, v72, v9
	v_fmac_f32_e32 v39, v72, v10
	v_fmac_f32_e32 v38, v72, v11
	v_fmac_f32_e32 v37, v73, v13
	v_fmac_f32_e32 v36, v73, v14
	v_fmac_f32_e32 v33, v72, v14
	v_fmac_f32_e32 v26, v72, v15
	v_fmac_f32_e32 v17, v72, v16
	v_fmac_f32_e32 v8, v72, v18
	v_fmac_f32_e32 v0, v74, v21
	v_lshlrev_b32_e32 v23, 16, v23
	v_fmac_f32_e32 v51, v75, v1
	v_fmac_f32_e32 v49, v75, v2
	v_fmac_f32_e32 v48, v75, v3
	v_fmac_f32_e32 v47, v75, v4
	v_fmac_f32_e32 v46, v75, v5
	v_fmac_f32_e32 v45, v73, v4
	v_fmac_f32_e32 v44, v73, v5
	v_fmac_f32_e32 v43, v76, v10
	v_fmac_f32_e32 v42, v76, v11
	v_fmac_f32_e32 v41, v73, v9
	v_fmac_f32_e32 v40, v73, v10
	v_fmac_f32_e32 v39, v73, v11
	v_fmac_f32_e32 v38, v73, v12
	v_fmac_f32_e32 v37, v74, v14
	v_fmac_f32_e32 v36, v74, v15
	v_fmac_f32_e32 v33, v73, v15
	v_fmac_f32_e32 v26, v73, v16
	v_fmac_f32_e32 v17, v73, v18
	v_fmac_f32_e32 v8, v73, v19
	v_fmac_f32_e32 v0, v75, v22
	v_lshlrev_b32_e32 v24, 16, v24
	v_fmac_f32_e32 v52, v76, v1
	v_fmac_f32_e32 v51, v76, v2
	v_fmac_f32_e32 v49, v76, v3
	v_fmac_f32_e32 v48, v76, v4
	v_fmac_f32_e32 v47, v76, v5
	v_fmac_f32_e32 v46, v76, v6
	v_fmac_f32_e32 v45, v74, v5
	v_fmac_f32_e32 v44, v74, v6
	v_fmac_f32_e32 v43, v77, v11
	v_fmac_f32_e32 v42, v77, v12
	v_fmac_f32_e32 v41, v74, v10
	v_fmac_f32_e32 v40, v74, v11
	v_fmac_f32_e32 v39, v74, v12
	v_fmac_f32_e32 v38, v74, v13
	v_fmac_f32_e32 v37, v75, v15
	v_fmac_f32_e32 v36, v75, v16
	v_fmac_f32_e32 v33, v74, v16
	v_fmac_f32_e32 v26, v74, v18
	v_fmac_f32_e32 v17, v74, v19
	v_fmac_f32_e32 v8, v74, v20
	v_fmac_f32_e32 v0, v76, v23
	v_lshlrev_b32_e32 v25, 16, v25
	v_fmac_f32_e32 v64, v77, v1
	v_fmac_f32_e32 v52, v77, v2
	v_fmac_f32_e32 v51, v77, v3
	v_fmac_f32_e32 v49, v77, v4
	v_fmac_f32_e32 v48, v77, v5
	v_fmac_f32_e32 v47, v77, v6
	v_fmac_f32_e32 v46, v77, v7
	v_fmac_f32_e32 v45, v75, v6
	v_fmac_f32_e32 v44, v75, v7
	v_fmac_f32_e32 v43, v78, v12
	v_fmac_f32_e32 v42, v78, v13
	v_fmac_f32_e32 v41, v75, v11
	v_fmac_f32_e32 v40, v75, v12
	v_fmac_f32_e32 v39, v75, v13
	v_fmac_f32_e32 v38, v75, v14
	v_fmac_f32_e32 v37, v76, v16
	v_fmac_f32_e32 v36, v76, v18
	v_fmac_f32_e32 v33, v75, v18
	v_fmac_f32_e32 v26, v75, v19
	v_fmac_f32_e32 v17, v75, v20
	v_fmac_f32_e32 v8, v75, v21
	v_fmac_f32_e32 v0, v77, v24
	v_lshlrev_b32_e32 v27, 16, v27
	v_fmac_f32_e32 v88, v78, v1
	v_fmac_f32_e32 v64, v78, v2
	v_fmac_f32_e32 v52, v78, v3
	v_fmac_f32_e32 v51, v78, v4
	v_fmac_f32_e32 v49, v78, v5
	v_fmac_f32_e32 v48, v78, v6
	v_fmac_f32_e32 v47, v78, v7
	v_fmac_f32_e32 v46, v78, v9
	v_fmac_f32_e32 v45, v76, v7
	v_fmac_f32_e32 v44, v76, v9
	v_fmac_f32_e32 v43, v79, v13
	v_fmac_f32_e32 v42, v79, v14
	v_fmac_f32_e32 v41, v76, v12
	v_fmac_f32_e32 v40, v76, v13
	v_fmac_f32_e32 v39, v76, v14
	v_fmac_f32_e32 v38, v76, v15
	v_fmac_f32_e32 v37, v77, v18
	v_fmac_f32_e32 v36, v77, v19
	v_fmac_f32_e32 v33, v76, v19
	v_fmac_f32_e32 v26, v76, v20
	v_fmac_f32_e32 v17, v76, v21
	v_fmac_f32_e32 v8, v76, v22
	v_fmac_f32_e32 v0, v78, v25
	v_lshlrev_b32_e32 v28, 16, v28
	ds_read_u16 v34, v34 offset:31232
	v_fmac_f32_e32 v89, v79, v1
	v_fmac_f32_e32 v88, v79, v2
	v_fmac_f32_e32 v64, v79, v3
	v_fmac_f32_e32 v52, v79, v4
	v_fmac_f32_e32 v51, v79, v5
	v_fmac_f32_e32 v49, v79, v6
	v_fmac_f32_e32 v48, v79, v7
	v_fmac_f32_e32 v47, v79, v9
	v_fmac_f32_e32 v46, v79, v10
	v_fmac_f32_e32 v45, v77, v9
	v_fmac_f32_e32 v44, v77, v10
	v_fmac_f32_e32 v43, v80, v14
	v_fmac_f32_e32 v42, v80, v15
	v_fmac_f32_e32 v41, v77, v13
	v_fmac_f32_e32 v40, v77, v14
	v_fmac_f32_e32 v39, v77, v15
	v_fmac_f32_e32 v38, v77, v16
	v_fmac_f32_e32 v37, v78, v19
	v_fmac_f32_e32 v36, v78, v20
	v_fmac_f32_e32 v33, v77, v20
	v_fmac_f32_e32 v26, v77, v21
	v_fmac_f32_e32 v17, v77, v22
	v_fmac_f32_e32 v8, v77, v23
	v_fmac_f32_e32 v0, v79, v27
	v_lshlrev_b32_e32 v29, 16, v29
	v_fmac_f32_e32 v90, v80, v1
	v_fmac_f32_e32 v89, v80, v2
	v_fmac_f32_e32 v88, v80, v3
	v_fmac_f32_e32 v64, v80, v4
	v_fmac_f32_e32 v52, v80, v5
	v_fmac_f32_e32 v51, v80, v6
	v_fmac_f32_e32 v49, v80, v7
	v_fmac_f32_e32 v48, v80, v9
	v_fmac_f32_e32 v47, v80, v10
	v_fmac_f32_e32 v46, v80, v11
	v_fmac_f32_e32 v45, v78, v10
	v_fmac_f32_e32 v44, v78, v11
	v_fmac_f32_e32 v43, v81, v15
	v_fmac_f32_e32 v42, v81, v16
	v_fmac_f32_e32 v41, v78, v14
	v_fmac_f32_e32 v40, v78, v15
	v_fmac_f32_e32 v39, v78, v16
	v_fmac_f32_e32 v38, v78, v18
	v_fmac_f32_e32 v37, v79, v20
	v_fmac_f32_e32 v36, v79, v21
	v_fmac_f32_e32 v33, v78, v21
	v_fmac_f32_e32 v26, v78, v22
	v_fmac_f32_e32 v17, v78, v23
	v_fmac_f32_e32 v8, v78, v24
	v_fmac_f32_e32 v0, v80, v28
	v_lshlrev_b32_e32 v30, 16, v30
	v_fmac_f32_e32 v91, v81, v1
	v_fmac_f32_e32 v90, v81, v2
	v_fmac_f32_e32 v89, v81, v3
	v_fmac_f32_e32 v88, v81, v4
	v_fmac_f32_e32 v64, v81, v5
	v_fmac_f32_e32 v52, v81, v6
	v_fmac_f32_e32 v51, v81, v7
	v_fmac_f32_e32 v49, v81, v9
	v_fmac_f32_e32 v48, v81, v10
	v_fmac_f32_e32 v47, v81, v11
	v_fmac_f32_e32 v46, v81, v12
	v_fmac_f32_e32 v45, v79, v11
	v_fmac_f32_e32 v44, v79, v12
	v_fmac_f32_e32 v43, v82, v16
	v_fmac_f32_e32 v42, v82, v18
	v_fmac_f32_e32 v41, v79, v15
	v_fmac_f32_e32 v40, v79, v16
	v_fmac_f32_e32 v39, v79, v18
	v_fmac_f32_e32 v38, v79, v19
	v_fmac_f32_e32 v37, v80, v21
	v_fmac_f32_e32 v36, v80, v22
	v_fmac_f32_e32 v33, v79, v22
	v_fmac_f32_e32 v26, v79, v23
	v_fmac_f32_e32 v17, v79, v24
	v_fmac_f32_e32 v8, v79, v25
	v_fmac_f32_e32 v0, v81, v29
	v_lshlrev_b32_e32 v31, 16, v31
	v_fmac_f32_e32 v92, v82, v1
	v_fmac_f32_e32 v91, v82, v2
	v_fmac_f32_e32 v90, v82, v3
	v_fmac_f32_e32 v89, v82, v4
	v_fmac_f32_e32 v88, v82, v5
	v_fmac_f32_e32 v64, v82, v6
	v_fmac_f32_e32 v52, v82, v7
	v_fmac_f32_e32 v51, v82, v9
	v_fmac_f32_e32 v49, v82, v10
	v_fmac_f32_e32 v48, v82, v11
	v_fmac_f32_e32 v47, v82, v12
	v_fmac_f32_e32 v46, v82, v13
	v_fmac_f32_e32 v45, v80, v12
	v_fmac_f32_e32 v44, v80, v13
	v_fmac_f32_e32 v43, v83, v18
	v_fmac_f32_e32 v42, v83, v19
	v_fmac_f32_e32 v41, v80, v16
	v_fmac_f32_e32 v40, v80, v18
	v_fmac_f32_e32 v39, v80, v19
	v_fmac_f32_e32 v38, v80, v20
	v_fmac_f32_e32 v37, v81, v22
	v_fmac_f32_e32 v36, v81, v23
	v_fmac_f32_e32 v33, v80, v23
	v_fmac_f32_e32 v26, v80, v24
	v_fmac_f32_e32 v17, v80, v25
	v_fmac_f32_e32 v8, v80, v27
	v_fmac_f32_e32 v0, v82, v30
	v_lshlrev_b32_e32 v32, 16, v32
	v_add3_u32 v87, 0, v35, v87
	v_fmac_f32_e32 v93, v83, v1
	v_fmac_f32_e32 v92, v83, v2
	v_fmac_f32_e32 v91, v83, v3
	v_fmac_f32_e32 v90, v83, v4
	v_fmac_f32_e32 v89, v83, v5
	v_fmac_f32_e32 v88, v83, v6
	v_fmac_f32_e32 v64, v83, v7
	v_fmac_f32_e32 v52, v83, v9
	v_fmac_f32_e32 v51, v83, v10
	v_fmac_f32_e32 v49, v83, v11
	v_fmac_f32_e32 v48, v83, v12
	v_fmac_f32_e32 v47, v83, v13
	v_fmac_f32_e32 v46, v83, v14
	v_fmac_f32_e32 v45, v81, v13
	v_fmac_f32_e32 v44, v81, v14
	v_fmac_f32_e32 v43, v84, v19
	v_fmac_f32_e32 v42, v84, v20
	v_fmac_f32_e32 v41, v81, v18
	v_fmac_f32_e32 v40, v81, v19
	v_fmac_f32_e32 v39, v81, v20
	v_fmac_f32_e32 v38, v81, v21
	v_fmac_f32_e32 v37, v82, v23
	v_fmac_f32_e32 v36, v82, v24
	v_fmac_f32_e32 v33, v81, v24
	v_fmac_f32_e32 v26, v81, v25
	v_fmac_f32_e32 v17, v81, v27
	v_fmac_f32_e32 v8, v81, v28
	v_fmac_f32_e32 v0, v83, v31
	s_waitcnt lgkmcnt(0)
	v_lshlrev_b32_e32 v34, 16, v34
	v_add_u32_e32 v35, 0xbc00, v87
	v_fmac_f32_e32 v95, v85, v1
	v_fmac_f32_e32 v94, v84, v1
	v_fmac_f32_e32 v93, v84, v2
	v_fmac_f32_e32 v92, v84, v3
	v_fmac_f32_e32 v91, v84, v4
	v_fmac_f32_e32 v90, v84, v5
	v_fmac_f32_e32 v89, v84, v6
	v_fmac_f32_e32 v88, v84, v7
	v_fmac_f32_e32 v64, v84, v9
	v_fmac_f32_e32 v52, v84, v10
	v_fmac_f32_e32 v51, v84, v11
	v_fmac_f32_e32 v49, v84, v12
	v_fmac_f32_e32 v48, v84, v13
	v_fmac_f32_e32 v47, v84, v14
	v_fmac_f32_e32 v46, v84, v15
	v_fmac_f32_e32 v45, v82, v14
	v_fmac_f32_e32 v44, v82, v15
	v_fmac_f32_e32 v43, v85, v20
	v_fmac_f32_e32 v42, v85, v21
	v_fmac_f32_e32 v41, v82, v19
	v_fmac_f32_e32 v40, v82, v20
	v_fmac_f32_e32 v39, v82, v21
	v_fmac_f32_e32 v38, v82, v22
	v_fmac_f32_e32 v37, v83, v24
	v_fmac_f32_e32 v36, v83, v25
	v_fmac_f32_e32 v33, v82, v25
	v_fmac_f32_e32 v26, v82, v27
	v_fmac_f32_e32 v17, v82, v28
	v_fmac_f32_e32 v8, v82, v29
	v_fmac_f32_e32 v0, v84, v32
	v_lshlrev_b32_e32 v1, 5, v50
	v_fmac_f32_e32 v94, v85, v2
	v_fmac_f32_e32 v93, v85, v3
	v_fmac_f32_e32 v92, v85, v4
	v_fmac_f32_e32 v91, v85, v5
	v_fmac_f32_e32 v90, v85, v6
	v_fmac_f32_e32 v89, v85, v7
	v_fmac_f32_e32 v88, v85, v9
	v_fmac_f32_e32 v64, v85, v10
	v_fmac_f32_e32 v52, v85, v11
	v_fmac_f32_e32 v51, v85, v12
	v_fmac_f32_e32 v49, v85, v13
	v_fmac_f32_e32 v48, v85, v14
	v_fmac_f32_e32 v47, v85, v15
	v_fmac_f32_e32 v46, v85, v16
	v_fmac_f32_e32 v45, v83, v15
	v_fmac_f32_e32 v44, v83, v16
	ds_write2st64_b32 v35, v43, v42 offset0:76 offset1:80
	v_fmac_f32_e32 v41, v83, v20
	v_fmac_f32_e32 v40, v83, v21
	v_fmac_f32_e32 v39, v83, v22
	v_fmac_f32_e32 v38, v83, v23
	v_fmac_f32_e32 v37, v84, v25
	v_fmac_f32_e32 v36, v84, v27
	v_fmac_f32_e32 v33, v83, v27
	v_fmac_f32_e32 v26, v83, v28
	v_fmac_f32_e32 v17, v83, v29
	v_fmac_f32_e32 v8, v83, v30
	v_fmac_f32_e32 v0, v85, v34
	v_ashrrev_i32_e32 v42, 3, v50
	v_and_b32_e32 v43, 0xe0, v1
	ds_write2st64_b32 v87, v97, v96 offset0:188 offset1:192
	ds_write2st64_b32 v87, v95, v94 offset0:196 offset1:200
	ds_write2st64_b32 v87, v93, v92 offset0:204 offset1:208
	ds_write2st64_b32 v87, v91, v90 offset0:212 offset1:216
	ds_write2st64_b32 v87, v89, v88 offset0:220 offset1:224
	ds_write2st64_b32 v87, v64, v52 offset0:228 offset1:232
	ds_write2st64_b32 v87, v51, v49 offset0:236 offset1:240
	ds_write2st64_b32 v87, v48, v47 offset0:244 offset1:248
	ds_write_b32 v87, v46 offset:64512
	v_fmac_f32_e32 v45, v84, v16
	v_fmac_f32_e32 v44, v84, v18
	v_fmac_f32_e32 v41, v84, v21
	v_fmac_f32_e32 v40, v84, v22
	v_fmac_f32_e32 v39, v84, v23
	v_fmac_f32_e32 v38, v84, v24
	v_fmac_f32_e32 v37, v85, v27
	v_fmac_f32_e32 v36, v85, v28
	v_fmac_f32_e32 v33, v84, v28
	v_fmac_f32_e32 v26, v84, v29
	v_fmac_f32_e32 v17, v84, v30
	v_fmac_f32_e32 v8, v84, v31
	ds_write_b32 v35, v0 offset:31744
	v_lshlrev_b32_e32 v0, 10, v42
	v_lshlrev_b32_e32 v87, 2, v43
	global_load_dwordx4 v[104:107], v87, s[22:23] offset:16
	global_load_dwordx4 v[108:111], v87, s[22:23]
	global_load_dwordx4 v[118:121], v87, s[2:3] offset:16
	global_load_dwordx4 v[122:125], v87, s[2:3]
	global_load_dwordx4 v[126:129], v87, s[22:23] offset:48
	global_load_dwordx4 v[134:137], v87, s[22:23] offset:32
	global_load_dwordx4 v[138:141], v87, s[2:3] offset:48
	global_load_dwordx4 v[142:145], v87, s[2:3] offset:32
	global_load_dwordx4 v[146:149], v87, s[22:23] offset:80
	global_load_dwordx4 v[150:153], v87, s[22:23] offset:64
	global_load_dwordx4 v[154:157], v87, s[2:3] offset:80
	global_load_dwordx4 v[160:163], v87, s[2:3] offset:64
	global_load_dwordx4 v[168:171], v87, s[22:23] offset:112
	global_load_dwordx4 v[172:175], v87, s[22:23] offset:96
	global_load_dwordx4 v[176:179], v87, s[2:3] offset:112
	global_load_dwordx4 v[184:187], v87, s[2:3] offset:96
	v_fmac_f32_e32 v45, v85, v18
	v_fmac_f32_e32 v44, v85, v19
	v_fmac_f32_e32 v41, v85, v22
	v_fmac_f32_e32 v40, v85, v23
	v_fmac_f32_e32 v39, v85, v24
	v_fmac_f32_e32 v38, v85, v25
	ds_write2st64_b32 v35, v37, v36 offset0:100 offset1:104
	v_fmac_f32_e32 v33, v85, v29
	v_fmac_f32_e32 v26, v85, v30
	v_fmac_f32_e32 v17, v85, v31
	v_fmac_f32_e32 v8, v85, v32
	v_add3_u32 v37, 0, v0, v87
	ds_write2st64_b32 v35, v45, v44 offset0:68 offset1:72
	ds_write2st64_b32 v35, v41, v40 offset0:84 offset1:88
	ds_write2st64_b32 v35, v39, v38 offset0:92 offset1:96
	ds_write2st64_b32 v35, v33, v26 offset0:108 offset1:112
	ds_write2st64_b32 v35, v17, v8 offset0:116 offset1:120
	s_waitcnt lgkmcnt(0)
	s_barrier
	ds_read_b128 v[28:31], v37 offset:48128
	ds_read_b128 v[24:27], v37 offset:48144
	ds_read_b128 v[20:23], v37 offset:48160
	ds_read_b128 v[16:19], v37 offset:48176
	s_mov_b32 s0, 0x3b800000
	s_waitcnt lgkmcnt(3)
	v_pk_mul_f32 v[0:1], v[30:31], v[30:31]
	v_pk_mul_f32 v[2:3], v[28:29], v[28:29]
	v_mov_b32_e32 v6, v31
	v_pk_mov_b32 v[4:5], v[2:3], v[0:1] op_sel:[1,0]
	v_mov_b32_e32 v3, v1
	v_pk_add_f32 v[0:1], v[4:5], v[2:3]
	v_mov_b32_e32 v2, v28
	s_waitcnt lgkmcnt(2)
	v_mov_b32_e32 v3, v24
	v_mov_b32_e32 v4, v29
	v_mov_b32_e32 v5, v25
	v_pk_add_f32 v[2:3], v[2:3], v[4:5]
	v_mov_b32_e32 v4, v30
	v_mov_b32_e32 v5, v26
	v_mov_b32_e32 v7, v27
	v_pk_add_f32 v[4:5], v[4:5], v[6:7]
	v_pk_mul_f32 v[6:7], v[24:25], v[24:25]
	v_pk_add_f32 v[2:3], v[2:3], v[4:5]
	v_pk_mul_f32 v[4:5], v[26:27], v[26:27]
	v_add_f32_e32 v2, 0, v2
	v_pk_mov_b32 v[8:9], v[6:7], v[4:5] op_sel:[1,0]
	v_mov_b32_e32 v7, v5
	v_pk_add_f32 v[4:5], v[8:9], v[6:7]
	s_waitcnt lgkmcnt(1)
	v_mov_b32_e32 v6, v21
	v_mov_b32_e32 v7, v22
	v_mov_b32_e32 v8, v20
	v_mov_b32_e32 v9, v23
	v_pk_add_f32 v[6:7], v[6:7], v[8:9]
	v_add_f32_e32 v2, v2, v3
	v_pk_add_f32 v[6:7], v[6:7], v[6:7] op_sel:[0,1] op_sel_hi:[1,0]
	s_waitcnt lgkmcnt(0)
	v_mul_f32_e32 v3, v16, v16
	v_mul_f32_e32 v7, v17, v17
	v_pk_add_f32 v[0:1], v[0:1], v[0:1] op_sel:[0,1] op_sel_hi:[1,0]
	v_pk_add_f32 v[4:5], v[4:5], v[4:5] op_sel:[0,1] op_sel_hi:[1,0]
	v_mov_b32_e32 v1, v3
	v_mov_b32_e32 v5, v7
	v_pk_add_f32 v[0:1], v[0:1], v[4:5]
	v_mul_f32_e32 v4, v21, v21
	v_mul_f32_e32 v12, v23, v23
	v_mul_f32_e32 v9, v18, v18
	v_mul_f32_e32 v11, v19, v19
	v_pk_fma_f32 v[4:5], v[20:21], v[20:21], v[4:5] op_sel_hi:[1,1,0]
	v_pk_fma_f32 v[12:13], v[22:23], v[22:23], v[12:13] op_sel_hi:[1,1,0]
	v_mov_b32_e32 v5, v9
	v_mov_b32_e32 v13, v11
	v_pk_add_f32 v[4:5], v[4:5], v[12:13]
	ds_read_b128 v[12:15], v37 offset:48192
	v_add_f32_e32 v8, v16, v17
	v_add_f32_e32 v10, v18, v19
	v_pk_add_f32 v[0:1], v[0:1], v[4:5]
	v_lshlrev_b32_e32 v64, 1, v43
	s_waitcnt lgkmcnt(0)
	v_mov_b32_e32 v9, v14
	v_mov_b32_e32 v11, v15
	v_mov_b32_e32 v3, v12
	v_mov_b32_e32 v7, v13
	v_pk_add_f32 v[4:5], v[8:9], v[10:11]
	ds_read_b128 v[8:11], v37 offset:48208
	v_pk_add_f32 v[2:3], v[2:3], v[6:7]
	v_pk_add_f32 v[0:1], v[0:1], v[0:1] op_sel:[0,1] op_sel_hi:[1,0]
	v_pk_add_f32 v[2:3], v[2:3], v[4:5]
	v_pk_mul_f32 v[4:5], v[12:13], v[12:13]
	v_pk_add_f32 v[32:33], v[2:3], v[2:3] op_sel:[0,1] op_sel_hi:[1,0]
	v_pk_mul_f32 v[2:3], v[14:15], v[14:15]
	s_waitcnt lgkmcnt(0)
	v_mul_f32_e32 v40, v11, v11
	v_pk_mov_b32 v[6:7], v[4:5], v[2:3] op_sel:[1,0]
	v_mov_b32_e32 v5, v3
	v_pk_add_f32 v[2:3], v[6:7], v[4:5]
	v_mov_b32_e32 v4, v9
	v_mov_b32_e32 v5, v10
	v_mov_b32_e32 v6, v8
	v_mov_b32_e32 v7, v11
	v_pk_add_f32 v[4:5], v[4:5], v[6:7]
	v_pk_add_f32 v[2:3], v[2:3], v[2:3] op_sel:[0,1] op_sel_hi:[1,0]
	v_pk_add_f32 v[34:35], v[4:5], v[4:5] op_sel:[0,1] op_sel_hi:[1,0]
	ds_read_b128 v[4:7], v37 offset:48224
	v_pk_fma_f32 v[40:41], v[10:11], v[10:11], v[40:41] op_sel_hi:[1,1,0]
	s_add_i32 s67, s67, s10
	s_waitcnt lgkmcnt(0)
	v_mul_f32_e32 v33, v4, v4
	v_mul_f32_e32 v35, v5, v5
	v_mov_b32_e32 v1, v33
	v_mov_b32_e32 v3, v35
	v_pk_add_f32 v[0:1], v[0:1], v[2:3]
	v_mul_f32_e32 v2, v9, v9
	v_mul_f32_e32 v39, v6, v6
	v_mul_f32_e32 v44, v7, v7
	v_pk_fma_f32 v[2:3], v[8:9], v[8:9], v[2:3] op_sel_hi:[1,1,0]
	v_mov_b32_e32 v41, v44
	v_mov_b32_e32 v3, v39
	v_pk_add_f32 v[2:3], v[2:3], v[40:41]
	v_add_f32_e32 v36, v4, v5
	v_pk_add_f32 v[0:1], v[0:1], v[2:3]
	v_add_f32_e32 v38, v6, v7
	v_pk_add_f32 v[40:41], v[0:1], v[0:1] op_sel:[0,1] op_sel_hi:[1,0]
	ds_read_b128 v[0:3], v37 offset:48240
	s_waitcnt lgkmcnt(0)
	v_mov_b32_e32 v33, v0
	v_mov_b32_e32 v35, v1
	v_mov_b32_e32 v37, v2
	v_mov_b32_e32 v39, v3
	v_pk_add_f32 v[32:33], v[32:33], v[34:35]
	v_pk_add_f32 v[34:35], v[36:37], v[38:39]
	v_pk_mul_f32 v[36:37], v[0:1], v[0:1]
	v_pk_add_f32 v[32:33], v[32:33], v[34:35]
	v_pk_mul_f32 v[34:35], v[2:3], v[2:3]
	v_mov_b32_e32 v41, v32
	v_pk_mov_b32 v[38:39], v[36:37], v[34:35] op_sel:[1,0]
	v_mov_b32_e32 v37, v35
	v_pk_add_f32 v[34:35], v[38:39], v[36:37]
	s_nop 0
	v_pk_add_f32 v[34:35], v[34:35], v[34:35] op_sel:[0,1] op_sel_hi:[1,0]
	s_nop 0
	v_mov_b32_e32 v35, v33
	v_pk_add_f32 v[32:33], v[40:41], v[34:35]
	ds_swizzle_b32 v35, v33 offset:swizzle(SWAP,1)
	ds_swizzle_b32 v34, v32 offset:swizzle(SWAP,1)
	s_waitcnt lgkmcnt(0)
	v_pk_add_f32 v[32:33], v[32:33], v[34:35]
	ds_swizzle_b32 v35, v33 offset:swizzle(SWAP,2)
	ds_swizzle_b32 v34, v32 offset:swizzle(SWAP,2)
	s_waitcnt lgkmcnt(0)
	v_pk_add_f32 v[32:33], v[32:33], v[34:35]
	ds_swizzle_b32 v35, v33 offset:swizzle(SWAP,4)
	ds_swizzle_b32 v34, v32 offset:swizzle(SWAP,4)
	s_waitcnt lgkmcnt(0)
	v_pk_add_f32 v[32:33], v[32:33], v[34:35]
	s_nop 0
	v_pk_mul_f32 v[50:51], v[32:33], s[0:1] op_sel_hi:[1,0]
	s_mov_b32 s0, 0x800000
	v_fma_f32 v32, -v51, v51, v50
	v_max_f32_e32 v32, 0, v32
	v_add_f32_e32 v32, 0x3727c5ac, v32
	v_cmp_gt_f32_e32 vcc, s0, v32
	v_mul_f32_e32 v33, 0x4b800000, v32
	v_pk_add_f32 v[28:29], v[28:29], v[50:51] op_sel:[0,1] neg_lo:[0,1] neg_hi:[0,1]
	v_cndmask_b32_e32 v32, v32, v33, vcc
	v_rsq_f32_e32 v32, v32
	v_pk_add_f32 v[24:25], v[24:25], v[50:51] op_sel:[0,1] neg_lo:[0,1] neg_hi:[0,1]
	v_pk_add_f32 v[20:21], v[20:21], v[50:51] op_sel:[0,1] neg_lo:[0,1] neg_hi:[0,1]
	v_pk_add_f32 v[16:17], v[16:17], v[50:51] op_sel:[0,1] neg_lo:[0,1] neg_hi:[0,1]
	v_mul_f32_e32 v33, 0x45800000, v32
	v_cndmask_b32_e32 v52, v32, v33, vcc
	v_add3_u32 v32, s34, v42, 15
	v_ashrrev_i32_e32 v33, 31, v32
	v_lshlrev_b64 v[32:33], 11, v[32:33]
	v_lshl_add_u64 v[32:33], s[8:9], 0, v[32:33]
	v_lshl_add_u64 v[48:49], v[32:33], 0, v[64:65]
	v_pk_mul_f32 v[28:29], v[28:29], v[52:53] op_sel_hi:[1,0]
	v_pk_mul_f32 v[24:25], v[24:25], v[52:53] op_sel_hi:[1,0]
	v_pk_mul_f32 v[20:21], v[20:21], v[52:53] op_sel_hi:[1,0]
	v_pk_mul_f32 v[16:17], v[16:17], v[52:53] op_sel_hi:[1,0]
	v_pk_add_f32 v[12:13], v[12:13], v[50:51] op_sel:[0,1] neg_lo:[0,1] neg_hi:[0,1]
	v_pk_add_f32 v[8:9], v[8:9], v[50:51] op_sel:[0,1] neg_lo:[0,1] neg_hi:[0,1]
	v_pk_mul_f32 v[12:13], v[12:13], v[52:53] op_sel_hi:[1,0]
	v_pk_mul_f32 v[8:9], v[8:9], v[52:53] op_sel_hi:[1,0]
	v_pk_add_f32 v[4:5], v[4:5], v[50:51] op_sel:[0,1] neg_lo:[0,1] neg_hi:[0,1]
	v_pk_add_f32 v[0:1], v[0:1], v[50:51] op_sel:[0,1] neg_lo:[0,1] neg_hi:[0,1]
	v_pk_mul_f32 v[4:5], v[4:5], v[52:53] op_sel_hi:[1,0]
	v_pk_mul_f32 v[0:1], v[0:1], v[52:53] op_sel_hi:[1,0]
	s_add_i32 s34, s34, s13
	s_cmpk_lt_i32 s67, 0xc0
	s_waitcnt vmcnt(0)
	v_pk_fma_f32 v[24:25], v[104:105], v[24:25], v[118:119]
	v_pk_fma_f32 v[28:29], v[108:109], v[28:29], v[122:123]
	s_nop 0
	v_mul_f32_e32 v40, 0xbfb8aa3b, v28
	v_mul_f32_e32 v41, 0xbfb8aa3b, v29
	v_exp_f32_e32 v40, v40
	v_exp_f32_e32 v41, v41
	s_nop 0
	v_pk_add_f32 v[40:41], v[40:41], 1.0 op_sel_hi:[1,0]
	s_nop 0
	v_div_scale_f32 v44, s[0:1], v41, v41, v29
	v_rcp_f32_e32 v45, v44
	s_nop 0
	v_fma_f32 v64, -v44, v45, 1.0
	v_fmac_f32_e32 v45, v64, v45
	v_div_scale_f32 v64, vcc, v29, v41, v29
	v_mul_f32_e32 v88, v64, v45
	v_fma_f32 v89, -v44, v88, v64
	v_fmac_f32_e32 v88, v89, v45
	v_fma_f32 v44, -v44, v88, v64
	v_div_fmas_f32 v44, v44, v45, v88
	v_div_fixup_f32 v41, v44, v41, v29
	v_div_scale_f32 v29, s[0:1], v40, v40, v28
	v_rcp_f32_e32 v44, v29
	s_nop 0
	v_fma_f32 v45, -v29, v44, 1.0
	v_fmac_f32_e32 v44, v45, v44
	v_div_scale_f32 v45, vcc, v28, v40, v28
	v_mul_f32_e32 v64, v45, v44
	v_fma_f32 v88, -v29, v64, v45
	v_fmac_f32_e32 v64, v88, v44
	v_fma_f32 v29, -v29, v64, v45
	v_div_fmas_f32 v29, v29, v44, v64
	v_div_fixup_f32 v40, v29, v40, v28
	v_pk_add_f32 v[28:29], v[30:31], v[50:51] op_sel:[0,1] neg_lo:[0,1] neg_hi:[0,1]
	s_nop 0
	v_pk_mul_f32 v[28:29], v[28:29], v[52:53] op_sel_hi:[1,0]
	s_nop 0
	v_pk_fma_f32 v[28:29], v[110:111], v[28:29], v[124:125]
	s_nop 0
	v_mul_f32_e32 v30, 0xbfb8aa3b, v28
	v_mul_f32_e32 v31, 0xbfb8aa3b, v29
	v_exp_f32_e32 v30, v30
	v_exp_f32_e32 v31, v31
	s_nop 0
	v_pk_add_f32 v[30:31], v[30:31], 1.0 op_sel_hi:[1,0]
	s_nop 0
	v_div_scale_f32 v42, s[0:1], v31, v31, v29
	v_rcp_f32_e32 v43, v42
	s_nop 0
	v_fma_f32 v44, -v42, v43, 1.0
	v_fmac_f32_e32 v43, v44, v43
	v_div_scale_f32 v44, vcc, v29, v31, v29
	v_mul_f32_e32 v45, v44, v43
	v_fma_f32 v46, -v42, v45, v44
	v_fmac_f32_e32 v45, v46, v43
	v_fma_f32 v42, -v42, v45, v44
	v_div_fmas_f32 v42, v42, v43, v45
	v_div_fixup_f32 v31, v42, v31, v29
	v_div_scale_f32 v29, s[0:1], v30, v30, v28
	v_rcp_f32_e32 v42, v29
	s_nop 0
	v_fma_f32 v43, -v29, v42, 1.0
	v_fmac_f32_e32 v42, v43, v42
	v_div_scale_f32 v43, vcc, v28, v30, v28
	v_mul_f32_e32 v44, v43, v42
	v_fma_f32 v45, -v29, v44, v43
	v_fmac_f32_e32 v44, v45, v42
	v_fma_f32 v29, -v29, v44, v43
	v_div_fmas_f32 v29, v29, v42, v44
	v_div_fixup_f32 v30, v29, v30, v28
	v_mul_f32_e32 v28, 0xbfb8aa3b, v24
	v_mul_f32_e32 v29, 0xbfb8aa3b, v25
	v_exp_f32_e32 v28, v28
	v_exp_f32_e32 v29, v29
	s_nop 0
	v_pk_add_f32 v[28:29], v[28:29], 1.0 op_sel_hi:[1,0]
	s_nop 0
	v_div_scale_f32 v32, s[0:1], v29, v29, v25
	v_rcp_f32_e32 v33, v32
	s_nop 0
	v_fma_f32 v36, -v32, v33, 1.0
	v_fmac_f32_e32 v33, v36, v33
	v_div_scale_f32 v36, vcc, v25, v29, v25
	v_mul_f32_e32 v37, v36, v33
	v_fma_f32 v42, -v32, v37, v36
	v_fmac_f32_e32 v37, v42, v33
	v_fma_f32 v32, -v32, v37, v36
	v_div_fmas_f32 v32, v32, v33, v37
	v_div_fixup_f32 v29, v32, v29, v25
	v_div_scale_f32 v25, s[0:1], v28, v28, v24
	v_rcp_f32_e32 v32, v25
	s_nop 0
	v_fma_f32 v33, -v25, v32, 1.0
	v_fmac_f32_e32 v32, v33, v32
	v_div_scale_f32 v33, vcc, v24, v28, v24
	v_mul_f32_e32 v36, v33, v32
	v_fma_f32 v37, -v25, v36, v33
	v_fmac_f32_e32 v36, v37, v32
	v_fma_f32 v25, -v25, v36, v33
	v_div_fmas_f32 v25, v25, v32, v36
	v_div_fixup_f32 v28, v25, v28, v24
	v_pk_add_f32 v[24:25], v[26:27], v[50:51] op_sel:[0,1] neg_lo:[0,1] neg_hi:[0,1]
	s_nop 0
	v_pk_mul_f32 v[24:25], v[24:25], v[52:53] op_sel_hi:[1,0]
	s_nop 0
	v_pk_fma_f32 v[24:25], v[24:25], v[106:107], v[120:121]
	s_nop 0
	v_mul_f32_e32 v26, 0xbfb8aa3b, v24
	v_mul_f32_e32 v27, 0xbfb8aa3b, v25
	v_exp_f32_e32 v26, v26
	v_exp_f32_e32 v27, v27
	s_nop 0
	v_pk_add_f32 v[26:27], v[26:27], 1.0 op_sel_hi:[1,0]
	s_nop 0
	v_div_scale_f32 v32, s[0:1], v27, v27, v25
	v_rcp_f32_e32 v33, v32
	s_nop 0
	v_fma_f32 v34, -v32, v33, 1.0
	v_fmac_f32_e32 v33, v34, v33
	v_div_scale_f32 v34, vcc, v25, v27, v25
	v_mul_f32_e32 v35, v34, v33
	v_fma_f32 v36, -v32, v35, v34
	v_fmac_f32_e32 v35, v36, v33
	v_fma_f32 v32, -v32, v35, v34
	v_div_fmas_f32 v32, v32, v33, v35
	v_div_fixup_f32 v27, v32, v27, v25
	v_div_scale_f32 v25, s[0:1], v26, v26, v24
	v_rcp_f32_e32 v32, v25
	s_nop 0
	v_fma_f32 v33, -v25, v32, 1.0
	v_fmac_f32_e32 v32, v33, v32
	v_div_scale_f32 v33, vcc, v24, v26, v24
	v_mul_f32_e32 v34, v33, v32
	v_fma_f32 v35, -v25, v34, v33
	v_fmac_f32_e32 v34, v35, v32
	v_fma_f32 v25, -v25, v34, v33
	v_div_fmas_f32 v25, v25, v32, v34
	v_div_fixup_f32 v32, v25, v26, v24
	v_cvt_pk_bf16_f32 v24, v40, v41
	v_cvt_pk_bf16_f32 v25, v30, v31
	v_cvt_pk_bf16_f32 v26, v28, v29
	v_cvt_pk_bf16_f32 v27, v32, v27
	global_store_dwordx4 v[48:49], v[24:27], off sc1
	s_nop 0
	v_pk_fma_f32 v[16:17], v[16:17], v[126:127], v[138:139]
	v_pk_fma_f32 v[20:21], v[20:21], v[134:135], v[142:143]
	s_nop 0
	v_mul_f32_e32 v32, 0xbfb8aa3b, v20
	v_mul_f32_e32 v33, 0xbfb8aa3b, v21
	v_exp_f32_e32 v32, v32
	v_exp_f32_e32 v33, v33
	s_nop 0
	v_pk_add_f32 v[32:33], v[32:33], 1.0 op_sel_hi:[1,0]
	s_nop 0
	v_div_scale_f32 v36, s[0:1], v33, v33, v21
	v_rcp_f32_e32 v37, v36
	s_nop 0
	v_fma_f32 v40, -v36, v37, 1.0
	v_fmac_f32_e32 v37, v40, v37
	v_div_scale_f32 v40, vcc, v21, v33, v21
	v_mul_f32_e32 v41, v40, v37
	v_fma_f32 v42, -v36, v41, v40
	v_fmac_f32_e32 v41, v42, v37
	v_fma_f32 v36, -v36, v41, v40
	v_div_fmas_f32 v36, v36, v37, v41
	v_div_fixup_f32 v33, v36, v33, v21
	v_div_scale_f32 v21, s[0:1], v32, v32, v20
	v_rcp_f32_e32 v36, v21
	s_nop 0
	v_fma_f32 v37, -v21, v36, 1.0
	v_fmac_f32_e32 v36, v37, v36
	v_div_scale_f32 v37, vcc, v20, v32, v20
	v_mul_f32_e32 v40, v37, v36
	v_fma_f32 v41, -v21, v40, v37
	v_fmac_f32_e32 v40, v41, v36
	v_fma_f32 v21, -v21, v40, v37
	v_div_fmas_f32 v21, v21, v36, v40
	v_div_fixup_f32 v32, v21, v32, v20
	v_pk_add_f32 v[20:21], v[22:23], v[50:51] op_sel:[0,1] neg_lo:[0,1] neg_hi:[0,1]
	s_nop 0
	v_pk_mul_f32 v[20:21], v[20:21], v[52:53] op_sel_hi:[1,0]
	s_nop 0
	v_pk_fma_f32 v[20:21], v[20:21], v[136:137], v[144:145]
	s_nop 0
	v_mul_f32_e32 v22, 0xbfb8aa3b, v20
	v_mul_f32_e32 v23, 0xbfb8aa3b, v21
	v_exp_f32_e32 v22, v22
	v_exp_f32_e32 v23, v23
	s_nop 0
	v_pk_add_f32 v[22:23], v[22:23], 1.0 op_sel_hi:[1,0]
	s_nop 0
	v_div_scale_f32 v34, s[0:1], v23, v23, v21
	v_rcp_f32_e32 v35, v34
	s_nop 0
	v_fma_f32 v36, -v34, v35, 1.0
	v_fmac_f32_e32 v35, v36, v35
	v_div_scale_f32 v36, vcc, v21, v23, v21
	v_mul_f32_e32 v37, v36, v35
	v_fma_f32 v38, -v34, v37, v36
	v_fmac_f32_e32 v37, v38, v35
	v_fma_f32 v34, -v34, v37, v36
	v_div_fmas_f32 v34, v34, v35, v37
	v_div_fixup_f32 v23, v34, v23, v21
	v_div_scale_f32 v21, s[0:1], v22, v22, v20
	v_rcp_f32_e32 v34, v21
	s_nop 0
	v_fma_f32 v35, -v21, v34, 1.0
	v_fmac_f32_e32 v34, v35, v34
	v_div_scale_f32 v35, vcc, v20, v22, v20
	v_mul_f32_e32 v36, v35, v34
	v_fma_f32 v37, -v21, v36, v35
	v_fmac_f32_e32 v36, v37, v34
	v_fma_f32 v21, -v21, v36, v35
	v_div_fmas_f32 v21, v21, v34, v36
	v_div_fixup_f32 v22, v21, v22, v20
	v_mul_f32_e32 v20, 0xbfb8aa3b, v16
	v_mul_f32_e32 v21, 0xbfb8aa3b, v17
	v_exp_f32_e32 v20, v20
	v_exp_f32_e32 v21, v21
	s_nop 0
	v_pk_add_f32 v[20:21], v[20:21], 1.0 op_sel_hi:[1,0]
	s_nop 0
	v_div_scale_f32 v24, s[0:1], v21, v21, v17
	v_rcp_f32_e32 v25, v24
	s_nop 0
	v_fma_f32 v28, -v24, v25, 1.0
	v_fmac_f32_e32 v25, v28, v25
	v_div_scale_f32 v28, vcc, v17, v21, v17
	v_mul_f32_e32 v29, v28, v25
	v_fma_f32 v34, -v24, v29, v28
	v_fmac_f32_e32 v29, v34, v25
	v_fma_f32 v24, -v24, v29, v28
	v_div_fmas_f32 v24, v24, v25, v29
	v_div_fixup_f32 v21, v24, v21, v17
	v_div_scale_f32 v17, s[0:1], v20, v20, v16
	v_rcp_f32_e32 v24, v17
	s_nop 0
	v_fma_f32 v25, -v17, v24, 1.0
	v_fmac_f32_e32 v24, v25, v24
	v_div_scale_f32 v25, vcc, v16, v20, v16
	v_mul_f32_e32 v28, v25, v24
	v_fma_f32 v29, -v17, v28, v25
	v_fmac_f32_e32 v28, v29, v24
	v_fma_f32 v17, -v17, v28, v25
	v_div_fmas_f32 v17, v17, v24, v28
	v_div_fixup_f32 v20, v17, v20, v16
	v_pk_add_f32 v[16:17], v[18:19], v[50:51] op_sel:[0,1] neg_lo:[0,1] neg_hi:[0,1]
	s_nop 0
	v_pk_mul_f32 v[16:17], v[16:17], v[52:53] op_sel_hi:[1,0]
	s_nop 0
	v_pk_fma_f32 v[16:17], v[16:17], v[128:129], v[140:141]
	s_nop 0
	v_mul_f32_e32 v18, 0xbfb8aa3b, v16
	v_mul_f32_e32 v19, 0xbfb8aa3b, v17
	v_exp_f32_e32 v18, v18
	v_exp_f32_e32 v19, v19
	s_nop 0
	v_pk_add_f32 v[18:19], v[18:19], 1.0 op_sel_hi:[1,0]
	s_nop 0
	v_div_scale_f32 v24, s[0:1], v19, v19, v17
	v_rcp_f32_e32 v25, v24
	s_nop 0
	v_fma_f32 v26, -v24, v25, 1.0
	v_fmac_f32_e32 v25, v26, v25
	v_div_scale_f32 v26, vcc, v17, v19, v17
	v_mul_f32_e32 v27, v26, v25
	v_fma_f32 v28, -v24, v27, v26
	v_fmac_f32_e32 v27, v28, v25
	v_fma_f32 v24, -v24, v27, v26
	v_div_fmas_f32 v24, v24, v25, v27
	v_div_fixup_f32 v19, v24, v19, v17
	v_div_scale_f32 v17, s[0:1], v18, v18, v16
	v_rcp_f32_e32 v24, v17
	s_nop 0
	v_fma_f32 v25, -v17, v24, 1.0
	v_fmac_f32_e32 v24, v25, v24
	v_div_scale_f32 v25, vcc, v16, v18, v16
	v_mul_f32_e32 v26, v25, v24
	v_fma_f32 v27, -v17, v26, v25
	v_fmac_f32_e32 v26, v27, v24
	v_fma_f32 v17, -v17, v26, v25
	v_div_fmas_f32 v17, v17, v24, v26
	v_div_fixup_f32 v24, v17, v18, v16
	v_cvt_pk_bf16_f32 v16, v32, v33
	v_cvt_pk_bf16_f32 v17, v22, v23
	v_cvt_pk_bf16_f32 v18, v20, v21
	v_cvt_pk_bf16_f32 v19, v24, v19
	global_store_dwordx4 v[48:49], v[16:19], off offset:16 sc1
	s_nop 0
	v_pk_fma_f32 v[8:9], v[8:9], v[146:147], v[154:155]
	v_pk_fma_f32 v[12:13], v[12:13], v[150:151], v[160:161]
	s_nop 0
	v_mul_f32_e32 v24, 0xbfb8aa3b, v12
	v_mul_f32_e32 v25, 0xbfb8aa3b, v13
	v_exp_f32_e32 v24, v24
	v_exp_f32_e32 v25, v25
	s_nop 0
	v_pk_add_f32 v[24:25], v[24:25], 1.0 op_sel_hi:[1,0]
	s_nop 0
	v_div_scale_f32 v28, s[0:1], v25, v25, v13
	v_rcp_f32_e32 v29, v28
	s_nop 0
	v_fma_f32 v32, -v28, v29, 1.0
	v_fmac_f32_e32 v29, v32, v29
	v_div_scale_f32 v32, vcc, v13, v25, v13
	v_mul_f32_e32 v33, v32, v29
	v_fma_f32 v34, -v28, v33, v32
	v_fmac_f32_e32 v33, v34, v29
	v_fma_f32 v28, -v28, v33, v32
	v_div_fmas_f32 v28, v28, v29, v33
	v_div_fixup_f32 v25, v28, v25, v13
	v_div_scale_f32 v13, s[0:1], v24, v24, v12
	v_rcp_f32_e32 v28, v13
	s_nop 0
	v_fma_f32 v29, -v13, v28, 1.0
	v_fmac_f32_e32 v28, v29, v28
	v_div_scale_f32 v29, vcc, v12, v24, v12
	v_mul_f32_e32 v32, v29, v28
	v_fma_f32 v33, -v13, v32, v29
	v_fmac_f32_e32 v32, v33, v28
	v_fma_f32 v13, -v13, v32, v29
	v_div_fmas_f32 v13, v13, v28, v32
	v_div_fixup_f32 v24, v13, v24, v12
	v_pk_add_f32 v[12:13], v[14:15], v[50:51] op_sel:[0,1] neg_lo:[0,1] neg_hi:[0,1]
	s_nop 0
	v_pk_mul_f32 v[12:13], v[12:13], v[52:53] op_sel_hi:[1,0]
	s_nop 0
	v_pk_fma_f32 v[12:13], v[12:13], v[152:153], v[162:163]
	s_nop 0
	v_mul_f32_e32 v14, 0xbfb8aa3b, v12
	v_mul_f32_e32 v15, 0xbfb8aa3b, v13
	v_exp_f32_e32 v14, v14
	v_exp_f32_e32 v15, v15
	s_nop 0
	v_pk_add_f32 v[14:15], v[14:15], 1.0 op_sel_hi:[1,0]
	s_nop 0
	v_div_scale_f32 v26, s[0:1], v15, v15, v13
	v_rcp_f32_e32 v27, v26
	s_nop 0
	v_fma_f32 v28, -v26, v27, 1.0
	v_fmac_f32_e32 v27, v28, v27
	v_div_scale_f32 v28, vcc, v13, v15, v13
	v_mul_f32_e32 v29, v28, v27
	v_fma_f32 v30, -v26, v29, v28
	v_fmac_f32_e32 v29, v30, v27
	v_fma_f32 v26, -v26, v29, v28
	v_div_fmas_f32 v26, v26, v27, v29
	v_div_fixup_f32 v15, v26, v15, v13
	v_div_scale_f32 v13, s[0:1], v14, v14, v12
	v_rcp_f32_e32 v26, v13
	s_nop 0
	v_fma_f32 v27, -v13, v26, 1.0
	v_fmac_f32_e32 v26, v27, v26
	v_div_scale_f32 v27, vcc, v12, v14, v12
	v_mul_f32_e32 v28, v27, v26
	v_fma_f32 v29, -v13, v28, v27
	v_fmac_f32_e32 v28, v29, v26
	v_fma_f32 v13, -v13, v28, v27
	v_div_fmas_f32 v13, v13, v26, v28
	v_div_fixup_f32 v14, v13, v14, v12
	v_mul_f32_e32 v12, 0xbfb8aa3b, v8
	v_mul_f32_e32 v13, 0xbfb8aa3b, v9
	v_exp_f32_e32 v12, v12
	v_exp_f32_e32 v13, v13
	s_nop 0
	v_pk_add_f32 v[12:13], v[12:13], 1.0 op_sel_hi:[1,0]
	s_nop 0
	v_div_scale_f32 v16, s[0:1], v13, v13, v9
	v_rcp_f32_e32 v17, v16
	s_nop 0
	v_fma_f32 v20, -v16, v17, 1.0
	v_fmac_f32_e32 v17, v20, v17
	v_div_scale_f32 v20, vcc, v9, v13, v9
	v_mul_f32_e32 v21, v20, v17
	v_fma_f32 v26, -v16, v21, v20
	v_fmac_f32_e32 v21, v26, v17
	v_fma_f32 v16, -v16, v21, v20
	v_div_fmas_f32 v16, v16, v17, v21
	v_div_fixup_f32 v13, v16, v13, v9
	v_div_scale_f32 v9, s[0:1], v12, v12, v8
	v_rcp_f32_e32 v16, v9
	s_nop 0
	v_fma_f32 v17, -v9, v16, 1.0
	v_fmac_f32_e32 v16, v17, v16
	v_div_scale_f32 v17, vcc, v8, v12, v8
	v_mul_f32_e32 v20, v17, v16
	v_fma_f32 v21, -v9, v20, v17
	v_fmac_f32_e32 v20, v21, v16
	v_fma_f32 v9, -v9, v20, v17
	v_div_fmas_f32 v9, v9, v16, v20
	v_div_fixup_f32 v12, v9, v12, v8
	v_pk_add_f32 v[8:9], v[10:11], v[50:51] op_sel:[0,1] neg_lo:[0,1] neg_hi:[0,1]
	s_nop 0
	v_pk_mul_f32 v[8:9], v[8:9], v[52:53] op_sel_hi:[1,0]
	s_nop 0
	v_pk_fma_f32 v[8:9], v[8:9], v[148:149], v[156:157]
	s_nop 0
	v_mul_f32_e32 v10, 0xbfb8aa3b, v8
	v_mul_f32_e32 v11, 0xbfb8aa3b, v9
	v_exp_f32_e32 v10, v10
	v_exp_f32_e32 v11, v11
	s_nop 0
	v_pk_add_f32 v[10:11], v[10:11], 1.0 op_sel_hi:[1,0]
	s_nop 0
	v_div_scale_f32 v16, s[0:1], v11, v11, v9
	v_rcp_f32_e32 v17, v16
	s_nop 0
	v_fma_f32 v18, -v16, v17, 1.0
	v_fmac_f32_e32 v17, v18, v17
	v_div_scale_f32 v18, vcc, v9, v11, v9
	v_mul_f32_e32 v19, v18, v17
	v_fma_f32 v20, -v16, v19, v18
	v_fmac_f32_e32 v19, v20, v17
	v_fma_f32 v16, -v16, v19, v18
	v_div_fmas_f32 v16, v16, v17, v19
	v_div_fixup_f32 v11, v16, v11, v9
	v_div_scale_f32 v9, s[0:1], v10, v10, v8
	v_rcp_f32_e32 v16, v9
	s_nop 0
	v_fma_f32 v17, -v9, v16, 1.0
	v_fmac_f32_e32 v16, v17, v16
	v_div_scale_f32 v17, vcc, v8, v10, v8
	v_mul_f32_e32 v18, v17, v16
	v_fma_f32 v19, -v9, v18, v17
	v_fmac_f32_e32 v18, v19, v16
	v_fma_f32 v9, -v9, v18, v17
	v_div_fmas_f32 v9, v9, v16, v18
	v_div_fixup_f32 v16, v9, v10, v8
	v_cvt_pk_bf16_f32 v8, v24, v25
	v_cvt_pk_bf16_f32 v9, v14, v15
	v_cvt_pk_bf16_f32 v10, v12, v13
	v_cvt_pk_bf16_f32 v11, v16, v11
	global_store_dwordx4 v[48:49], v[8:11], off offset:32 sc1
	s_nop 0
	v_pk_fma_f32 v[0:1], v[0:1], v[168:169], v[176:177]
	v_pk_fma_f32 v[4:5], v[4:5], v[172:173], v[184:185]
	s_nop 0
	v_mul_f32_e32 v16, 0xbfb8aa3b, v4
	v_mul_f32_e32 v17, 0xbfb8aa3b, v5
	v_exp_f32_e32 v16, v16
	v_exp_f32_e32 v17, v17
	s_nop 0
	v_pk_add_f32 v[16:17], v[16:17], 1.0 op_sel_hi:[1,0]
	s_nop 0
	v_div_scale_f32 v20, s[0:1], v17, v17, v5
	v_rcp_f32_e32 v21, v20
	s_nop 0
	v_fma_f32 v24, -v20, v21, 1.0
	v_fmac_f32_e32 v21, v24, v21
	v_div_scale_f32 v24, vcc, v5, v17, v5
	v_mul_f32_e32 v25, v24, v21
	v_fma_f32 v26, -v20, v25, v24
	v_fmac_f32_e32 v25, v26, v21
	v_fma_f32 v20, -v20, v25, v24
	v_div_fmas_f32 v20, v20, v21, v25
	v_div_fixup_f32 v17, v20, v17, v5
	v_div_scale_f32 v5, s[0:1], v16, v16, v4
	v_rcp_f32_e32 v20, v5
	s_nop 0
	v_fma_f32 v21, -v5, v20, 1.0
	v_fmac_f32_e32 v20, v21, v20
	v_div_scale_f32 v21, vcc, v4, v16, v4
	v_mul_f32_e32 v24, v21, v20
	v_fma_f32 v25, -v5, v24, v21
	v_fmac_f32_e32 v24, v25, v20
	v_fma_f32 v5, -v5, v24, v21
	v_div_fmas_f32 v5, v5, v20, v24
	v_div_fixup_f32 v16, v5, v16, v4
	v_pk_add_f32 v[4:5], v[6:7], v[50:51] op_sel:[0,1] neg_lo:[0,1] neg_hi:[0,1]
	s_nop 0
	v_pk_mul_f32 v[4:5], v[4:5], v[52:53] op_sel_hi:[1,0]
	s_nop 0
	v_pk_fma_f32 v[4:5], v[4:5], v[174:175], v[186:187]
	s_nop 0
	v_mul_f32_e32 v6, 0xbfb8aa3b, v4
	v_mul_f32_e32 v7, 0xbfb8aa3b, v5
	v_exp_f32_e32 v6, v6
	v_exp_f32_e32 v7, v7
	s_nop 0
	v_pk_add_f32 v[6:7], v[6:7], 1.0 op_sel_hi:[1,0]
	s_nop 0
	v_div_scale_f32 v18, s[0:1], v7, v7, v5
	v_rcp_f32_e32 v19, v18
	s_nop 0
	v_fma_f32 v20, -v18, v19, 1.0
	v_fmac_f32_e32 v19, v20, v19
	v_div_scale_f32 v20, vcc, v5, v7, v5
	v_mul_f32_e32 v21, v20, v19
	v_fma_f32 v22, -v18, v21, v20
	v_fmac_f32_e32 v21, v22, v19
	v_fma_f32 v18, -v18, v21, v20
	v_div_fmas_f32 v18, v18, v19, v21
	v_div_fixup_f32 v7, v18, v7, v5
	v_div_scale_f32 v5, s[0:1], v6, v6, v4
	v_rcp_f32_e32 v18, v5
	s_nop 0
	v_fma_f32 v19, -v5, v18, 1.0
	v_fmac_f32_e32 v18, v19, v18
	v_div_scale_f32 v19, vcc, v4, v6, v4
	v_mul_f32_e32 v20, v19, v18
	v_fma_f32 v21, -v5, v20, v19
	v_fmac_f32_e32 v20, v21, v18
	v_fma_f32 v5, -v5, v20, v19
	v_div_fmas_f32 v5, v5, v18, v20
	v_div_fixup_f32 v6, v5, v6, v4
	v_mul_f32_e32 v4, 0xbfb8aa3b, v0
	v_mul_f32_e32 v5, 0xbfb8aa3b, v1
	v_exp_f32_e32 v4, v4
	v_exp_f32_e32 v5, v5
	s_nop 0
	v_pk_add_f32 v[4:5], v[4:5], 1.0 op_sel_hi:[1,0]
	s_nop 0
	v_div_scale_f32 v8, s[0:1], v5, v5, v1
	v_rcp_f32_e32 v9, v8
	s_nop 0
	v_fma_f32 v12, -v8, v9, 1.0
	v_fmac_f32_e32 v9, v12, v9
	v_div_scale_f32 v12, vcc, v1, v5, v1
	v_mul_f32_e32 v13, v12, v9
	v_fma_f32 v18, -v8, v13, v12
	v_fmac_f32_e32 v13, v18, v9
	v_fma_f32 v8, -v8, v13, v12
	v_div_fmas_f32 v8, v8, v9, v13
	v_div_fixup_f32 v5, v8, v5, v1
	v_div_scale_f32 v1, s[0:1], v4, v4, v0
	v_rcp_f32_e32 v8, v1
	s_nop 0
	v_fma_f32 v9, -v1, v8, 1.0
	v_fmac_f32_e32 v8, v9, v8
	v_div_scale_f32 v9, vcc, v0, v4, v0
	v_mul_f32_e32 v12, v9, v8
	v_fma_f32 v13, -v1, v12, v9
	v_fmac_f32_e32 v12, v13, v8
	v_fma_f32 v1, -v1, v12, v9
	v_div_fmas_f32 v1, v1, v8, v12
	v_div_fixup_f32 v4, v1, v4, v0
	v_pk_add_f32 v[0:1], v[2:3], v[50:51] op_sel:[0,1] neg_lo:[0,1] neg_hi:[0,1]
	s_nop 0
	v_pk_mul_f32 v[0:1], v[0:1], v[52:53] op_sel_hi:[1,0]
	s_nop 0
	v_pk_fma_f32 v[0:1], v[0:1], v[170:171], v[178:179]
	s_nop 0
	v_mul_f32_e32 v2, 0xbfb8aa3b, v0
	v_mul_f32_e32 v3, 0xbfb8aa3b, v1
	v_exp_f32_e32 v2, v2
	v_exp_f32_e32 v3, v3
	s_nop 0
	v_pk_add_f32 v[2:3], v[2:3], 1.0 op_sel_hi:[1,0]
	s_nop 0
	v_div_scale_f32 v8, s[0:1], v3, v3, v1
	v_rcp_f32_e32 v9, v8
	s_nop 0
	v_fma_f32 v10, -v8, v9, 1.0
	v_fmac_f32_e32 v9, v10, v9
	v_div_scale_f32 v10, vcc, v1, v3, v1
	v_mul_f32_e32 v11, v10, v9
	v_fma_f32 v12, -v8, v11, v10
	v_fmac_f32_e32 v11, v12, v9
	v_fma_f32 v8, -v8, v11, v10
	v_div_fmas_f32 v8, v8, v9, v11
	v_div_fixup_f32 v3, v8, v3, v1
	v_div_scale_f32 v1, s[0:1], v2, v2, v0
	v_rcp_f32_e32 v8, v1
	s_nop 0
	v_fma_f32 v9, -v1, v8, 1.0
	v_fmac_f32_e32 v8, v9, v8
	v_div_scale_f32 v9, vcc, v0, v2, v0
	v_mul_f32_e32 v10, v9, v8
	v_fma_f32 v11, -v1, v10, v9
	v_fmac_f32_e32 v10, v11, v8
	v_fma_f32 v1, -v1, v10, v9
	v_div_fmas_f32 v1, v1, v8, v10
	v_div_fixup_f32 v8, v1, v2, v0
	v_cvt_pk_bf16_f32 v0, v16, v17
	v_cvt_pk_bf16_f32 v1, v6, v7
	v_cvt_pk_bf16_f32 v2, v4, v5
	v_cvt_pk_bf16_f32 v3, v8, v3
	global_store_dwordx4 v[48:49], v[0:3], off offset:48 sc1
	s_barrier
	s_cbranch_scc0 .LBB0_858

.LBB0_842:
	global_store_dwordx4 v[206:207], v[130:133], off offset:528 sc1
	s_cbranch_execnz .LBB0_631

.LBB0_844:
	global_store_dwordx4 v[198:199], v[114:117], off offset:528 sc1
	s_cbranch_execnz .LBB0_647

.LBB0_846:
	global_store_dwordx4 v[182:183], v[86:89], off offset:528 sc1
	s_cbranch_execnz .LBB0_663

.LBB0_848:
	global_store_dwordx4 v[166:167], v[66:69], off offset:528 sc1
	s_cbranch_execnz .LBB0_679

.LBB0_850:
	global_store_dwordx4 v[166:167], v[48:51], off offset:528 sc1
	s_cbranch_execnz .LBB0_695

.LBB0_852:
	global_store_dwordx4 v[166:167], v[32:35], off offset:528 sc1
	s_cbranch_execnz .LBB0_711

.LBB0_854:
	global_store_dwordx4 v[158:159], v[16:19], off offset:528 sc1
	s_cbranch_execnz .LBB0_727

.LBB0_856:
	global_store_dwordx4 v[102:103], v[0:3], off offset:528 sc1
	s_cbranch_execnz .LBB0_743

.LBB0_865:
	s_or_b64 exec, exec, s[0:1]
	s_waitcnt lgkmcnt(0)
	s_barrier
	s_and_saveexec_b64 s[0:1], s[8:9]
	s_cbranch_execz .LBB0_862
	ds_read2_b32 v[0:1], v18 offset1:2
	ds_read2_b32 v[2:3], v18 offset0:4 offset1:6
	ds_read2_b32 v[4:5], v18 offset0:8 offset1:10
	ds_read2_b32 v[6:7], v18 offset0:12 offset1:14
	v_readlane_b32 s4, v251, 29
	s_waitcnt lgkmcnt(3)
	v_max_f32_e32 v1, v1, v1
	v_max_f32_e32 v0, v0, v0
	v_max_f32_e32 v0, v0, v1
	s_waitcnt lgkmcnt(2)
	v_max3_f32 v0, v0, v2, v3
	s_waitcnt lgkmcnt(1)
	v_max3_f32 v0, v0, v4, v5
	v_ashrrev_i32_e32 v17, 31, v16
	v_readlane_b32 s5, v251, 30
	s_waitcnt lgkmcnt(0)
	v_max3_f32 v2, v0, v6, v7
	v_lshl_add_u64 v[0:1], v[16:17], 2, s[4:5]
	global_store_dword v[0:1], v2, off sc1
	s_branch .LBB0_862

.LBB0_873:
	s_add_i32 s2, s46, s85
	s_cmpk_lt_i32 s2, 0x4000
	s_cselect_b64 s[44:45], -1, 0
	s_and_b64 s[4:5], s[44:45], exec
	s_cselect_b32 s4, s2, 0
	s_ashr_i32 s5, s4, 31
	v_readlane_b32 s3, v249, 9
	s_lshl_b64 s[4:5], s[4:5], 12
	s_add_i32 s28, s3, s46
	s_cmpk_lt_i32 s28, 0x4000
	s_cselect_b64 s[42:43], -1, 0
	s_and_b64 s[6:7], s[42:43], exec
	s_cselect_b32 s6, s28, 0
	v_readlane_b32 s3, v249, 2
	s_ashr_i32 s7, s6, 31
	s_mul_i32 s3, s3, 24
	s_lshl_b64 s[6:7], s[6:7], 12
	s_add_i32 s22, s3, s46
	s_cmpk_lt_i32 s22, 0x4000
	s_cselect_b64 s[36:37], -1, 0
	s_and_b64 s[8:9], s[36:37], exec
	s_cselect_b32 s8, s22, 0
	s_ashr_i32 s47, s46, 31
	s_lshl_b64 s[10:11], s[46:47], 12
	s_waitcnt vmcnt(6)
	v_lshl_add_u64 v[0:1], v[48:49], 0, s[10:11]
	global_load_dwordx4 v[24:27], v[0:1], off
	global_load_dwordx4 v[32:35], v[0:1], off offset:1024
	global_load_dwordx4 v[56:59], v[0:1], off offset:2048
	global_load_dwordx4 v[60:63], v[0:1], off offset:3072
	v_lshl_add_u64 v[0:1], v[48:49], 0, s[4:5]
	global_load_dwordx4 v[44:47], v[0:1], off
	global_load_dwordx4 v[40:43], v[0:1], off offset:1024
	global_load_dwordx4 v[36:39], v[0:1], off offset:2048
	global_load_dwordx4 v[28:31], v[0:1], off offset:3072
	v_lshl_add_u64 v[0:1], v[48:49], 0, s[6:7]
	s_ashr_i32 s9, s8, 31
	global_load_dwordx4 v[20:23], v[0:1], off
	global_load_dwordx4 v[16:19], v[0:1], off offset:1024
	global_load_dwordx4 v[12:15], v[0:1], off offset:2048
	global_load_dwordx4 v[8:11], v[0:1], off offset:3072
	s_lshl_b64 s[4:5], s[8:9], 12
	v_lshl_add_u64 v[66:67], v[48:49], 0, s[4:5]
	global_load_dwordx4 v[4:7], v[66:67], off
	global_load_dwordx4 v[0:3], v[66:67], off offset:1024
	s_lshl_b64 s[4:5], s[46:47], 11
	s_waitcnt vmcnt(13)
	v_cvt_pk_bf16_f32 v52, v24, v25
	v_cvt_pk_bf16_f32 v53, v26, v27
	s_waitcnt vmcnt(12)
	v_cvt_pk_bf16_f32 v54, v32, v33
	v_cvt_pk_bf16_f32 v55, v34, v35
	s_waitcnt vmcnt(11)
	v_cvt_pk_bf16_f32 v56, v56, v57
	v_cvt_pk_bf16_f32 v57, v58, v59
	s_waitcnt vmcnt(10)
	v_cvt_pk_bf16_f32 v59, v62, v63
	v_and_b32_e32 v25, 0xffff0000, v52
	v_lshlrev_b32_e32 v24, 16, v52
	v_and_b32_e32 v27, 0xffff0000, v53
	v_and_b32_e32 v33, 0xffff0000, v54
	v_and_b32_e32 v35, 0xffff0000, v55
	v_mul_f32_e32 v69, v25, v25
	v_and_b32_e32 v25, 0xffff0000, v59
	v_lshlrev_b32_e32 v26, 16, v53
	v_lshlrev_b32_e32 v32, 16, v54
	v_lshlrev_b32_e32 v34, 16, v55
	v_fmac_f32_e32 v69, v24, v24
	v_lshlrev_b32_e32 v24, 16, v59
	v_mul_f32_e32 v70, v27, v27
	v_mul_f32_e32 v71, v33, v33
	v_mul_f32_e32 v72, v35, v35
	v_mul_f32_e32 v73, v25, v25
	v_fmac_f32_e32 v70, v26, v26
	v_fmac_f32_e32 v71, v32, v32
	v_fmac_f32_e32 v72, v34, v34
	v_fmac_f32_e32 v73, v24, v24
	global_load_dwordx4 v[32:35], v[66:67], off offset:2048
	global_load_dwordx4 v[24:27], v[66:67], off offset:3072
	v_cvt_pk_bf16_f32 v58, v60, v61
	v_and_b32_e32 v61, 0xffff0000, v56
	v_and_b32_e32 v63, 0xffff0000, v57
	v_lshlrev_b32_e32 v60, 16, v56
	v_lshlrev_b32_e32 v62, 16, v57
	v_and_b32_e32 v68, 0xffff0000, v58
	v_mul_f32_e32 v61, v61, v61
	v_mul_f32_e32 v63, v63, v63
	v_lshlrev_b32_e32 v64, 16, v58
	v_mul_f32_e32 v68, v68, v68
	v_fmac_f32_e32 v61, v60, v60
	v_fmac_f32_e32 v63, v62, v62
	v_add_f32_e32 v60, v69, v70
	v_add_f32_e32 v62, v71, v72
	v_fmac_f32_e32 v68, v64, v64
	v_add_f32_e32 v61, v61, v63
	v_add_f32_e32 v60, v62, v60
	v_add_f32_e32 v63, v68, v73
	v_add_f32_e32 v60, v61, v60
	v_add_f32_e32 v60, v63, v60
	ds_swizzle_b32 v61, v60 offset:swizzle(SWAP,1)
	s_waitcnt lgkmcnt(0)
	v_add_f32_e32 v60, v60, v61
	ds_swizzle_b32 v61, v60 offset:swizzle(SWAP,2)
	s_waitcnt lgkmcnt(0)
	v_add_f32_e32 v60, v60, v61
	ds_swizzle_b32 v61, v60 offset:swizzle(SWAP,4)
	s_waitcnt lgkmcnt(0)
	v_add_f32_e32 v62, v60, v61
	ds_swizzle_b32 v63, v62 offset:swizzle(SWAP,8)
	v_lshl_add_u64 v[60:61], v[50:51], 0, s[4:5]
	global_store_dwordx2 v[60:61], v[52:53], off sc1
	global_store_dwordx2 v[60:61], v[54:55], off offset:512 sc1
	global_store_dwordx2 v[60:61], v[56:57], off offset:1024 sc1
	global_store_dwordx2 v[60:61], v[58:59], off offset:1536 sc1
	s_waitcnt lgkmcnt(0)
	v_add_f32_e32 v62, v62, v63
	ds_swizzle_b32 v63, v62 offset:swizzle(SWAP,16)
	s_waitcnt lgkmcnt(0)
	v_add_f32_e32 v52, v62, v63
	v_mov_b32_e32 v53, v52
	s_nop 1
	v_permlane32_swap_b32_e32 v52, v53
	s_and_saveexec_b64 s[48:49], s[0:1]
	s_cbranch_execz .LBB0_875
	s_lshl_b64 s[4:5], s[46:47], 4
	s_add_u32 s4, s76, s4
	s_addc_u32 s5, s77, s5
	v_add_f32_e32 v64, v52, v53
	v_mov_b32_e32 v66, v65
	v_mov_b32_e32 v67, v65
	global_store_dwordx4 v65, v[64:67], s[4:5] sc1
.LBB0_875:
	s_or_b64 exec, exec, s[48:49]
	s_andn2_b64 vcc, exec, s[44:45]
	s_cbranch_vccnz .LBB0_872
	s_waitcnt vmcnt(15)
	v_cvt_pk_bf16_f32 v44, v44, v45
	v_cvt_pk_bf16_f32 v45, v46, v47
	v_and_b32_e32 v47, 0xffff0000, v44
	v_lshlrev_b32_e32 v46, 16, v44
	v_and_b32_e32 v53, 0xffff0000, v45
	v_mul_f32_e32 v47, v47, v47
	s_waitcnt vmcnt(14)
	v_cvt_pk_bf16_f32 v40, v40, v41
	v_lshlrev_b32_e32 v52, 16, v45
	v_fmac_f32_e32 v47, v46, v46
	v_mul_f32_e32 v46, v53, v53
	v_cvt_pk_bf16_f32 v41, v42, v43
	v_and_b32_e32 v43, 0xffff0000, v40
	v_fmac_f32_e32 v46, v52, v52
	v_lshlrev_b32_e32 v42, 16, v40
	v_and_b32_e32 v52, 0xffff0000, v41
	v_mul_f32_e32 v43, v43, v43
	v_add_f32_e32 v46, v47, v46
	v_lshlrev_b32_e32 v47, 16, v41
	v_fmac_f32_e32 v43, v42, v42
	v_mul_f32_e32 v42, v52, v52
	v_fmac_f32_e32 v42, v47, v47
	s_waitcnt vmcnt(13)
	v_cvt_pk_bf16_f32 v36, v36, v37
	v_add_f32_e32 v42, v43, v42
	v_cvt_pk_bf16_f32 v37, v38, v39
	v_and_b32_e32 v39, 0xffff0000, v36
	v_add_f32_e32 v42, v46, v42
	v_lshlrev_b32_e32 v38, 16, v36
	v_and_b32_e32 v46, 0xffff0000, v37
	v_mul_f32_e32 v39, v39, v39
	v_lshlrev_b32_e32 v43, 16, v37
	v_fmac_f32_e32 v39, v38, v38
	v_mul_f32_e32 v38, v46, v46
	v_fmac_f32_e32 v38, v43, v43
	s_waitcnt vmcnt(12)
	v_cvt_pk_bf16_f32 v28, v28, v29
	v_add_f32_e32 v38, v39, v38
	v_cvt_pk_bf16_f32 v29, v30, v31
	v_and_b32_e32 v31, 0xffff0000, v28
	v_add_f32_e32 v38, v42, v38
	v_lshlrev_b32_e32 v30, 16, v28
	v_and_b32_e32 v42, 0xffff0000, v29
	v_mul_f32_e32 v31, v31, v31
	v_lshlrev_b32_e32 v39, 16, v29
	v_fmac_f32_e32 v31, v30, v30
	v_mul_f32_e32 v30, v42, v42
	v_fmac_f32_e32 v30, v39, v39
	v_add_f32_e32 v30, v31, v30
	v_add_f32_e32 v30, v38, v30
	ds_swizzle_b32 v31, v30 offset:swizzle(SWAP,1)
	s_ashr_i32 s3, s2, 31
	s_lshl_b64 s[4:5], s[2:3], 11
	s_waitcnt lgkmcnt(0)
	v_add_f32_e32 v30, v30, v31
	ds_swizzle_b32 v31, v30 offset:swizzle(SWAP,2)
	s_waitcnt lgkmcnt(0)
	v_add_f32_e32 v30, v30, v31
	ds_swizzle_b32 v31, v30 offset:swizzle(SWAP,4)
	s_waitcnt lgkmcnt(0)
	v_add_f32_e32 v38, v30, v31
	ds_swizzle_b32 v39, v38 offset:swizzle(SWAP,8)
	v_lshl_add_u64 v[30:31], v[50:51], 0, s[4:5]
	global_store_dwordx2 v[30:31], v[44:45], off sc1
	global_store_dwordx2 v[30:31], v[40:41], off offset:512 sc1
	global_store_dwordx2 v[30:31], v[36:37], off offset:1024 sc1
	global_store_dwordx2 v[30:31], v[28:29], off offset:1536 sc1
	s_waitcnt lgkmcnt(0)
	v_add_f32_e32 v38, v38, v39
	ds_swizzle_b32 v39, v38 offset:swizzle(SWAP,16)
	s_waitcnt lgkmcnt(0)
	v_add_f32_e32 v28, v38, v39
	v_mov_b32_e32 v29, v28
	s_nop 1
	v_permlane32_swap_b32_e32 v28, v29
	s_and_saveexec_b64 s[44:45], s[0:1]
	s_cbranch_execz .LBB0_878
	s_lshl_b64 s[4:5], s[2:3], 4
	s_add_u32 s4, s76, s4
	s_addc_u32 s5, s77, s5
	v_add_f32_e32 v64, v28, v29
	v_mov_b32_e32 v66, v65
	v_mov_b32_e32 v67, v65
	global_store_dwordx4 v65, v[64:67], s[4:5] sc1
.LBB0_878:
	s_or_b64 exec, exec, s[44:45]
	s_andn2_b64 vcc, exec, s[42:43]
	s_cbranch_vccnz .LBB0_872
	s_waitcnt vmcnt(15)
	v_cvt_pk_bf16_f32 v20, v20, v21
	v_cvt_pk_bf16_f32 v21, v22, v23
	v_and_b32_e32 v23, 0xffff0000, v20
	v_lshlrev_b32_e32 v22, 16, v20
	v_and_b32_e32 v29, 0xffff0000, v21
	v_mul_f32_e32 v23, v23, v23
	s_waitcnt vmcnt(14)
	v_cvt_pk_bf16_f32 v16, v16, v17
	v_lshlrev_b32_e32 v28, 16, v21
	v_fmac_f32_e32 v23, v22, v22
	v_mul_f32_e32 v22, v29, v29
	v_cvt_pk_bf16_f32 v17, v18, v19
	v_and_b32_e32 v19, 0xffff0000, v16
	v_fmac_f32_e32 v22, v28, v28
	v_lshlrev_b32_e32 v18, 16, v16
	v_and_b32_e32 v28, 0xffff0000, v17
	v_mul_f32_e32 v19, v19, v19
	v_add_f32_e32 v22, v23, v22
	v_lshlrev_b32_e32 v23, 16, v17
	v_fmac_f32_e32 v19, v18, v18
	v_mul_f32_e32 v18, v28, v28
	v_fmac_f32_e32 v18, v23, v23
	s_waitcnt vmcnt(13)
	v_cvt_pk_bf16_f32 v12, v12, v13
	v_add_f32_e32 v18, v19, v18
	v_cvt_pk_bf16_f32 v13, v14, v15
	v_and_b32_e32 v15, 0xffff0000, v12
	v_add_f32_e32 v18, v22, v18
	v_lshlrev_b32_e32 v14, 16, v12
	v_and_b32_e32 v22, 0xffff0000, v13
	v_mul_f32_e32 v15, v15, v15
	v_lshlrev_b32_e32 v19, 16, v13
	v_fmac_f32_e32 v15, v14, v14
	v_mul_f32_e32 v14, v22, v22
	v_fmac_f32_e32 v14, v19, v19
	s_waitcnt vmcnt(12)
	v_cvt_pk_bf16_f32 v8, v8, v9
	v_add_f32_e32 v14, v15, v14
	v_cvt_pk_bf16_f32 v9, v10, v11
	v_and_b32_e32 v11, 0xffff0000, v8
	v_add_f32_e32 v14, v18, v14
	v_lshlrev_b32_e32 v10, 16, v8
	v_and_b32_e32 v18, 0xffff0000, v9
	v_mul_f32_e32 v11, v11, v11
	v_lshlrev_b32_e32 v15, 16, v9
	v_fmac_f32_e32 v11, v10, v10
	v_mul_f32_e32 v10, v18, v18
	v_fmac_f32_e32 v10, v15, v15
	v_add_f32_e32 v10, v11, v10
	v_add_f32_e32 v10, v14, v10
	ds_swizzle_b32 v11, v10 offset:swizzle(SWAP,1)
	s_ashr_i32 s29, s28, 31
	s_lshl_b64 s[4:5], s[28:29], 11
	s_waitcnt lgkmcnt(0)
	v_add_f32_e32 v10, v10, v11
	ds_swizzle_b32 v11, v10 offset:swizzle(SWAP,2)
	s_waitcnt lgkmcnt(0)
	v_add_f32_e32 v10, v10, v11
	ds_swizzle_b32 v11, v10 offset:swizzle(SWAP,4)
	s_waitcnt lgkmcnt(0)
	v_add_f32_e32 v14, v10, v11
	ds_swizzle_b32 v15, v14 offset:swizzle(SWAP,8)
	v_lshl_add_u64 v[10:11], v[50:51], 0, s[4:5]
	global_store_dwordx2 v[10:11], v[20:21], off sc1
	global_store_dwordx2 v[10:11], v[16:17], off offset:512 sc1
	global_store_dwordx2 v[10:11], v[12:13], off offset:1024 sc1
	global_store_dwordx2 v[10:11], v[8:9], off offset:1536 sc1
	s_waitcnt lgkmcnt(0)
	v_add_f32_e32 v14, v14, v15
	ds_swizzle_b32 v15, v14 offset:swizzle(SWAP,16)
	s_waitcnt lgkmcnt(0)
	v_add_f32_e32 v8, v14, v15
	v_mov_b32_e32 v9, v8
	s_nop 1
	v_permlane32_swap_b32_e32 v8, v9
	s_and_saveexec_b64 s[42:43], s[0:1]
	s_cbranch_execz .LBB0_881
	s_lshl_b64 s[4:5], s[28:29], 4
	s_add_u32 s4, s76, s4
	s_addc_u32 s5, s77, s5
	v_add_f32_e32 v64, v8, v9
	v_mov_b32_e32 v66, v65
	v_mov_b32_e32 v67, v65
	global_store_dwordx4 v65, v[64:67], s[4:5] sc1
.LBB0_881:
	s_or_b64 exec, exec, s[42:43]
	s_andn2_b64 vcc, exec, s[36:37]
	s_cbranch_vccnz .LBB0_872
	s_waitcnt vmcnt(15)
	v_cvt_pk_bf16_f32 v4, v4, v5
	v_cvt_pk_bf16_f32 v5, v6, v7
	v_and_b32_e32 v7, 0xffff0000, v4
	v_lshlrev_b32_e32 v6, 16, v4
	v_and_b32_e32 v9, 0xffff0000, v5
	v_mul_f32_e32 v7, v7, v7
	s_waitcnt vmcnt(14)
	v_cvt_pk_bf16_f32 v0, v0, v1
	v_lshlrev_b32_e32 v8, 16, v5
	v_fmac_f32_e32 v7, v6, v6
	v_mul_f32_e32 v6, v9, v9
	v_cvt_pk_bf16_f32 v1, v2, v3
	v_and_b32_e32 v3, 0xffff0000, v0
	v_fmac_f32_e32 v6, v8, v8
	v_lshlrev_b32_e32 v2, 16, v0
	v_and_b32_e32 v8, 0xffff0000, v1
	v_mul_f32_e32 v3, v3, v3
	v_add_f32_e32 v6, v7, v6
	v_lshlrev_b32_e32 v7, 16, v1
	v_fmac_f32_e32 v3, v2, v2
	v_mul_f32_e32 v2, v8, v8
	v_fmac_f32_e32 v2, v7, v7
	v_add_f32_e32 v2, v3, v2
	v_add_f32_e32 v6, v6, v2
	s_waitcnt vmcnt(13)
	v_cvt_pk_bf16_f32 v2, v32, v33
	v_cvt_pk_bf16_f32 v3, v34, v35
	v_and_b32_e32 v8, 0xffff0000, v2
	v_lshlrev_b32_e32 v7, 16, v2
	v_and_b32_e32 v10, 0xffff0000, v3
	v_mul_f32_e32 v8, v8, v8
	v_lshlrev_b32_e32 v9, 16, v3
	v_fmac_f32_e32 v8, v7, v7
	v_mul_f32_e32 v7, v10, v10
	v_fmac_f32_e32 v7, v9, v9
	v_add_f32_e32 v7, v8, v7
	v_add_f32_e32 v8, v6, v7
	s_waitcnt vmcnt(12)
	v_cvt_pk_bf16_f32 v6, v24, v25
	v_cvt_pk_bf16_f32 v7, v26, v27
	v_and_b32_e32 v10, 0xffff0000, v6
	v_lshlrev_b32_e32 v9, 16, v6
	v_and_b32_e32 v12, 0xffff0000, v7
	v_mul_f32_e32 v10, v10, v10
	v_lshlrev_b32_e32 v11, 16, v7
	v_fmac_f32_e32 v10, v9, v9
	v_mul_f32_e32 v9, v12, v12
	v_fmac_f32_e32 v9, v11, v11
	v_add_f32_e32 v9, v10, v9
	v_add_f32_e32 v8, v8, v9
	ds_swizzle_b32 v9, v8 offset:swizzle(SWAP,1)
	s_ashr_i32 s23, s22, 31
	s_lshl_b64 s[4:5], s[22:23], 11
	s_waitcnt lgkmcnt(0)
	v_add_f32_e32 v8, v8, v9
	ds_swizzle_b32 v9, v8 offset:swizzle(SWAP,2)
	s_waitcnt lgkmcnt(0)
	v_add_f32_e32 v8, v8, v9
	ds_swizzle_b32 v9, v8 offset:swizzle(SWAP,4)
	s_waitcnt lgkmcnt(0)
	v_add_f32_e32 v10, v8, v9
	ds_swizzle_b32 v11, v10 offset:swizzle(SWAP,8)
	v_lshl_add_u64 v[8:9], v[50:51], 0, s[4:5]
	global_store_dwordx2 v[8:9], v[4:5], off sc1
	global_store_dwordx2 v[8:9], v[0:1], off offset:512 sc1
	global_store_dwordx2 v[8:9], v[2:3], off offset:1024 sc1
	global_store_dwordx2 v[8:9], v[6:7], off offset:1536 sc1
	s_waitcnt lgkmcnt(0)
	v_add_f32_e32 v10, v10, v11
	ds_swizzle_b32 v11, v10 offset:swizzle(SWAP,16)
	s_waitcnt lgkmcnt(0)
	v_add_f32_e32 v0, v10, v11
	v_mov_b32_e32 v1, v0
	s_nop 1
	v_permlane32_swap_b32_e32 v0, v1
	s_and_saveexec_b64 s[28:29], s[0:1]
	s_cbranch_execz .LBB0_871
	s_lshl_b64 s[4:5], s[22:23], 4
	s_add_u32 s4, s76, s4
	s_addc_u32 s5, s77, s5
	v_add_f32_e32 v64, v0, v1
	v_mov_b32_e32 v66, v65
	v_mov_b32_e32 v67, v65
	global_store_dwordx4 v65, v[64:67], s[4:5] sc1
	s_branch .LBB0_871

.LBB0_886:
	v_add_u32_e32 v4, 0x18c0, v53
	ds_write2_b32 v4, v12, v13 offset1:1
	v_add_u32_e32 v4, 0x18c8, v53
	ds_write2_b32 v4, v10, v11 offset1:1
	s_waitcnt vmcnt(0)
	v_pk_mul_f32 v[0:1], v[0:1], v[8:9] op_sel_hi:[1,0]
	v_add_u32_e32 v4, 0x1ce0, v53
	ds_write2_b32 v4, v0, v1 offset1:1
	v_pk_mul_f32 v[0:1], v[2:3], v[8:9] op_sel_hi:[1,0]
	v_add_u32_e32 v2, 0x1ce8, v53
	ds_write2_b32 v2, v0, v1 offset1:1
	s_waitcnt lgkmcnt(0)
	ds_read2_b32 v[4:5], v59 offset0:33 offset1:41
	ds_read2_b32 v[6:7], v59 offset1:8
	ds_read2_b32 v[8:9], v59 offset0:66 offset1:74
	ds_read2_b32 v[10:11], v59 offset0:99 offset1:107
	ds_read2_b32 v[12:13], v59 offset0:132 offset1:140
	ds_read2_b32 v[14:15], v59 offset0:165 offset1:173
	ds_read2_b32 v[16:17], v59 offset0:198 offset1:206
	ds_read2_b32 v[18:19], v59 offset0:231 offset1:239
	v_add_u32_e32 v22, s7, v32
	v_ashrrev_i32_e32 v23, 31, v22
	v_lshl_add_u64 v[20:21], s[2:3], 1, v[50:51]
	v_lshlrev_b64 v[24:25], 11, v[22:23]
	s_waitcnt lgkmcnt(6)
	v_cvt_pk_bf16_f32 v0, v6, v4
	s_waitcnt lgkmcnt(4)
	v_cvt_pk_bf16_f32 v1, v8, v10
	s_waitcnt lgkmcnt(2)
	v_cvt_pk_bf16_f32 v2, v12, v14
	s_waitcnt lgkmcnt(0)
	v_cvt_pk_bf16_f32 v3, v16, v18
	v_lshl_add_u64 v[24:25], v[20:21], 0, v[24:25]
	v_add_u32_e32 v4, 8, v22
	global_store_dwordx4 v[24:25], v[0:3], off sc1
	s_nop 1
	v_cvt_pk_bf16_f32 v0, v7, v5
	v_ashrrev_i32_e32 v5, 31, v4
	v_cvt_pk_bf16_f32 v1, v9, v11
	v_cvt_pk_bf16_f32 v2, v13, v15
	v_cvt_pk_bf16_f32 v3, v17, v19
	v_lshlrev_b64 v[4:5], 11, v[4:5]
	ds_read2_b32 v[6:7], v59 offset0:49 offset1:57
	ds_read2_b32 v[8:9], v59 offset0:16 offset1:24
	ds_read2_b32 v[10:11], v59 offset0:82 offset1:90
	ds_read2_b32 v[12:13], v59 offset0:115 offset1:123
	ds_read2_b32 v[14:15], v59 offset0:148 offset1:156
	ds_read2_b32 v[16:17], v59 offset0:181 offset1:189
	ds_read2_b32 v[18:19], v59 offset0:214 offset1:222
	ds_read2_b32 v[24:25], v59 offset0:247 offset1:255
	v_lshl_add_u64 v[4:5], v[20:21], 0, v[4:5]
	global_store_dwordx4 v[4:5], v[0:3], off sc1
	v_add_u32_e32 v4, 16, v22
	v_ashrrev_i32_e32 v5, 31, v4
	v_lshlrev_b64 v[4:5], 11, v[4:5]
	s_waitcnt lgkmcnt(6)
	v_cvt_pk_bf16_f32 v0, v8, v6
	s_waitcnt lgkmcnt(4)
	v_cvt_pk_bf16_f32 v1, v10, v12
	s_waitcnt lgkmcnt(2)
	v_cvt_pk_bf16_f32 v2, v14, v16
	s_waitcnt lgkmcnt(0)
	v_cvt_pk_bf16_f32 v3, v18, v24
	v_lshl_add_u64 v[4:5], v[20:21], 0, v[4:5]
	global_store_dwordx4 v[4:5], v[0:3], off sc1
	v_add_u32_e32 v4, 24, v22
	v_ashrrev_i32_e32 v5, 31, v4
	v_lshlrev_b64 v[4:5], 11, v[4:5]
	v_cvt_pk_bf16_f32 v0, v9, v7
	v_cvt_pk_bf16_f32 v1, v11, v13
	v_cvt_pk_bf16_f32 v2, v15, v17
	v_cvt_pk_bf16_f32 v3, v19, v25
	v_lshl_add_u64 v[4:5], v[20:21], 0, v[4:5]
	global_store_dwordx4 v[4:5], v[0:3], off sc1
	s_waitcnt lgkmcnt(0)

.LBB0_914:
	v_mov_b32_e32 v53, v4
	v_pk_mul_f32 v[6:7], v[8:9], v[52:53] op_sel_hi:[1,0]
	v_add_u32_e32 v8, 0x18c0, v28
	v_pk_mul_f32 v[4:5], v[10:11], v[52:53] op_sel_hi:[1,0]
	ds_write2_b32 v8, v6, v7 offset1:1
	v_add_u32_e32 v6, 0x18c8, v28
	ds_write2_b32 v6, v4, v5 offset1:1
	v_pk_mul_f32 v[0:1], v[0:1], v[52:53] op_sel:[0,1]
	v_add_u32_e32 v4, 0x1ce0, v28
	ds_write2_b32 v4, v0, v1 offset1:1
	v_pk_mul_f32 v[0:1], v[2:3], v[52:53] op_sel:[0,1]
	v_add_u32_e32 v2, 0x1ce8, v28
	ds_write2_b32 v2, v0, v1 offset1:1
	s_waitcnt lgkmcnt(0)
	ds_read2_b32 v[4:5], v59 offset0:33 offset1:41
	ds_read2_b32 v[6:7], v59 offset1:8
	ds_read2_b32 v[8:9], v59 offset0:66 offset1:74
	ds_read2_b32 v[10:11], v59 offset0:99 offset1:107
	ds_read2_b32 v[12:13], v59 offset0:132 offset1:140
	ds_read2_b32 v[14:15], v59 offset0:165 offset1:173
	ds_read2_b32 v[16:17], v59 offset0:198 offset1:206
	ds_read2_b32 v[18:19], v59 offset0:231 offset1:239
	v_add_u32_e32 v22, s7, v32
	v_ashrrev_i32_e32 v23, 31, v22
	v_lshl_add_u64 v[20:21], s[34:35], 1, v[48:49]
	v_lshlrev_b64 v[22:23], 11, v[22:23]
	s_waitcnt lgkmcnt(6)
	v_cvt_pk_bf16_f32 v0, v6, v4
	s_waitcnt lgkmcnt(4)
	v_cvt_pk_bf16_f32 v1, v8, v10
	s_waitcnt lgkmcnt(2)
	v_cvt_pk_bf16_f32 v2, v12, v14
	s_waitcnt lgkmcnt(0)
	v_cvt_pk_bf16_f32 v3, v16, v18
	v_lshl_add_u64 v[22:23], v[20:21], 0, v[22:23]
	v_add_u32_e32 v4, s7, v34
	global_store_dwordx4 v[22:23], v[0:3], off sc1
	s_nop 1
	v_cvt_pk_bf16_f32 v0, v7, v5
	v_ashrrev_i32_e32 v5, 31, v4
	v_cvt_pk_bf16_f32 v1, v9, v11
	v_cvt_pk_bf16_f32 v2, v13, v15
	v_cvt_pk_bf16_f32 v3, v17, v19
	v_lshlrev_b64 v[4:5], 11, v[4:5]
	ds_read2_b32 v[6:7], v59 offset0:16 offset1:24
	ds_read2_b32 v[8:9], v59 offset0:49 offset1:57
	ds_read2_b32 v[10:11], v59 offset0:82 offset1:90
	ds_read2_b32 v[12:13], v59 offset0:115 offset1:123
	ds_read2_b32 v[14:15], v59 offset0:148 offset1:156
	ds_read2_b32 v[16:17], v59 offset0:181 offset1:189
	ds_read2_b32 v[18:19], v59 offset0:214 offset1:222
	ds_read2_b32 v[22:23], v59 offset0:247 offset1:255
	v_lshl_add_u64 v[4:5], v[20:21], 0, v[4:5]
	global_store_dwordx4 v[4:5], v[0:3], off sc1
	v_add_u32_e32 v4, s7, v36
	v_ashrrev_i32_e32 v5, 31, v4
	v_lshlrev_b64 v[4:5], 11, v[4:5]
	s_waitcnt lgkmcnt(6)
	v_cvt_pk_bf16_f32 v0, v6, v8
	s_waitcnt lgkmcnt(4)
	v_cvt_pk_bf16_f32 v1, v10, v12
	s_waitcnt lgkmcnt(2)
	v_cvt_pk_bf16_f32 v2, v14, v16
	s_waitcnt lgkmcnt(0)
	v_cvt_pk_bf16_f32 v3, v18, v22
	v_lshl_add_u64 v[4:5], v[20:21], 0, v[4:5]
	global_store_dwordx4 v[4:5], v[0:3], off sc1
	v_add_u32_e32 v4, s7, v38
	v_ashrrev_i32_e32 v5, 31, v4
	v_lshlrev_b64 v[4:5], 11, v[4:5]
	v_cvt_pk_bf16_f32 v0, v7, v9
	v_cvt_pk_bf16_f32 v1, v11, v13
	v_cvt_pk_bf16_f32 v2, v15, v17
	v_cvt_pk_bf16_f32 v3, v19, v23
	v_lshl_add_u64 v[4:5], v[20:21], 0, v[4:5]
	global_store_dwordx4 v[4:5], v[0:3], off sc1
	s_waitcnt lgkmcnt(0)
	s_branch .LBB0_887
